# v71 with the two pre-barrier waits of each load segment merged into one s_waitcnt vmcnt(8) lgkmcnt(0)
# speedup vs baseline: 1.0022x; 1.0022x over previous
; #define PG8_STAGE(bufoff, gbase, voff) do { _Pragma("unroll") for (int _i = 0; _i < 2; ++_i) \
;         __builtin_amdgcn_global_load_lds((const unsigned*)((const char*)(gbase) + (voff)[_i]), (PG8_LAS unsigned*)(lds + (bufoff) + ldsw + _i * 8192), 16, 0, 0); } while (0)
; #define PG8_LDA(dst, b, h) do { _Pragma("unroll") for (int m = 0; m < 4; ++m) _Pragma("unroll") for (int k = 0; k < 2; ++k) dst[m][k] = *(const PG8_LAS bf16x8*)(lds + PG8_SA(b, h) + aoff + m * 2048 + k * 1024); } while (0)
; #define PG8_LDB(dst, b, h) do { _Pragma("unroll") for (int n = 0; n < 2; ++n) _Pragma("unroll") for (int k = 0; k < 2; ++k) dst[n][k] = *(const PG8_LAS bf16x8*)(lds + PG8_SB(b, h) + boff + n * 2048 + k * 1024); } while (0)
; #define PG8_MMA(ai, bj, At, Bt) do { __builtin_amdgcn_s_setprio(1); _Pragma("unroll") for (int m = 0; m < 4; ++m) _Pragma("unroll") for (int n = 0; n < 2; ++n) _Pragma("unroll") for (int k = 0; k < 2; ++k) \
;         acc[ai][bj][m][n] = __builtin_amdgcn_mfma_f32_16x16x32_bf16(Bt[n][k], At[m][k], acc[ai][bj][m][n], 0, 0, 0); __builtin_amdgcn_s_setprio(0); } while (0)
; #define PG8_WAIT_V(n) asm volatile("s_waitcnt vmcnt(" #n ")" ::: "memory")
; #define PG8_WAIT_L(n) asm volatile("s_waitcnt lgkmcnt(" #n ")" ::: "memory")
; template <class Epi, class Sched, bool ALIGN_EPI = false, bool SP2 = false>
; __device__ __forceinline__ void gemm_phase(PG8_LAS unsigned char* lds, const Gemm g, const Sched& S, const Epi& E) {
;     ...
;             const bool last = (t == nt - 2);
;             const char* a1 = cA + (size_t)(t + 1) * kstep;
;             const char* a2 = last ? nA : cA + (size_t)(t + 2) * kstep; const char* b2 = last ? nB : cB + (size_t)(t + 2) * kstep;
;             const char* a3 = a2 + kstep; const char* b3 = b2 + kstep;
;             if (last && has_next) S.a_ready(nxt);
;             if constexpr (SP2) {
;             PG8_LDB(B0, 0, 0); PG8_LDB(B1, 0, 1); PG8_SCHED; PG8_LDA(At, 0, 0); PG8_STAGE(PG8_SA(1, 1), a1 + hstep, voffA);
;             PG8_WAIT_V(8); PG8_WAIT_L(0); PG8_BAR; PG8_MMA(0, 0, At, B0); PG8_MMA(0, 1, At, B1); PG8_BAR; PG8_SCHED;
;             PG8_LDA(At, 0, 1); PG8_STAGE(PG8_SB(0, 0), b2, voffB); PG8_STAGE(PG8_SB(0, 1), b2 + hstep, voffB); PG8_STAGE(PG8_SA(0, 0), a2, voffA);
;             PG8_WAIT_V(8); PG8_WAIT_L(0); PG8_BAR; PG8_MMA(1, 0, At, B0); PG8_MMA(1, 1, At, B1); PG8_BAR; PG8_SCHED;
.LBB0_139:
	ds_read_b128 v[2:5], v187
	ds_read_b128 v[6:9], v187 offset:1024
	ds_read_b128 v[138:141], v187 offset:2048
	ds_read_b128 v[142:145], v187 offset:3072
	ds_read_b128 v[146:149], v197
	ds_read_b128 v[150:153], v197 offset:1024
	ds_read_b128 v[154:157], v197 offset:2048
	ds_read_b128 v[158:161], v197 offset:3072
	s_add_u32 s14, s12, 0xfff00080
	s_addc_u32 s15, s13, -1
	s_cmp_eq_u32 s33, 60
	s_cselect_b32 s17, s2, s15
	s_cselect_b32 s16, s11, s14
	s_cselect_b32 s15, s26, s30
	s_cselect_b32 s14, s28, s29
	s_add_i32 m0, s27, 0xc000
	ds_read_b128 v[202:205], v199
	ds_read_b128 v[206:209], v199 offset:1024
	ds_read_b128 v[214:217], v199 offset:2048
	ds_read_b128 v[218:221], v199 offset:3072
	ds_read_b128 v[222:225], v199 offset:4096
	ds_read_b128 v[226:229], v199 offset:5120
	ds_read_b128 v[230:233], v199 offset:6144
	ds_read_b128 v[234:237], v199 offset:7168
	global_load_lds_dwordx4 v188, s[12:13]
	s_add_i32 m0, s27, 0xe000
	s_nop 0
	global_load_lds_dwordx4 v190, s[12:13]
	s_waitcnt vmcnt(8) lgkmcnt(0)
	s_setprio 1
	s_barrier
	v_mfma_f32_16x16x32_bf16 v[134:137], v[2:5], v[202:205], v[134:137]
	v_mfma_f32_16x16x32_bf16 v[134:137], v[6:9], v[206:209], v[134:137]
	v_mfma_f32_16x16x32_bf16 v[118:121], v[6:9], v[218:221], v[118:121]
	v_mfma_f32_16x16x32_bf16 v[118:121], v[2:5], v[214:217], v[118:121]
	v_mfma_f32_16x16x32_bf16 v[102:105], v[2:5], v[222:225], v[102:105]
	v_mfma_f32_16x16x32_bf16 v[102:105], v[6:9], v[226:229], v[102:105]
	v_mfma_f32_16x16x32_bf16 v[86:89], v[6:9], v[234:237], v[86:89]
	v_mfma_f32_16x16x32_bf16 v[86:89], v[2:5], v[230:233], v[86:89]
	v_mfma_f32_16x16x32_bf16 v[82:85], v[138:141], v[230:233], v[82:85]
	v_mfma_f32_16x16x32_bf16 v[82:85], v[142:145], v[234:237], v[82:85]
	v_mfma_f32_16x16x32_bf16 v[130:133], v[142:145], v[206:209], v[130:133]
	v_mfma_f32_16x16x32_bf16 v[130:133], v[138:141], v[202:205], v[130:133]
	v_mfma_f32_16x16x32_bf16 v[114:117], v[138:141], v[214:217], v[114:117]
	v_mfma_f32_16x16x32_bf16 v[114:117], v[142:145], v[218:221], v[114:117]
	v_mfma_f32_16x16x32_bf16 v[98:101], v[142:145], v[226:229], v[98:101]
	v_mfma_f32_16x16x32_bf16 v[98:101], v[138:141], v[222:225], v[98:101]
	s_setprio 0
	s_setprio 1
	v_mfma_f32_16x16x32_bf16 v[94:97], v[146:149], v[222:225], v[94:97]
	v_mfma_f32_16x16x32_bf16 v[94:97], v[150:153], v[226:229], v[94:97]
	v_mfma_f32_16x16x32_bf16 v[126:129], v[150:153], v[206:209], v[126:129]
	v_mfma_f32_16x16x32_bf16 v[126:129], v[146:149], v[202:205], v[126:129]
	v_mfma_f32_16x16x32_bf16 v[110:113], v[146:149], v[214:217], v[110:113]
	v_mfma_f32_16x16x32_bf16 v[110:113], v[150:153], v[218:221], v[110:113]
	v_mfma_f32_16x16x32_bf16 v[78:81], v[150:153], v[234:237], v[78:81]
	v_mfma_f32_16x16x32_bf16 v[78:81], v[146:149], v[230:233], v[78:81]
	v_mfma_f32_16x16x32_bf16 v[74:77], v[154:157], v[230:233], v[74:77]
	v_mfma_f32_16x16x32_bf16 v[74:77], v[158:161], v[234:237], v[74:77]
	v_mfma_f32_16x16x32_bf16 v[122:125], v[158:161], v[206:209], v[122:125]
	v_mfma_f32_16x16x32_bf16 v[122:125], v[154:157], v[202:205], v[122:125]
	v_mfma_f32_16x16x32_bf16 v[106:109], v[154:157], v[214:217], v[106:109]
	v_mfma_f32_16x16x32_bf16 v[106:109], v[158:161], v[218:221], v[106:109]
	v_mfma_f32_16x16x32_bf16 v[90:93], v[158:161], v[226:229], v[90:93]
	v_mfma_f32_16x16x32_bf16 v[90:93], v[154:157], v[222:225], v[90:93]
	s_barrier
	s_setprio 0
	s_add_i32 s34, s41, s25
	s_mov_b32 m0, s34
	ds_read_b128 v[202:205], v199 offset:16384
	ds_read_b128 v[206:209], v199 offset:17408
	ds_read_b128 v[214:217], v199 offset:18432
	ds_read_b128 v[218:221], v199 offset:19456
	ds_read_b128 v[222:225], v199 offset:20480
	ds_read_b128 v[226:229], v199 offset:21504
	ds_read_b128 v[230:233], v199 offset:22528
	ds_read_b128 v[234:237], v199 offset:23552
	global_load_lds_dwordx4 v168, s[14:15]
	s_add_i32 m0, s34, 0x2000
	s_add_u32 s34, s14, 0x100000
	s_addc_u32 s35, s15, 0
	s_add_i32 s79, s92, s25
	global_load_lds_dwordx4 v172, s[14:15]
	s_mov_b32 m0, s79
	v_lshl_add_u64 v[240:241], s[16:17], 0, v[170:171]
	global_load_lds_dwordx4 v168, s[34:35]
	s_add_i32 m0, s79, 0x2000
	s_nop 0
	global_load_lds_dwordx4 v172, s[34:35]
	v_lshl_add_u64 v[238:239], s[16:17], 0, v[164:165]
	s_mov_b32 m0, s27
	s_nop 0
	global_load_lds_dwordx4 v164, s[16:17]
	s_mov_b32 m0, s39
	s_nop 0
	global_load_lds_dwordx4 v170, s[16:17]
	s_waitcnt vmcnt(8) lgkmcnt(0)
	s_setprio 1
	s_barrier
	v_mfma_f32_16x16x32_bf16 v[70:73], v[6:9], v[206:209], v[70:73]
	v_mfma_f32_16x16x32_bf16 v[70:73], v[2:5], v[202:205], v[70:73]
	v_mfma_f32_16x16x32_bf16 v[54:57], v[2:5], v[214:217], v[54:57]
	v_mfma_f32_16x16x32_bf16 v[54:57], v[6:9], v[218:221], v[54:57]
	v_mfma_f32_16x16x32_bf16 v[38:41], v[6:9], v[226:229], v[38:41]
	v_mfma_f32_16x16x32_bf16 v[38:41], v[2:5], v[222:225], v[38:41]
	v_mfma_f32_16x16x32_bf16 v[2:5], v[2:5], v[230:233], v[22:25]
	v_mfma_f32_16x16x32_bf16 v[2:5], v[6:9], v[234:237], v[2:5]
	v_mfma_f32_16x16x32_bf16 v[6:9], v[142:145], v[234:237], v[18:21]
	v_mfma_f32_16x16x32_bf16 v[6:9], v[138:141], v[230:233], v[6:9]
	v_mfma_f32_16x16x32_bf16 v[66:69], v[138:141], v[202:205], v[66:69]
	v_mfma_f32_16x16x32_bf16 v[66:69], v[142:145], v[206:209], v[66:69]
	v_mfma_f32_16x16x32_bf16 v[50:53], v[142:145], v[218:221], v[50:53]
	v_mfma_f32_16x16x32_bf16 v[50:53], v[138:141], v[214:217], v[50:53]
	v_mfma_f32_16x16x32_bf16 v[34:37], v[138:141], v[222:225], v[34:37]
	v_mfma_f32_16x16x32_bf16 v[34:37], v[142:145], v[226:229], v[34:37]
	s_setprio 0
	s_setprio 1
	v_mfma_f32_16x16x32_bf16 v[18:21], v[150:153], v[226:229], v[30:33]
	v_mfma_f32_16x16x32_bf16 v[30:33], v[146:149], v[222:225], v[18:21]
	v_mfma_f32_16x16x32_bf16 v[14:17], v[146:149], v[230:233], v[14:17]
	v_mfma_f32_16x16x32_bf16 v[14:17], v[150:153], v[234:237], v[14:17]
	v_mfma_f32_16x16x32_bf16 v[18:21], v[150:153], v[206:209], v[62:65]
	v_mfma_f32_16x16x32_bf16 v[62:65], v[146:149], v[202:205], v[18:21]
	v_mfma_f32_16x16x32_bf16 v[18:21], v[146:149], v[214:217], v[46:49]
	v_mfma_f32_16x16x32_bf16 v[46:49], v[150:153], v[218:221], v[18:21]
	v_mfma_f32_16x16x32_bf16 v[18:21], v[158:161], v[218:221], v[42:45]
	v_mfma_f32_16x16x32_bf16 v[42:45], v[154:157], v[214:217], v[18:21]
	v_mfma_f32_16x16x32_bf16 v[18:21], v[154:157], v[222:225], v[26:29]
	v_mfma_f32_16x16x32_bf16 v[26:29], v[158:161], v[226:229], v[18:21]
	v_mfma_f32_16x16x32_bf16 v[10:13], v[158:161], v[234:237], v[10:13]
	v_mfma_f32_16x16x32_bf16 v[10:13], v[154:157], v[230:233], v[10:13]
	v_mfma_f32_16x16x32_bf16 v[18:21], v[154:157], v[202:205], v[58:61]
	v_mfma_f32_16x16x32_bf16 v[58:61], v[158:161], v[206:209], v[18:21]
	s_barrier
; #define PG8_STAGE(bufoff, gbase, voff) do { _Pragma("unroll") for (int _i = 0; _i < 2; ++_i) \
;         __builtin_amdgcn_global_load_lds((const unsigned*)((const char*)(gbase) + (voff)[_i]), (PG8_LAS unsigned*)(lds + (bufoff) + ldsw + _i * 8192), 16, 0, 0); } while (0)
; #define PG8_LDA(dst, b, h) do { _Pragma("unroll") for (int m = 0; m < 4; ++m) _Pragma("unroll") for (int k = 0; k < 2; ++k) dst[m][k] = *(const PG8_LAS bf16x8*)(lds + PG8_SA(b, h) + aoff + m * 2048 + k * 1024); } while (0)
; #define PG8_LDB(dst, b, h) do { _Pragma("unroll") for (int n = 0; n < 2; ++n) _Pragma("unroll") for (int k = 0; k < 2; ++k) dst[n][k] = *(const PG8_LAS bf16x8*)(lds + PG8_SB(b, h) + boff + n * 2048 + k * 1024); } while (0)
; #define PG8_MMA(ai, bj, At, Bt) do { __builtin_amdgcn_s_setprio(1); _Pragma("unroll") for (int m = 0; m < 4; ++m) _Pragma("unroll") for (int n = 0; n < 2; ++n) _Pragma("unroll") for (int k = 0; k < 2; ++k) \
;         acc[ai][bj][m][n] = __builtin_amdgcn_mfma_f32_16x16x32_bf16(Bt[n][k], At[m][k], acc[ai][bj][m][n], 0, 0, 0); __builtin_amdgcn_s_setprio(0); } while (0)
; #define PG8_WAIT_V(n) asm volatile("s_waitcnt vmcnt(" #n ")" ::: "memory")
; #define PG8_WAIT_L(n) asm volatile("s_waitcnt lgkmcnt(" #n ")" ::: "memory")
; #define PG8_BAR __builtin_amdgcn_s_barrier()
; #define PG8_SCHED __builtin_amdgcn_sched_barrier(0)
; template <class Epi, class Sched, bool ALIGN_EPI = false, bool SP2 = false>
; __device__ __forceinline__ void gemm_phase(PG8_LAS unsigned char* lds, const Gemm g, const Sched& S, const Epi& E) {
;     ...
;             PG8_LDB(B0, 1, 0); PG8_LDB(B1, 1, 1); PG8_SCHED; PG8_LDA(At, 1, 0); PG8_STAGE(PG8_SA(0, 1), a2 + hstep, voffA);
;             PG8_WAIT_V(8); PG8_WAIT_L(0); PG8_BAR; PG8_MMA(0, 0, At, B0); PG8_MMA(0, 1, At, B1); PG8_BAR; PG8_SCHED;
;             PG8_LDA(At, 1, 1); PG8_STAGE(PG8_SB(1, 0), b3, voffB); PG8_STAGE(PG8_SB(1, 1), b3 + hstep, voffB); PG8_STAGE(PG8_SA(1, 0), a3, voffA);
;             PG8_WAIT_V(8); PG8_WAIT_L(0); PG8_BAR; PG8_MMA(1, 0, At, B0); PG8_MMA(1, 1, At, B1); PG8_BAR; PG8_SCHED;
	s_setprio 0
	s_add_i32 s34, 0, 0x18000
	s_add_i32 s35, 0, 0x1c000
	v_add_u32_e32 v142, s34, v179
	v_add_u32_e32 v158, s35, v179
	ds_read_b128 v[18:21], v142
	ds_read_b128 v[22:25], v142 offset:1024
	ds_read_b128 v[138:141], v142 offset:2048
	ds_read_b128 v[142:145], v142 offset:3072
	ds_read_b128 v[146:149], v158
	ds_read_b128 v[150:153], v158 offset:1024
	ds_read_b128 v[154:157], v158 offset:2048
	ds_read_b128 v[158:161], v158 offset:3072
	s_add_u32 s16, s16, 0x100000
	s_addc_u32 s17, s17, 0
	s_mov_b32 m0, s71
	ds_read_b128 v[202:205], v199 offset:32768
	ds_read_b128 v[206:209], v199 offset:33792
	ds_read_b128 v[214:217], v199 offset:34816
	ds_read_b128 v[218:221], v199 offset:35840
	ds_read_b128 v[222:225], v199 offset:36864
	ds_read_b128 v[226:229], v199 offset:37888
	ds_read_b128 v[230:233], v199 offset:38912
	ds_read_b128 v[234:237], v199 offset:39936
	global_load_lds_dwordx4 v164, s[16:17]
	s_mov_b32 m0, s87
	s_nop 0
	global_load_lds_dwordx4 v170, s[16:17]
	s_waitcnt vmcnt(8) lgkmcnt(0)
	s_setprio 1
	s_barrier
	v_mfma_f32_16x16x32_bf16 v[134:137], v[18:21], v[202:205], v[134:137]
	v_mfma_f32_16x16x32_bf16 v[134:137], v[22:25], v[206:209], v[134:137]
	v_mfma_f32_16x16x32_bf16 v[118:121], v[22:25], v[218:221], v[118:121]
	v_mfma_f32_16x16x32_bf16 v[118:121], v[18:21], v[214:217], v[118:121]
	v_mfma_f32_16x16x32_bf16 v[102:105], v[18:21], v[222:225], v[102:105]
	v_mfma_f32_16x16x32_bf16 v[102:105], v[22:25], v[226:229], v[102:105]
	v_mfma_f32_16x16x32_bf16 v[86:89], v[22:25], v[234:237], v[86:89]
	v_mfma_f32_16x16x32_bf16 v[86:89], v[18:21], v[230:233], v[86:89]
	v_mfma_f32_16x16x32_bf16 v[82:85], v[138:141], v[230:233], v[82:85]
	v_mfma_f32_16x16x32_bf16 v[82:85], v[142:145], v[234:237], v[82:85]
	v_mfma_f32_16x16x32_bf16 v[130:133], v[142:145], v[206:209], v[130:133]
	v_mfma_f32_16x16x32_bf16 v[130:133], v[138:141], v[202:205], v[130:133]
	v_mfma_f32_16x16x32_bf16 v[114:117], v[138:141], v[214:217], v[114:117]
	v_mfma_f32_16x16x32_bf16 v[114:117], v[142:145], v[218:221], v[114:117]
	v_mfma_f32_16x16x32_bf16 v[98:101], v[142:145], v[226:229], v[98:101]
	v_mfma_f32_16x16x32_bf16 v[98:101], v[138:141], v[222:225], v[98:101]
	s_setprio 0
	s_setprio 1
	v_mfma_f32_16x16x32_bf16 v[94:97], v[146:149], v[222:225], v[94:97]
	v_mfma_f32_16x16x32_bf16 v[94:97], v[150:153], v[226:229], v[94:97]
	v_mfma_f32_16x16x32_bf16 v[126:129], v[150:153], v[206:209], v[126:129]
	v_mfma_f32_16x16x32_bf16 v[126:129], v[146:149], v[202:205], v[126:129]
	v_mfma_f32_16x16x32_bf16 v[110:113], v[146:149], v[214:217], v[110:113]
	v_mfma_f32_16x16x32_bf16 v[110:113], v[150:153], v[218:221], v[110:113]
	v_mfma_f32_16x16x32_bf16 v[78:81], v[150:153], v[234:237], v[78:81]
	v_mfma_f32_16x16x32_bf16 v[78:81], v[146:149], v[230:233], v[78:81]
	v_mfma_f32_16x16x32_bf16 v[74:77], v[154:157], v[230:233], v[74:77]
	v_mfma_f32_16x16x32_bf16 v[74:77], v[158:161], v[234:237], v[74:77]
	v_mfma_f32_16x16x32_bf16 v[122:125], v[158:161], v[206:209], v[122:125]
	v_mfma_f32_16x16x32_bf16 v[122:125], v[154:157], v[202:205], v[122:125]
	v_mfma_f32_16x16x32_bf16 v[106:109], v[154:157], v[214:217], v[106:109]
	v_mfma_f32_16x16x32_bf16 v[106:109], v[158:161], v[218:221], v[106:109]
	v_mfma_f32_16x16x32_bf16 v[90:93], v[158:161], v[226:229], v[90:93]
	v_mfma_f32_16x16x32_bf16 v[90:93], v[154:157], v[222:225], v[90:93]
	s_barrier
	s_setprio 0
	s_add_i32 s16, s34, s25
	s_add_u32 s98, s14, s46
	s_addc_u32 s99, s15, s47
	s_mov_b32 m0, s16
	ds_read_b128 v[202:205], v199 offset:49152
	ds_read_b128 v[206:209], v199 offset:50176
	ds_read_b128 v[214:217], v199 offset:51200
	ds_read_b128 v[218:221], v199 offset:52224
	ds_read_b128 v[222:225], v199 offset:53248
	ds_read_b128 v[226:229], v199 offset:54272
	ds_read_b128 v[230:233], v199 offset:55296
	ds_read_b128 v[234:237], v199 offset:56320
	global_load_lds_dwordx4 v168, s[98:99]
	s_add_i32 m0, s16, 0x2000
	s_add_u32 s14, s14, 0x100080
	s_addc_u32 s15, s15, 0
	s_add_i32 s16, s35, s25
	global_load_lds_dwordx4 v172, s[98:99]
	s_mov_b32 m0, s16
	s_nop 0
	global_load_lds_dwordx4 v168, s[14:15]
	s_add_i32 m0, s16, 0x2000
	s_nop 0
	global_load_lds_dwordx4 v172, s[14:15]
	v_lshl_add_u64 v[162:163], v[238:239], 0, s[46:47]
	s_mov_b32 m0, s95
	s_nop 0
	global_load_lds_dwordx4 v[162:163], off
	v_lshl_add_u64 v[162:163], v[240:241], 0, s[46:47]
	s_mov_b32 m0, s96
	s_nop 0
	global_load_lds_dwordx4 v[162:163], off
	s_waitcnt vmcnt(8) lgkmcnt(0)
	s_setprio 1
	s_barrier
	v_mfma_f32_16x16x32_bf16 v[70:73], v[18:21], v[202:205], v[70:73]
	v_mfma_f32_16x16x32_bf16 v[70:73], v[22:25], v[206:209], v[70:73]
	v_mfma_f32_16x16x32_bf16 v[54:57], v[22:25], v[218:221], v[54:57]
	v_mfma_f32_16x16x32_bf16 v[54:57], v[18:21], v[214:217], v[54:57]
	v_mfma_f32_16x16x32_bf16 v[38:41], v[18:21], v[222:225], v[38:41]
	v_mfma_f32_16x16x32_bf16 v[38:41], v[22:25], v[226:229], v[38:41]
	v_mfma_f32_16x16x32_bf16 v[2:5], v[22:25], v[234:237], v[2:5]
	v_mfma_f32_16x16x32_bf16 v[22:25], v[18:21], v[230:233], v[2:5]
	v_mfma_f32_16x16x32_bf16 v[2:5], v[138:141], v[230:233], v[6:9]
	v_mfma_f32_16x16x32_bf16 v[18:21], v[142:145], v[234:237], v[2:5]
	v_mfma_f32_16x16x32_bf16 v[66:69], v[142:145], v[206:209], v[66:69]
	v_mfma_f32_16x16x32_bf16 v[66:69], v[138:141], v[202:205], v[66:69]
	v_mfma_f32_16x16x32_bf16 v[50:53], v[138:141], v[214:217], v[50:53]
	v_mfma_f32_16x16x32_bf16 v[50:53], v[142:145], v[218:221], v[50:53]
	v_mfma_f32_16x16x32_bf16 v[34:37], v[142:145], v[226:229], v[34:37]
	v_mfma_f32_16x16x32_bf16 v[34:37], v[138:141], v[222:225], v[34:37]
	s_setprio 0
	s_setprio 1
	v_mfma_f32_16x16x32_bf16 v[2:5], v[146:149], v[222:225], v[30:33]
	v_mfma_f32_16x16x32_bf16 v[30:33], v[150:153], v[226:229], v[2:5]
	v_mfma_f32_16x16x32_bf16 v[2:5], v[150:153], v[234:237], v[14:17]
	v_mfma_f32_16x16x32_bf16 v[14:17], v[146:149], v[230:233], v[2:5]
	v_mfma_f32_16x16x32_bf16 v[2:5], v[146:149], v[202:205], v[62:65]
	v_mfma_f32_16x16x32_bf16 v[62:65], v[150:153], v[206:209], v[2:5]
	v_mfma_f32_16x16x32_bf16 v[2:5], v[150:153], v[218:221], v[46:49]
	v_mfma_f32_16x16x32_bf16 v[46:49], v[146:149], v[214:217], v[2:5]
	v_mfma_f32_16x16x32_bf16 v[2:5], v[154:157], v[214:217], v[42:45]
	v_mfma_f32_16x16x32_bf16 v[42:45], v[158:161], v[218:221], v[2:5]
	v_mfma_f32_16x16x32_bf16 v[2:5], v[158:161], v[226:229], v[26:29]
	v_mfma_f32_16x16x32_bf16 v[26:29], v[154:157], v[222:225], v[2:5]
	v_mfma_f32_16x16x32_bf16 v[2:5], v[154:157], v[230:233], v[10:13]
	v_mfma_f32_16x16x32_bf16 v[10:13], v[158:161], v[234:237], v[2:5]
	v_mfma_f32_16x16x32_bf16 v[2:5], v[158:161], v[206:209], v[58:61]
	v_mfma_f32_16x16x32_bf16 v[58:61], v[154:157], v[202:205], v[2:5]
	s_barrier
	s_setprio 0
	s_add_i32 s33, s33, 2
	s_add_u32 s12, s12, 0x100
	s_addc_u32 s13, s13, 0
	s_add_u32 s29, s29, 0x100
	s_addc_u32 s30, s30, 0
	s_cmp_gt_u32 s33, 61
	s_cbranch_scc0 .LBB0_139
	s_and_b64 vcc, exec, s[48:49]
	s_cbranch_vccz .LBB0_142
	s_barrier

; #define PG8_STAGE(bufoff, gbase, voff) do { _Pragma("unroll") for (int _i = 0; _i < 2; ++_i) \
;         __builtin_amdgcn_global_load_lds((const unsigned*)((const char*)(gbase) + (voff)[_i]), (PG8_LAS unsigned*)(lds + (bufoff) + ldsw + _i * 8192), 16, 0, 0); } while (0)
; #define PG8_LDA(dst, b, h) do { _Pragma("unroll") for (int m = 0; m < 4; ++m) _Pragma("unroll") for (int k = 0; k < 2; ++k) dst[m][k] = *(const PG8_LAS bf16x8*)(lds + PG8_SA(b, h) + aoff + m * 2048 + k * 1024); } while (0)
; #define PG8_LDB(dst, b, h) do { _Pragma("unroll") for (int n = 0; n < 2; ++n) _Pragma("unroll") for (int k = 0; k < 2; ++k) dst[n][k] = *(const PG8_LAS bf16x8*)(lds + PG8_SB(b, h) + boff + n * 2048 + k * 1024); } while (0)
; #define PG8_MMA(ai, bj, At, Bt) do { __builtin_amdgcn_s_setprio(1); _Pragma("unroll") for (int m = 0; m < 4; ++m) _Pragma("unroll") for (int n = 0; n < 2; ++n) _Pragma("unroll") for (int k = 0; k < 2; ++k) \
;         acc[ai][bj][m][n] = __builtin_amdgcn_mfma_f32_16x16x32_bf16(Bt[n][k], At[m][k], acc[ai][bj][m][n], 0, 0, 0); __builtin_amdgcn_s_setprio(0); } while (0)
; #define PG8_WAIT_V(n) asm volatile("s_waitcnt vmcnt(" #n ")" ::: "memory")
; #define PG8_WAIT_L(n) asm volatile("s_waitcnt lgkmcnt(" #n ")" ::: "memory")
; template <class Epi, class Sched, bool ALIGN_EPI = false, bool SP2 = false>
; __device__ __forceinline__ void gemm_phase(PG8_LAS unsigned char* lds, const Gemm g, const Sched& S, const Epi& E) {
;     ...
;             const bool last = (t == nt - 2);
;             const char* a1 = cA + (size_t)(t + 1) * kstep;
;             const char* a2 = last ? nA : cA + (size_t)(t + 2) * kstep; const char* b2 = last ? nB : cB + (size_t)(t + 2) * kstep;
;             const char* a3 = a2 + kstep; const char* b3 = b2 + kstep;
;             if (last && has_next) S.a_ready(nxt);
;             if constexpr (SP2) {
;             PG8_LDB(B0, 0, 0); PG8_LDB(B1, 0, 1); PG8_SCHED; PG8_LDA(At, 0, 0); PG8_STAGE(PG8_SA(1, 1), a1 + hstep, voffA);
;             PG8_WAIT_V(8); PG8_WAIT_L(0); PG8_BAR; PG8_MMA(0, 0, At, B0); PG8_MMA(0, 1, At, B1); PG8_BAR; PG8_SCHED;
;             PG8_LDA(At, 0, 1); PG8_STAGE(PG8_SB(0, 0), b2, voffB); PG8_STAGE(PG8_SB(0, 1), b2 + hstep, voffB); PG8_STAGE(PG8_SA(0, 0), a2, voffA);
;             PG8_WAIT_V(8); PG8_WAIT_L(0); PG8_BAR; PG8_MMA(1, 0, At, B0); PG8_MMA(1, 1, At, B1); PG8_BAR; PG8_SCHED;
.LBB0_592:
	s_or_b32 s10, s52, 1
	s_lshl_b64 s[96:97], s[10:11], 7
	s_add_i32 s10, s52, 2
	s_lshl_b64 s[54:55], s[10:11], 7
	s_cmp_lg_u32 s52, s94
	s_cselect_b32 s52, s54, 0
	s_cselect_b32 s53, s55, 0
	s_add_u32 s54, s50, s52
	s_addc_u32 s55, s51, s53
	s_add_i32 s95, 0, 0x10000
	v_add_u32_e32 v87, s95, v85
	ds_read_b128 v[88:91], v87
	ds_read_b128 v[92:95], v87 offset:1024
	ds_read_b128 v[100:103], v87 offset:2048
	ds_read_b128 v[104:107], v87 offset:3072
	s_add_u32 s52, s48, s52
	s_addc_u32 s53, s49, s53
	s_add_u32 s96, s50, s96
	s_addc_u32 s97, s51, s97
	s_add_u32 s96, s96, 0x100000
	s_addc_u32 s97, s97, 0
	s_add_i32 m0, s17, 0xc000
	ds_read_b128 v[108:111], v86
	ds_read_b128 v[112:115], v86 offset:1024
	ds_read_b128 v[116:119], v86 offset:2048
	ds_read_b128 v[120:123], v86 offset:3072
	ds_read_b128 v[124:127], v86 offset:4096
	ds_read_b128 v[128:131], v86 offset:5120
	ds_read_b128 v[132:135], v86 offset:6144
	ds_read_b128 v[136:139], v86 offset:7168
	global_load_lds_dwordx4 v66, s[96:97]
	s_add_i32 m0, s17, 0xe000
	s_nop 0
	global_load_lds_dwordx4 v76, s[96:97]
	s_waitcnt vmcnt(8) lgkmcnt(0)
	s_setprio 1
	s_barrier
	v_mfma_f32_16x16x32_bf16 v[62:65], v[88:91], v[108:111], v[62:65]
	v_mfma_f32_16x16x32_bf16 v[62:65], v[92:95], v[112:115], v[62:65]
	v_mfma_f32_16x16x32_bf16 v[54:57], v[92:95], v[120:123], v[54:57]
	v_mfma_f32_16x16x32_bf16 v[54:57], v[88:91], v[116:119], v[54:57]
	v_mfma_f32_16x16x32_bf16 v[46:49], v[88:91], v[124:127], v[46:49]
	v_mfma_f32_16x16x32_bf16 v[46:49], v[92:95], v[128:131], v[46:49]
	v_mfma_f32_16x16x32_bf16 v[38:41], v[92:95], v[136:139], v[38:41]
	v_mfma_f32_16x16x32_bf16 v[38:41], v[88:91], v[132:135], v[38:41]
	v_mfma_f32_16x16x32_bf16 v[34:37], v[100:103], v[132:135], v[34:37]
	v_mfma_f32_16x16x32_bf16 v[34:37], v[104:107], v[136:139], v[34:37]
	v_mfma_f32_16x16x32_bf16 v[58:61], v[104:107], v[112:115], v[58:61]
	v_mfma_f32_16x16x32_bf16 v[58:61], v[100:103], v[108:111], v[58:61]
	v_mfma_f32_16x16x32_bf16 v[50:53], v[100:103], v[116:119], v[50:53]
	v_mfma_f32_16x16x32_bf16 v[50:53], v[104:107], v[120:123], v[50:53]
	v_mfma_f32_16x16x32_bf16 v[42:45], v[104:107], v[128:131], v[42:45]
	v_mfma_f32_16x16x32_bf16 v[42:45], v[100:103], v[124:127], v[42:45]
	s_setprio 0
	s_setprio 1
	s_setprio 0
	s_barrier
	s_add_i32 s95, s95, s29
	s_mov_b32 m0, s95
	ds_read_b128 v[108:111], v86 offset:16384
	ds_read_b128 v[112:115], v86 offset:17408
	ds_read_b128 v[116:119], v86 offset:18432
	ds_read_b128 v[120:123], v86 offset:19456
	ds_read_b128 v[124:127], v86 offset:20480
	ds_read_b128 v[128:131], v86 offset:21504
	ds_read_b128 v[132:135], v86 offset:22528
	ds_read_b128 v[136:139], v86 offset:23552
	global_load_lds_dwordx4 v78, s[52:53]
	s_add_i32 m0, s95, 0x2000
	s_add_u32 s96, s52, 0x100000
	s_addc_u32 s97, s53, 0
	global_load_lds_dwordx4 v74, s[52:53]
	s_mov_b32 m0, s30
	v_lshl_add_u64 v[144:145], s[54:55], 0, v[76:77]
	global_load_lds_dwordx4 v78, s[96:97]
	s_mov_b32 m0, s33
	s_nop 0
	global_load_lds_dwordx4 v74, s[96:97]
	v_lshl_add_u64 v[142:143], s[54:55], 0, v[66:67]
	s_mov_b32 m0, s17
	s_nop 0
	global_load_lds_dwordx4 v66, s[54:55]
	s_mov_b32 m0, s34
	s_nop 0
	global_load_lds_dwordx4 v76, s[54:55]
	s_waitcnt vmcnt(8) lgkmcnt(0)
	s_setprio 1
	s_barrier
	v_mfma_f32_16x16x32_bf16 v[30:33], v[88:91], v[108:111], v[30:33]
	v_mfma_f32_16x16x32_bf16 v[30:33], v[92:95], v[112:115], v[30:33]
	v_mfma_f32_16x16x32_bf16 v[22:25], v[92:95], v[120:123], v[22:25]
	v_mfma_f32_16x16x32_bf16 v[22:25], v[88:91], v[116:119], v[22:25]
	v_mfma_f32_16x16x32_bf16 v[14:17], v[88:91], v[124:127], v[14:17]
	v_mfma_f32_16x16x32_bf16 v[14:17], v[92:95], v[128:131], v[14:17]
	v_mfma_f32_16x16x32_bf16 v[6:9], v[92:95], v[136:139], v[6:9]
	v_mfma_f32_16x16x32_bf16 v[6:9], v[88:91], v[132:135], v[6:9]
	v_mfma_f32_16x16x32_bf16 v[2:5], v[100:103], v[132:135], v[2:5]
	v_mfma_f32_16x16x32_bf16 v[2:5], v[104:107], v[136:139], v[2:5]
	v_mfma_f32_16x16x32_bf16 v[26:29], v[104:107], v[112:115], v[26:29]
	v_mfma_f32_16x16x32_bf16 v[26:29], v[100:103], v[108:111], v[26:29]
	v_mfma_f32_16x16x32_bf16 v[18:21], v[100:103], v[116:119], v[18:21]
	v_mfma_f32_16x16x32_bf16 v[18:21], v[104:107], v[120:123], v[18:21]
	v_mfma_f32_16x16x32_bf16 v[10:13], v[104:107], v[128:131], v[10:13]
	v_mfma_f32_16x16x32_bf16 v[10:13], v[100:103], v[124:127], v[10:13]
	s_setprio 0
	s_setprio 1
	s_setprio 0
	s_barrier
; #define PG8_STAGE(bufoff, gbase, voff) do { _Pragma("unroll") for (int _i = 0; _i < 2; ++_i) \
;         __builtin_amdgcn_global_load_lds((const unsigned*)((const char*)(gbase) + (voff)[_i]), (PG8_LAS unsigned*)(lds + (bufoff) + ldsw + _i * 8192), 16, 0, 0); } while (0)
; #define PG8_LDA(dst, b, h) do { _Pragma("unroll") for (int m = 0; m < 4; ++m) _Pragma("unroll") for (int k = 0; k < 2; ++k) dst[m][k] = *(const PG8_LAS bf16x8*)(lds + PG8_SA(b, h) + aoff + m * 2048 + k * 1024); } while (0)
; #define PG8_LDB(dst, b, h) do { _Pragma("unroll") for (int n = 0; n < 2; ++n) _Pragma("unroll") for (int k = 0; k < 2; ++k) dst[n][k] = *(const PG8_LAS bf16x8*)(lds + PG8_SB(b, h) + boff + n * 2048 + k * 1024); } while (0)
; #define PG8_MMA(ai, bj, At, Bt) do { __builtin_amdgcn_s_setprio(1); _Pragma("unroll") for (int m = 0; m < 4; ++m) _Pragma("unroll") for (int n = 0; n < 2; ++n) _Pragma("unroll") for (int k = 0; k < 2; ++k) \
;         acc[ai][bj][m][n] = __builtin_amdgcn_mfma_f32_16x16x32_bf16(Bt[n][k], At[m][k], acc[ai][bj][m][n], 0, 0, 0); __builtin_amdgcn_s_setprio(0); } while (0)
; #define PG8_WAIT_V(n) asm volatile("s_waitcnt vmcnt(" #n ")" ::: "memory")
; #define PG8_WAIT_L(n) asm volatile("s_waitcnt lgkmcnt(" #n ")" ::: "memory")
; #define PG8_BAR __builtin_amdgcn_s_barrier()
; #define PG8_SCHED __builtin_amdgcn_sched_barrier(0)
; template <class Epi, class Sched, bool ALIGN_EPI = false, bool SP2 = false>
; __device__ __forceinline__ void gemm_phase(PG8_LAS unsigned char* lds, const Gemm g, const Sched& S, const Epi& E) {
;     ...
;             PG8_LDB(B0, 1, 0); PG8_LDB(B1, 1, 1); PG8_SCHED; PG8_LDA(At, 1, 0); PG8_STAGE(PG8_SA(0, 1), a2 + hstep, voffA);
;             PG8_WAIT_V(8); PG8_WAIT_L(0); PG8_BAR; PG8_MMA(0, 0, At, B0); PG8_MMA(0, 1, At, B1); PG8_BAR; PG8_SCHED;
;             PG8_LDA(At, 1, 1); PG8_STAGE(PG8_SB(1, 0), b3, voffB); PG8_STAGE(PG8_SB(1, 1), b3 + hstep, voffB); PG8_STAGE(PG8_SA(1, 0), a3, voffA);
;             PG8_WAIT_V(8); PG8_WAIT_L(0); PG8_BAR; PG8_MMA(1, 0, At, B0); PG8_MMA(1, 1, At, B1); PG8_BAR; PG8_SCHED;
;     ...
;         if constexpr (ALIGN_EPI) { if (wr == 0) PG8_BAR; }
;         if constexpr (!Epi::AFTER_DRAIN) { E(acc, cur, wr, wc, fr, fq); S.done(cur); }
;         if (!has_next) break;
	s_add_i32 s95, 0, 0x18000
	v_add_u32_e32 v87, s95, v85
	ds_read_b128 v[88:91], v87
	ds_read_b128 v[92:95], v87 offset:1024
	ds_read_b128 v[100:103], v87 offset:2048
	ds_read_b128 v[104:107], v87 offset:3072
	s_add_u32 s54, s54, 0x100000
	s_addc_u32 s55, s55, 0
	s_mov_b32 m0, s35
	ds_read_b128 v[108:111], v86 offset:32768
	ds_read_b128 v[112:115], v86 offset:33792
	ds_read_b128 v[116:119], v86 offset:34816
	ds_read_b128 v[120:123], v86 offset:35840
	ds_read_b128 v[124:127], v86 offset:36864
	ds_read_b128 v[128:131], v86 offset:37888
	ds_read_b128 v[132:135], v86 offset:38912
	ds_read_b128 v[136:139], v86 offset:39936
	global_load_lds_dwordx4 v66, s[54:55]
	s_mov_b32 m0, s88
	s_nop 0
	global_load_lds_dwordx4 v76, s[54:55]
	s_waitcnt vmcnt(8) lgkmcnt(0)
	s_setprio 1
	s_barrier
	v_mfma_f32_16x16x32_bf16 v[62:65], v[88:91], v[108:111], v[62:65]
	v_mfma_f32_16x16x32_bf16 v[62:65], v[92:95], v[112:115], v[62:65]
	v_mfma_f32_16x16x32_bf16 v[54:57], v[92:95], v[120:123], v[54:57]
	v_mfma_f32_16x16x32_bf16 v[54:57], v[88:91], v[116:119], v[54:57]
	v_mfma_f32_16x16x32_bf16 v[46:49], v[88:91], v[124:127], v[46:49]
	v_mfma_f32_16x16x32_bf16 v[46:49], v[92:95], v[128:131], v[46:49]
	v_mfma_f32_16x16x32_bf16 v[38:41], v[92:95], v[136:139], v[38:41]
	v_mfma_f32_16x16x32_bf16 v[38:41], v[88:91], v[132:135], v[38:41]
	v_mfma_f32_16x16x32_bf16 v[34:37], v[100:103], v[132:135], v[34:37]
	v_mfma_f32_16x16x32_bf16 v[34:37], v[104:107], v[136:139], v[34:37]
	v_mfma_f32_16x16x32_bf16 v[58:61], v[104:107], v[112:115], v[58:61]
	v_mfma_f32_16x16x32_bf16 v[58:61], v[100:103], v[108:111], v[58:61]
	v_mfma_f32_16x16x32_bf16 v[50:53], v[100:103], v[116:119], v[50:53]
	v_mfma_f32_16x16x32_bf16 v[50:53], v[104:107], v[120:123], v[50:53]
	v_mfma_f32_16x16x32_bf16 v[42:45], v[104:107], v[128:131], v[42:45]
	v_mfma_f32_16x16x32_bf16 v[42:45], v[100:103], v[124:127], v[42:45]
	s_setprio 0
	s_setprio 1
	s_setprio 0
	s_barrier
	s_add_i32 s54, s95, s29
	s_add_u32 s98, s52, s14
	s_addc_u32 s99, s53, s15
	s_mov_b32 m0, s54
	ds_read_b128 v[108:111], v86 offset:49152
	ds_read_b128 v[112:115], v86 offset:50176
	ds_read_b128 v[116:119], v86 offset:51200
	ds_read_b128 v[120:123], v86 offset:52224
	ds_read_b128 v[124:127], v86 offset:53248
	ds_read_b128 v[128:131], v86 offset:54272
	ds_read_b128 v[132:135], v86 offset:55296
	ds_read_b128 v[136:139], v86 offset:56320
	global_load_lds_dwordx4 v78, s[98:99]
	s_add_i32 m0, s54, 0x2000
	s_add_u32 s52, s52, 0x100080
	s_addc_u32 s53, s53, 0
	global_load_lds_dwordx4 v74, s[98:99]
	s_mov_b32 m0, s92
	s_nop 0
	global_load_lds_dwordx4 v78, s[52:53]
	s_mov_b32 m0, s93
	s_nop 0
	global_load_lds_dwordx4 v74, s[52:53]
	v_lshl_add_u64 v[96:97], v[142:143], 0, s[14:15]
	s_mov_b32 m0, s90
	s_nop 0
	global_load_lds_dwordx4 v[96:97], off
	v_lshl_add_u64 v[96:97], v[144:145], 0, s[14:15]
	s_mov_b32 m0, s91
	s_nop 0
	global_load_lds_dwordx4 v[96:97], off
	s_waitcnt vmcnt(8) lgkmcnt(0)
	s_setprio 1
	s_barrier
	v_mfma_f32_16x16x32_bf16 v[30:33], v[88:91], v[108:111], v[30:33]
	v_mfma_f32_16x16x32_bf16 v[30:33], v[92:95], v[112:115], v[30:33]
	v_mfma_f32_16x16x32_bf16 v[22:25], v[92:95], v[120:123], v[22:25]
	v_mfma_f32_16x16x32_bf16 v[22:25], v[88:91], v[116:119], v[22:25]
	v_mfma_f32_16x16x32_bf16 v[14:17], v[88:91], v[124:127], v[14:17]
	v_mfma_f32_16x16x32_bf16 v[14:17], v[92:95], v[128:131], v[14:17]
	v_mfma_f32_16x16x32_bf16 v[6:9], v[92:95], v[136:139], v[6:9]
	v_mfma_f32_16x16x32_bf16 v[6:9], v[88:91], v[132:135], v[6:9]
	v_mfma_f32_16x16x32_bf16 v[2:5], v[100:103], v[132:135], v[2:5]
	v_mfma_f32_16x16x32_bf16 v[2:5], v[104:107], v[136:139], v[2:5]
	v_mfma_f32_16x16x32_bf16 v[26:29], v[104:107], v[112:115], v[26:29]
	v_mfma_f32_16x16x32_bf16 v[26:29], v[100:103], v[108:111], v[26:29]
	v_mfma_f32_16x16x32_bf16 v[18:21], v[100:103], v[116:119], v[18:21]
	v_mfma_f32_16x16x32_bf16 v[18:21], v[104:107], v[120:123], v[18:21]
	v_mfma_f32_16x16x32_bf16 v[10:13], v[104:107], v[128:131], v[10:13]
	v_mfma_f32_16x16x32_bf16 v[10:13], v[100:103], v[124:127], v[10:13]
	s_setprio 0
	s_setprio 1
	s_setprio 0
	s_barrier
	s_cmp_ge_u32 s10, s28
	s_mov_b32 s52, s10
	s_cbranch_scc0 .LBB0_592
	s_cmpk_lt_u32 s26, 0x100
	s_cbranch_scc0 .LBB0_482
	s_barrier
	s_branch .LBB0_482

; #define PG8_STAGE(bufoff, gbase, voff) do { _Pragma("unroll") for (int _i = 0; _i < 2; ++_i) \
;         __builtin_amdgcn_global_load_lds((const unsigned*)((const char*)(gbase) + (voff)[_i]), (PG8_LAS unsigned*)(lds + (bufoff) + ldsw + _i * 8192), 16, 0, 0); } while (0)
; #define PG8_LDA(dst, b, h) do { _Pragma("unroll") for (int m = 0; m < 4; ++m) _Pragma("unroll") for (int k = 0; k < 2; ++k) dst[m][k] = *(const PG8_LAS bf16x8*)(lds + PG8_SA(b, h) + aoff + m * 2048 + k * 1024); } while (0)
; #define PG8_LDB(dst, b, h) do { _Pragma("unroll") for (int n = 0; n < 2; ++n) _Pragma("unroll") for (int k = 0; k < 2; ++k) dst[n][k] = *(const PG8_LAS bf16x8*)(lds + PG8_SB(b, h) + boff + n * 2048 + k * 1024); } while (0)
; #define PG8_MMA(ai, bj, At, Bt) do { __builtin_amdgcn_s_setprio(1); _Pragma("unroll") for (int m = 0; m < 4; ++m) _Pragma("unroll") for (int n = 0; n < 2; ++n) _Pragma("unroll") for (int k = 0; k < 2; ++k) \
;         acc[ai][bj][m][n] = __builtin_amdgcn_mfma_f32_16x16x32_bf16(Bt[n][k], At[m][k], acc[ai][bj][m][n], 0, 0, 0); __builtin_amdgcn_s_setprio(0); } while (0)
; #define PG8_WAIT_V(n) asm volatile("s_waitcnt vmcnt(" #n ")" ::: "memory")
; #define PG8_WAIT_L(n) asm volatile("s_waitcnt lgkmcnt(" #n ")" ::: "memory")
; template <class Epi, class Sched, bool ALIGN_EPI = false, bool SP2 = false>
; __device__ __forceinline__ void gemm_phase(PG8_LAS unsigned char* lds, const Gemm g, const Sched& S, const Epi& E) {
;     ...
;             const bool last = (t == nt - 2);
;             const char* a1 = cA + (size_t)(t + 1) * kstep;
;             const char* a2 = last ? nA : cA + (size_t)(t + 2) * kstep; const char* b2 = last ? nB : cB + (size_t)(t + 2) * kstep;
;             const char* a3 = a2 + kstep; const char* b3 = b2 + kstep;
;             if (last && has_next) S.a_ready(nxt);
;             if constexpr (SP2) {
;             PG8_LDB(B0, 0, 0); PG8_LDB(B1, 0, 1); PG8_SCHED; PG8_LDA(At, 0, 0); PG8_STAGE(PG8_SA(1, 1), a1 + hstep, voffA);
;             PG8_WAIT_V(8); PG8_WAIT_L(0); PG8_BAR; PG8_MMA(0, 0, At, B0); PG8_MMA(0, 1, At, B1); PG8_BAR; PG8_SCHED;
;             PG8_LDA(At, 0, 1); PG8_STAGE(PG8_SB(0, 0), b2, voffB); PG8_STAGE(PG8_SB(0, 1), b2 + hstep, voffB); PG8_STAGE(PG8_SA(0, 0), a2, voffA);
;             PG8_WAIT_V(8); PG8_WAIT_L(0); PG8_BAR; PG8_MMA(1, 0, At, B0); PG8_MMA(1, 1, At, B1); PG8_BAR; PG8_SCHED;
.LBB0_1062:
	ds_read_b128 v[146:149], v155
	ds_read_b128 v[158:161], v155 offset:1024
	ds_read_b128 v[168:171], v155 offset:2048
	ds_read_b128 v[172:175], v155 offset:3072
	ds_read_b128 v[176:179], v156
	ds_read_b128 v[180:183], v156 offset:1024
	ds_read_b128 v[184:187], v156 offset:2048
	ds_read_b128 v[188:191], v156 offset:3072
	s_add_u32 s72, s70, 0xfff80080
	s_addc_u32 s73, s71, -1
	s_cmp_eq_u32 s77, 28
	s_cselect_b32 s75, s34, s73
	s_cselect_b32 s74, s35, s72
	s_cselect_b32 s73, s61, s76
	s_cselect_b32 s72, s63, s69
	s_add_i32 m0, s25, 0xc000
	ds_read_b128 v[200:203], v157
	ds_read_b128 v[204:207], v157 offset:1024
	ds_read_b128 v[208:211], v157 offset:2048
	ds_read_b128 v[212:215], v157 offset:3072
	ds_read_b128 v[216:219], v157 offset:4096
	ds_read_b128 v[220:223], v157 offset:5120
	ds_read_b128 v[224:227], v157 offset:6144
	ds_read_b128 v[228:231], v157 offset:7168
	global_load_lds_dwordx4 v138, s[70:71]
	s_add_i32 m0, s25, 0xe000
	s_nop 0
	global_load_lds_dwordx4 v140, s[70:71]
	s_waitcnt vmcnt(8) lgkmcnt(0)
	s_setprio 1
	s_barrier
	v_mfma_f32_16x16x32_bf16 v[126:129], v[146:149], v[200:203], v[126:129]
	v_mfma_f32_16x16x32_bf16 v[126:129], v[158:161], v[204:207], v[126:129]
	v_mfma_f32_16x16x32_bf16 v[110:113], v[158:161], v[212:215], v[110:113]
	v_mfma_f32_16x16x32_bf16 v[110:113], v[146:149], v[208:211], v[110:113]
	v_mfma_f32_16x16x32_bf16 v[94:97], v[146:149], v[216:219], v[94:97]
	v_mfma_f32_16x16x32_bf16 v[94:97], v[158:161], v[220:223], v[94:97]
	v_mfma_f32_16x16x32_bf16 v[78:81], v[158:161], v[228:231], v[78:81]
	v_mfma_f32_16x16x32_bf16 v[78:81], v[146:149], v[224:227], v[78:81]
	v_mfma_f32_16x16x32_bf16 v[74:77], v[168:171], v[224:227], v[74:77]
	v_mfma_f32_16x16x32_bf16 v[74:77], v[172:175], v[228:231], v[74:77]
	v_mfma_f32_16x16x32_bf16 v[122:125], v[172:175], v[204:207], v[122:125]
	v_mfma_f32_16x16x32_bf16 v[122:125], v[168:171], v[200:203], v[122:125]
	v_mfma_f32_16x16x32_bf16 v[106:109], v[168:171], v[208:211], v[106:109]
	v_mfma_f32_16x16x32_bf16 v[106:109], v[172:175], v[212:215], v[106:109]
	v_mfma_f32_16x16x32_bf16 v[90:93], v[172:175], v[220:223], v[90:93]
	v_mfma_f32_16x16x32_bf16 v[90:93], v[168:171], v[216:219], v[90:93]
	s_setprio 0
	s_setprio 1
	v_mfma_f32_16x16x32_bf16 v[86:89], v[176:179], v[216:219], v[86:89]
	v_mfma_f32_16x16x32_bf16 v[86:89], v[180:183], v[220:223], v[86:89]
	v_mfma_f32_16x16x32_bf16 v[118:121], v[180:183], v[204:207], v[118:121]
	v_mfma_f32_16x16x32_bf16 v[118:121], v[176:179], v[200:203], v[118:121]
	v_mfma_f32_16x16x32_bf16 v[102:105], v[176:179], v[208:211], v[102:105]
	v_mfma_f32_16x16x32_bf16 v[102:105], v[180:183], v[212:215], v[102:105]
	v_mfma_f32_16x16x32_bf16 v[70:73], v[180:183], v[228:231], v[70:73]
	v_mfma_f32_16x16x32_bf16 v[70:73], v[176:179], v[224:227], v[70:73]
	v_mfma_f32_16x16x32_bf16 v[66:69], v[184:187], v[224:227], v[66:69]
	v_mfma_f32_16x16x32_bf16 v[66:69], v[188:191], v[228:231], v[66:69]
	v_mfma_f32_16x16x32_bf16 v[114:117], v[188:191], v[204:207], v[114:117]
	v_mfma_f32_16x16x32_bf16 v[114:117], v[184:187], v[200:203], v[114:117]
	v_mfma_f32_16x16x32_bf16 v[98:101], v[184:187], v[208:211], v[98:101]
	v_mfma_f32_16x16x32_bf16 v[98:101], v[188:191], v[212:215], v[98:101]
	v_mfma_f32_16x16x32_bf16 v[82:85], v[188:191], v[220:223], v[82:85]
	v_mfma_f32_16x16x32_bf16 v[82:85], v[184:187], v[216:219], v[82:85]
	s_barrier
	s_setprio 0
	s_add_i32 s78, s31, s2
	s_mov_b32 m0, s78
	ds_read_b128 v[200:203], v157 offset:16384
	ds_read_b128 v[204:207], v157 offset:17408
	ds_read_b128 v[208:211], v157 offset:18432
	ds_read_b128 v[212:215], v157 offset:19456
	ds_read_b128 v[216:219], v157 offset:20480
	ds_read_b128 v[220:223], v157 offset:21504
	ds_read_b128 v[224:227], v157 offset:22528
	ds_read_b128 v[228:231], v157 offset:23552
	global_load_lds_dwordx4 v134, s[72:73]
	s_add_i32 m0, s78, 0x2000
	s_add_u32 s78, s72, 0x80000
	s_addc_u32 s79, s73, 0
	s_add_i32 s80, s40, s2
	global_load_lds_dwordx4 v130, s[72:73]
	s_mov_b32 m0, s80
	v_lshl_add_u64 v[232:233], s[74:75], 0, v[132:133]
	global_load_lds_dwordx4 v134, s[78:79]
	s_add_i32 m0, s80, 0x2000
	s_nop 0
	global_load_lds_dwordx4 v130, s[78:79]
	v_lshl_add_u64 v[192:193], s[74:75], 0, v[136:137]
	s_mov_b32 m0, s25
	s_nop 0
	global_load_lds_dwordx4 v136, s[74:75]
	s_mov_b32 m0, s26
	s_nop 0
	global_load_lds_dwordx4 v132, s[74:75]
	s_waitcnt vmcnt(8) lgkmcnt(0)
	s_setprio 1
	s_barrier
	v_mfma_f32_16x16x32_bf16 v[62:65], v[146:149], v[200:203], v[62:65]
	v_mfma_f32_16x16x32_bf16 v[62:65], v[158:161], v[204:207], v[62:65]
	v_mfma_f32_16x16x32_bf16 v[46:49], v[158:161], v[212:215], v[46:49]
	v_mfma_f32_16x16x32_bf16 v[46:49], v[146:149], v[208:211], v[46:49]
	v_mfma_f32_16x16x32_bf16 v[30:33], v[146:149], v[216:219], v[30:33]
	v_mfma_f32_16x16x32_bf16 v[30:33], v[158:161], v[220:223], v[30:33]
	v_mfma_f32_16x16x32_bf16 v[14:17], v[158:161], v[228:231], v[14:17]
	v_mfma_f32_16x16x32_bf16 v[14:17], v[146:149], v[224:227], v[14:17]
	v_mfma_f32_16x16x32_bf16 v[10:13], v[168:171], v[224:227], v[10:13]
	v_mfma_f32_16x16x32_bf16 v[10:13], v[172:175], v[228:231], v[10:13]
	v_mfma_f32_16x16x32_bf16 v[58:61], v[172:175], v[204:207], v[58:61]
	v_mfma_f32_16x16x32_bf16 v[58:61], v[168:171], v[200:203], v[58:61]
	v_mfma_f32_16x16x32_bf16 v[42:45], v[168:171], v[208:211], v[42:45]
	v_mfma_f32_16x16x32_bf16 v[42:45], v[172:175], v[212:215], v[42:45]
	v_mfma_f32_16x16x32_bf16 v[26:29], v[172:175], v[220:223], v[26:29]
	v_mfma_f32_16x16x32_bf16 v[26:29], v[168:171], v[216:219], v[26:29]
	s_setprio 0
	s_setprio 1
	v_mfma_f32_16x16x32_bf16 v[22:25], v[176:179], v[216:219], v[22:25]
	v_mfma_f32_16x16x32_bf16 v[22:25], v[180:183], v[220:223], v[22:25]
	v_mfma_f32_16x16x32_bf16 v[54:57], v[180:183], v[204:207], v[54:57]
	v_mfma_f32_16x16x32_bf16 v[54:57], v[176:179], v[200:203], v[54:57]
	v_mfma_f32_16x16x32_bf16 v[38:41], v[176:179], v[208:211], v[38:41]
	v_mfma_f32_16x16x32_bf16 v[38:41], v[180:183], v[212:215], v[38:41]
	v_mfma_f32_16x16x32_bf16 v[6:9], v[180:183], v[228:231], v[6:9]
	v_mfma_f32_16x16x32_bf16 v[6:9], v[176:179], v[224:227], v[6:9]
	v_mfma_f32_16x16x32_bf16 v[2:5], v[184:187], v[224:227], v[2:5]
	v_mfma_f32_16x16x32_bf16 v[2:5], v[188:191], v[228:231], v[2:5]
	v_mfma_f32_16x16x32_bf16 v[50:53], v[188:191], v[204:207], v[50:53]
	v_mfma_f32_16x16x32_bf16 v[50:53], v[184:187], v[200:203], v[50:53]
	v_mfma_f32_16x16x32_bf16 v[34:37], v[184:187], v[208:211], v[34:37]
	v_mfma_f32_16x16x32_bf16 v[34:37], v[188:191], v[212:215], v[34:37]
	v_mfma_f32_16x16x32_bf16 v[18:21], v[188:191], v[220:223], v[18:21]
	v_mfma_f32_16x16x32_bf16 v[18:21], v[184:187], v[216:219], v[18:21]
	s_barrier
; #define PG8_STAGE(bufoff, gbase, voff) do { _Pragma("unroll") for (int _i = 0; _i < 2; ++_i) \
;         __builtin_amdgcn_global_load_lds((const unsigned*)((const char*)(gbase) + (voff)[_i]), (PG8_LAS unsigned*)(lds + (bufoff) + ldsw + _i * 8192), 16, 0, 0); } while (0)
; #define PG8_LDA(dst, b, h) do { _Pragma("unroll") for (int m = 0; m < 4; ++m) _Pragma("unroll") for (int k = 0; k < 2; ++k) dst[m][k] = *(const PG8_LAS bf16x8*)(lds + PG8_SA(b, h) + aoff + m * 2048 + k * 1024); } while (0)
; #define PG8_LDB(dst, b, h) do { _Pragma("unroll") for (int n = 0; n < 2; ++n) _Pragma("unroll") for (int k = 0; k < 2; ++k) dst[n][k] = *(const PG8_LAS bf16x8*)(lds + PG8_SB(b, h) + boff + n * 2048 + k * 1024); } while (0)
; #define PG8_MMA(ai, bj, At, Bt) do { __builtin_amdgcn_s_setprio(1); _Pragma("unroll") for (int m = 0; m < 4; ++m) _Pragma("unroll") for (int n = 0; n < 2; ++n) _Pragma("unroll") for (int k = 0; k < 2; ++k) \
;         acc[ai][bj][m][n] = __builtin_amdgcn_mfma_f32_16x16x32_bf16(Bt[n][k], At[m][k], acc[ai][bj][m][n], 0, 0, 0); __builtin_amdgcn_s_setprio(0); } while (0)
; #define PG8_WAIT_V(n) asm volatile("s_waitcnt vmcnt(" #n ")" ::: "memory")
; #define PG8_WAIT_L(n) asm volatile("s_waitcnt lgkmcnt(" #n ")" ::: "memory")
; #define PG8_BAR __builtin_amdgcn_s_barrier()
; #define PG8_SCHED __builtin_amdgcn_sched_barrier(0)
; template <class Epi, class Sched, bool ALIGN_EPI = false, bool SP2 = false>
; __device__ __forceinline__ void gemm_phase(PG8_LAS unsigned char* lds, const Gemm g, const Sched& S, const Epi& E) {
;     ...
;             PG8_LDB(B0, 1, 0); PG8_LDB(B1, 1, 1); PG8_SCHED; PG8_LDA(At, 1, 0); PG8_STAGE(PG8_SA(0, 1), a2 + hstep, voffA);
;             PG8_WAIT_V(8); PG8_WAIT_L(0); PG8_BAR; PG8_MMA(0, 0, At, B0); PG8_MMA(0, 1, At, B1); PG8_BAR; PG8_SCHED;
;             PG8_LDA(At, 1, 1); PG8_STAGE(PG8_SB(1, 0), b3, voffB); PG8_STAGE(PG8_SB(1, 1), b3 + hstep, voffB); PG8_STAGE(PG8_SA(1, 0), a3, voffA);
;             PG8_WAIT_V(8); PG8_WAIT_L(0); PG8_BAR; PG8_MMA(1, 0, At, B0); PG8_MMA(1, 1, At, B1); PG8_BAR; PG8_SCHED;
	s_setprio 0
	s_add_i32 s78, 0, 0x18000
	v_add_u32_e32 v166, s78, v153
	s_add_i32 s79, 0, 0x1c000
	ds_read_b128 v[146:149], v166
	ds_read_b128 v[158:161], v166 offset:1024
	ds_read_b128 v[168:171], v166 offset:2048
	ds_read_b128 v[172:175], v166 offset:3072
	v_add_u32_e32 v166, s79, v153
	ds_read_b128 v[176:179], v166
	ds_read_b128 v[180:183], v166 offset:1024
	ds_read_b128 v[184:187], v166 offset:2048
	ds_read_b128 v[188:191], v166 offset:3072
	s_add_u32 s74, s74, 0x80000
	s_addc_u32 s75, s75, 0
	s_mov_b32 m0, s27
	ds_read_b128 v[200:203], v157 offset:32768
	ds_read_b128 v[204:207], v157 offset:33792
	ds_read_b128 v[208:211], v157 offset:34816
	ds_read_b128 v[212:215], v157 offset:35840
	ds_read_b128 v[216:219], v157 offset:36864
	ds_read_b128 v[220:223], v157 offset:37888
	ds_read_b128 v[224:227], v157 offset:38912
	ds_read_b128 v[228:231], v157 offset:39936
	global_load_lds_dwordx4 v136, s[74:75]
	s_mov_b32 m0, s28
	s_nop 0
	global_load_lds_dwordx4 v132, s[74:75]
	s_waitcnt vmcnt(8) lgkmcnt(0)
	s_setprio 1
	s_barrier
	v_mfma_f32_16x16x32_bf16 v[126:129], v[146:149], v[200:203], v[126:129]
	v_mfma_f32_16x16x32_bf16 v[126:129], v[158:161], v[204:207], v[126:129]
	v_mfma_f32_16x16x32_bf16 v[110:113], v[158:161], v[212:215], v[110:113]
	v_mfma_f32_16x16x32_bf16 v[110:113], v[146:149], v[208:211], v[110:113]
	v_mfma_f32_16x16x32_bf16 v[94:97], v[146:149], v[216:219], v[94:97]
	v_mfma_f32_16x16x32_bf16 v[94:97], v[158:161], v[220:223], v[94:97]
	v_mfma_f32_16x16x32_bf16 v[78:81], v[158:161], v[228:231], v[78:81]
	v_mfma_f32_16x16x32_bf16 v[78:81], v[146:149], v[224:227], v[78:81]
	v_mfma_f32_16x16x32_bf16 v[74:77], v[168:171], v[224:227], v[74:77]
	v_mfma_f32_16x16x32_bf16 v[74:77], v[172:175], v[228:231], v[74:77]
	v_mfma_f32_16x16x32_bf16 v[122:125], v[172:175], v[204:207], v[122:125]
	v_mfma_f32_16x16x32_bf16 v[122:125], v[168:171], v[200:203], v[122:125]
	v_mfma_f32_16x16x32_bf16 v[106:109], v[168:171], v[208:211], v[106:109]
	v_mfma_f32_16x16x32_bf16 v[106:109], v[172:175], v[212:215], v[106:109]
	v_mfma_f32_16x16x32_bf16 v[90:93], v[172:175], v[220:223], v[90:93]
	v_mfma_f32_16x16x32_bf16 v[90:93], v[168:171], v[216:219], v[90:93]
	s_setprio 0
	s_setprio 1
	v_mfma_f32_16x16x32_bf16 v[86:89], v[176:179], v[216:219], v[86:89]
	v_mfma_f32_16x16x32_bf16 v[86:89], v[180:183], v[220:223], v[86:89]
	v_mfma_f32_16x16x32_bf16 v[118:121], v[180:183], v[204:207], v[118:121]
	v_mfma_f32_16x16x32_bf16 v[118:121], v[176:179], v[200:203], v[118:121]
	v_mfma_f32_16x16x32_bf16 v[102:105], v[176:179], v[208:211], v[102:105]
	v_mfma_f32_16x16x32_bf16 v[102:105], v[180:183], v[212:215], v[102:105]
	v_mfma_f32_16x16x32_bf16 v[70:73], v[180:183], v[228:231], v[70:73]
	v_mfma_f32_16x16x32_bf16 v[70:73], v[176:179], v[224:227], v[70:73]
	v_mfma_f32_16x16x32_bf16 v[66:69], v[184:187], v[224:227], v[66:69]
	v_mfma_f32_16x16x32_bf16 v[66:69], v[188:191], v[228:231], v[66:69]
	v_mfma_f32_16x16x32_bf16 v[114:117], v[188:191], v[204:207], v[114:117]
	v_mfma_f32_16x16x32_bf16 v[114:117], v[184:187], v[200:203], v[114:117]
	v_mfma_f32_16x16x32_bf16 v[98:101], v[184:187], v[208:211], v[98:101]
	v_mfma_f32_16x16x32_bf16 v[98:101], v[188:191], v[212:215], v[98:101]
	v_mfma_f32_16x16x32_bf16 v[82:85], v[188:191], v[220:223], v[82:85]
	v_mfma_f32_16x16x32_bf16 v[82:85], v[184:187], v[216:219], v[82:85]
	s_barrier
	s_setprio 0
	s_add_i32 s74, s78, s2
	s_add_u32 s98, s72, s10
	s_addc_u32 s99, s73, s11
	s_mov_b32 m0, s74
	ds_read_b128 v[200:203], v157 offset:49152
	ds_read_b128 v[204:207], v157 offset:50176
	ds_read_b128 v[208:211], v157 offset:51200
	ds_read_b128 v[212:215], v157 offset:52224
	ds_read_b128 v[216:219], v157 offset:53248
	ds_read_b128 v[220:223], v157 offset:54272
	ds_read_b128 v[224:227], v157 offset:55296
	ds_read_b128 v[228:231], v157 offset:56320
	global_load_lds_dwordx4 v134, s[98:99]
	s_add_i32 m0, s74, 0x2000
	s_add_u32 s72, s72, 0x80080
	s_addc_u32 s73, s73, 0
	s_add_i32 s74, s79, s2
	global_load_lds_dwordx4 v130, s[98:99]
	s_mov_b32 m0, s74
	s_nop 0
	global_load_lds_dwordx4 v134, s[72:73]
	s_add_i32 m0, s74, 0x2000
	s_nop 0
	global_load_lds_dwordx4 v130, s[72:73]
	v_lshl_add_u64 v[150:151], v[192:193], 0, s[10:11]
	s_mov_b32 m0, s30
	s_nop 0
	global_load_lds_dwordx4 v[150:151], off
	v_lshl_add_u64 v[150:151], v[232:233], 0, s[10:11]
	s_mov_b32 m0, s33
	s_nop 0
	global_load_lds_dwordx4 v[150:151], off
	s_waitcnt vmcnt(8) lgkmcnt(0)
	s_setprio 1
	s_barrier
	v_mfma_f32_16x16x32_bf16 v[62:65], v[146:149], v[200:203], v[62:65]
	v_mfma_f32_16x16x32_bf16 v[62:65], v[158:161], v[204:207], v[62:65]
	v_mfma_f32_16x16x32_bf16 v[46:49], v[158:161], v[212:215], v[46:49]
	v_mfma_f32_16x16x32_bf16 v[46:49], v[146:149], v[208:211], v[46:49]
	v_mfma_f32_16x16x32_bf16 v[30:33], v[146:149], v[216:219], v[30:33]
	v_mfma_f32_16x16x32_bf16 v[30:33], v[158:161], v[220:223], v[30:33]
	v_mfma_f32_16x16x32_bf16 v[14:17], v[158:161], v[228:231], v[14:17]
	v_mfma_f32_16x16x32_bf16 v[14:17], v[146:149], v[224:227], v[14:17]
	v_mfma_f32_16x16x32_bf16 v[10:13], v[168:171], v[224:227], v[10:13]
	v_mfma_f32_16x16x32_bf16 v[10:13], v[172:175], v[228:231], v[10:13]
	v_mfma_f32_16x16x32_bf16 v[58:61], v[172:175], v[204:207], v[58:61]
	v_mfma_f32_16x16x32_bf16 v[58:61], v[168:171], v[200:203], v[58:61]
	v_mfma_f32_16x16x32_bf16 v[42:45], v[168:171], v[208:211], v[42:45]
	v_mfma_f32_16x16x32_bf16 v[42:45], v[172:175], v[212:215], v[42:45]
	v_mfma_f32_16x16x32_bf16 v[26:29], v[172:175], v[220:223], v[26:29]
	v_mfma_f32_16x16x32_bf16 v[26:29], v[168:171], v[216:219], v[26:29]
	s_setprio 0
	s_setprio 1
	v_mfma_f32_16x16x32_bf16 v[22:25], v[176:179], v[216:219], v[22:25]
	v_mfma_f32_16x16x32_bf16 v[22:25], v[180:183], v[220:223], v[22:25]
	v_mfma_f32_16x16x32_bf16 v[54:57], v[180:183], v[204:207], v[54:57]
	v_mfma_f32_16x16x32_bf16 v[54:57], v[176:179], v[200:203], v[54:57]
	v_mfma_f32_16x16x32_bf16 v[38:41], v[176:179], v[208:211], v[38:41]
	v_mfma_f32_16x16x32_bf16 v[38:41], v[180:183], v[212:215], v[38:41]
	v_mfma_f32_16x16x32_bf16 v[6:9], v[180:183], v[228:231], v[6:9]
	v_mfma_f32_16x16x32_bf16 v[6:9], v[176:179], v[224:227], v[6:9]
	v_mfma_f32_16x16x32_bf16 v[2:5], v[184:187], v[224:227], v[2:5]
	v_mfma_f32_16x16x32_bf16 v[2:5], v[188:191], v[228:231], v[2:5]
	v_mfma_f32_16x16x32_bf16 v[50:53], v[188:191], v[204:207], v[50:53]
	v_mfma_f32_16x16x32_bf16 v[50:53], v[184:187], v[200:203], v[50:53]
	v_mfma_f32_16x16x32_bf16 v[34:37], v[184:187], v[208:211], v[34:37]
	v_mfma_f32_16x16x32_bf16 v[34:37], v[188:191], v[212:215], v[34:37]
	v_mfma_f32_16x16x32_bf16 v[18:21], v[188:191], v[220:223], v[18:21]
	v_mfma_f32_16x16x32_bf16 v[18:21], v[184:187], v[216:219], v[18:21]
	s_barrier
	s_setprio 0
	s_add_i32 s77, s77, 2
	s_add_u32 s70, s70, 0x100
	s_addc_u32 s71, s71, 0
	s_add_u32 s69, s69, 0x100
	s_addc_u32 s76, s76, 0
	s_cmp_gt_u32 s77, 29
	s_cbranch_scc0 .LBB0_1062
	s_and_b64 vcc, exec, s[48:49]
	s_cbranch_vccz .LBB0_1065
	s_barrier

; #define PG8_STAGE(bufoff, gbase, voff) do { _Pragma("unroll") for (int _i = 0; _i < 2; ++_i) \
;         __builtin_amdgcn_global_load_lds((const unsigned*)((const char*)(gbase) + (voff)[_i]), (PG8_LAS unsigned*)(lds + (bufoff) + ldsw + _i * 8192), 16, 0, 0); } while (0)
; #define PG8_LDA(dst, b, h) do { _Pragma("unroll") for (int m = 0; m < 4; ++m) _Pragma("unroll") for (int k = 0; k < 2; ++k) dst[m][k] = *(const PG8_LAS bf16x8*)(lds + PG8_SA(b, h) + aoff + m * 2048 + k * 1024); } while (0)
; #define PG8_LDB(dst, b, h) do { _Pragma("unroll") for (int n = 0; n < 2; ++n) _Pragma("unroll") for (int k = 0; k < 2; ++k) dst[n][k] = *(const PG8_LAS bf16x8*)(lds + PG8_SB(b, h) + boff + n * 2048 + k * 1024); } while (0)
; #define PG8_MMA(ai, bj, At, Bt) do { __builtin_amdgcn_s_setprio(1); _Pragma("unroll") for (int m = 0; m < 4; ++m) _Pragma("unroll") for (int n = 0; n < 2; ++n) _Pragma("unroll") for (int k = 0; k < 2; ++k) \
;         acc[ai][bj][m][n] = __builtin_amdgcn_mfma_f32_16x16x32_bf16(Bt[n][k], At[m][k], acc[ai][bj][m][n], 0, 0, 0); __builtin_amdgcn_s_setprio(0); } while (0)
; #define PG8_WAIT_V(n) asm volatile("s_waitcnt vmcnt(" #n ")" ::: "memory")
; #define PG8_WAIT_L(n) asm volatile("s_waitcnt lgkmcnt(" #n ")" ::: "memory")
; template <class Epi, class Sched, bool ALIGN_EPI = false, bool SP2 = false>
; __device__ __forceinline__ void gemm_phase(PG8_LAS unsigned char* lds, const Gemm g, const Sched& S, const Epi& E) {
;     ...
;             const bool last = (t == nt - 2);
;             const char* a1 = cA + (size_t)(t + 1) * kstep;
;             const char* a2 = last ? nA : cA + (size_t)(t + 2) * kstep; const char* b2 = last ? nB : cB + (size_t)(t + 2) * kstep;
;             const char* a3 = a2 + kstep; const char* b3 = b2 + kstep;
;             if (last && has_next) S.a_ready(nxt);
;             if constexpr (SP2) {
;             PG8_LDB(B0, 0, 0); PG8_LDB(B1, 0, 1); PG8_SCHED; PG8_LDA(At, 0, 0); PG8_STAGE(PG8_SA(1, 1), a1 + hstep, voffA);
;             PG8_WAIT_V(8); PG8_WAIT_L(0); PG8_BAR; PG8_MMA(0, 0, At, B0); PG8_MMA(0, 1, At, B1); PG8_BAR; PG8_SCHED;
;             PG8_LDA(At, 0, 1); PG8_STAGE(PG8_SB(0, 0), b2, voffB); PG8_STAGE(PG8_SB(0, 1), b2 + hstep, voffB); PG8_STAGE(PG8_SA(0, 0), a2, voffA);
;             PG8_WAIT_V(8); PG8_WAIT_L(0); PG8_BAR; PG8_MMA(1, 0, At, B0); PG8_MMA(1, 1, At, B1); PG8_BAR; PG8_SCHED;
.LBB0_1078:
	ds_read_b128 v[146:149], v155
	ds_read_b128 v[158:161], v155 offset:1024
	ds_read_b128 v[168:171], v155 offset:2048
	ds_read_b128 v[172:175], v155 offset:3072
	ds_read_b128 v[176:179], v156
	ds_read_b128 v[180:183], v156 offset:1024
	ds_read_b128 v[184:187], v156 offset:2048
	ds_read_b128 v[188:191], v156 offset:3072
	s_add_u32 s68, s66, 0xfff80080
	s_addc_u32 s69, s67, -1
	s_cmp_eq_u32 s73, 28
	s_cselect_b32 s71, s34, s69
	s_cselect_b32 s70, s35, s68
	s_cselect_b32 s69, s57, s72
	s_cselect_b32 s68, s59, s65
	s_add_i32 m0, s25, 0xc000
	ds_read_b128 v[200:203], v157
	ds_read_b128 v[204:207], v157 offset:1024
	ds_read_b128 v[208:211], v157 offset:2048
	ds_read_b128 v[212:215], v157 offset:3072
	ds_read_b128 v[216:219], v157 offset:4096
	ds_read_b128 v[220:223], v157 offset:5120
	ds_read_b128 v[224:227], v157 offset:6144
	ds_read_b128 v[228:231], v157 offset:7168
	global_load_lds_dwordx4 v138, s[66:67]
	s_add_i32 m0, s25, 0xe000
	s_nop 0
	global_load_lds_dwordx4 v140, s[66:67]
	s_waitcnt vmcnt(8) lgkmcnt(0)
	s_setprio 1
	s_barrier
	v_mfma_f32_16x16x32_bf16 v[126:129], v[146:149], v[200:203], v[126:129]
	v_mfma_f32_16x16x32_bf16 v[126:129], v[158:161], v[204:207], v[126:129]
	v_mfma_f32_16x16x32_bf16 v[110:113], v[158:161], v[212:215], v[110:113]
	v_mfma_f32_16x16x32_bf16 v[110:113], v[146:149], v[208:211], v[110:113]
	v_mfma_f32_16x16x32_bf16 v[94:97], v[146:149], v[216:219], v[94:97]
	v_mfma_f32_16x16x32_bf16 v[94:97], v[158:161], v[220:223], v[94:97]
	v_mfma_f32_16x16x32_bf16 v[78:81], v[158:161], v[228:231], v[78:81]
	v_mfma_f32_16x16x32_bf16 v[78:81], v[146:149], v[224:227], v[78:81]
	v_mfma_f32_16x16x32_bf16 v[74:77], v[168:171], v[224:227], v[74:77]
	v_mfma_f32_16x16x32_bf16 v[74:77], v[172:175], v[228:231], v[74:77]
	v_mfma_f32_16x16x32_bf16 v[122:125], v[172:175], v[204:207], v[122:125]
	v_mfma_f32_16x16x32_bf16 v[122:125], v[168:171], v[200:203], v[122:125]
	v_mfma_f32_16x16x32_bf16 v[106:109], v[168:171], v[208:211], v[106:109]
	v_mfma_f32_16x16x32_bf16 v[106:109], v[172:175], v[212:215], v[106:109]
	v_mfma_f32_16x16x32_bf16 v[90:93], v[172:175], v[220:223], v[90:93]
	v_mfma_f32_16x16x32_bf16 v[90:93], v[168:171], v[216:219], v[90:93]
	s_setprio 0
	s_setprio 1
	v_mfma_f32_16x16x32_bf16 v[86:89], v[176:179], v[216:219], v[86:89]
	v_mfma_f32_16x16x32_bf16 v[86:89], v[180:183], v[220:223], v[86:89]
	v_mfma_f32_16x16x32_bf16 v[118:121], v[180:183], v[204:207], v[118:121]
	v_mfma_f32_16x16x32_bf16 v[118:121], v[176:179], v[200:203], v[118:121]
	v_mfma_f32_16x16x32_bf16 v[102:105], v[176:179], v[208:211], v[102:105]
	v_mfma_f32_16x16x32_bf16 v[102:105], v[180:183], v[212:215], v[102:105]
	v_mfma_f32_16x16x32_bf16 v[70:73], v[180:183], v[228:231], v[70:73]
	v_mfma_f32_16x16x32_bf16 v[70:73], v[176:179], v[224:227], v[70:73]
	v_mfma_f32_16x16x32_bf16 v[66:69], v[184:187], v[224:227], v[66:69]
	v_mfma_f32_16x16x32_bf16 v[66:69], v[188:191], v[228:231], v[66:69]
	v_mfma_f32_16x16x32_bf16 v[114:117], v[188:191], v[204:207], v[114:117]
	v_mfma_f32_16x16x32_bf16 v[114:117], v[184:187], v[200:203], v[114:117]
	v_mfma_f32_16x16x32_bf16 v[98:101], v[184:187], v[208:211], v[98:101]
	v_mfma_f32_16x16x32_bf16 v[98:101], v[188:191], v[212:215], v[98:101]
	v_mfma_f32_16x16x32_bf16 v[82:85], v[188:191], v[220:223], v[82:85]
	v_mfma_f32_16x16x32_bf16 v[82:85], v[184:187], v[216:219], v[82:85]
	s_barrier
	s_setprio 0
	s_add_i32 s74, s31, s2
	s_mov_b32 m0, s74
	ds_read_b128 v[200:203], v157 offset:16384
	ds_read_b128 v[204:207], v157 offset:17408
	ds_read_b128 v[208:211], v157 offset:18432
	ds_read_b128 v[212:215], v157 offset:19456
	ds_read_b128 v[216:219], v157 offset:20480
	ds_read_b128 v[220:223], v157 offset:21504
	ds_read_b128 v[224:227], v157 offset:22528
	ds_read_b128 v[228:231], v157 offset:23552
	global_load_lds_dwordx4 v134, s[68:69]
	s_add_i32 m0, s74, 0x2000
	s_add_u32 s74, s68, 0x80000
	s_addc_u32 s75, s69, 0
	s_add_i32 s76, s40, s2
	global_load_lds_dwordx4 v130, s[68:69]
	s_mov_b32 m0, s76
	v_lshl_add_u64 v[232:233], s[70:71], 0, v[132:133]
	global_load_lds_dwordx4 v134, s[74:75]
	s_add_i32 m0, s76, 0x2000
	s_nop 0
	global_load_lds_dwordx4 v130, s[74:75]
	v_lshl_add_u64 v[192:193], s[70:71], 0, v[136:137]
	s_mov_b32 m0, s25
	s_nop 0
	global_load_lds_dwordx4 v136, s[70:71]
	s_mov_b32 m0, s26
	s_nop 0
	global_load_lds_dwordx4 v132, s[70:71]
	s_waitcnt vmcnt(8) lgkmcnt(0)
	s_setprio 1
	s_barrier
	v_mfma_f32_16x16x32_bf16 v[62:65], v[146:149], v[200:203], v[62:65]
	v_mfma_f32_16x16x32_bf16 v[62:65], v[158:161], v[204:207], v[62:65]
	v_mfma_f32_16x16x32_bf16 v[46:49], v[158:161], v[212:215], v[46:49]
	v_mfma_f32_16x16x32_bf16 v[46:49], v[146:149], v[208:211], v[46:49]
	v_mfma_f32_16x16x32_bf16 v[30:33], v[146:149], v[216:219], v[30:33]
	v_mfma_f32_16x16x32_bf16 v[30:33], v[158:161], v[220:223], v[30:33]
	v_mfma_f32_16x16x32_bf16 v[14:17], v[158:161], v[228:231], v[14:17]
	v_mfma_f32_16x16x32_bf16 v[14:17], v[146:149], v[224:227], v[14:17]
	v_mfma_f32_16x16x32_bf16 v[10:13], v[168:171], v[224:227], v[10:13]
	v_mfma_f32_16x16x32_bf16 v[10:13], v[172:175], v[228:231], v[10:13]
	v_mfma_f32_16x16x32_bf16 v[58:61], v[172:175], v[204:207], v[58:61]
	v_mfma_f32_16x16x32_bf16 v[58:61], v[168:171], v[200:203], v[58:61]
	v_mfma_f32_16x16x32_bf16 v[42:45], v[168:171], v[208:211], v[42:45]
	v_mfma_f32_16x16x32_bf16 v[42:45], v[172:175], v[212:215], v[42:45]
	v_mfma_f32_16x16x32_bf16 v[26:29], v[172:175], v[220:223], v[26:29]
	v_mfma_f32_16x16x32_bf16 v[26:29], v[168:171], v[216:219], v[26:29]
	s_setprio 0
	s_setprio 1
	v_mfma_f32_16x16x32_bf16 v[22:25], v[176:179], v[216:219], v[22:25]
	v_mfma_f32_16x16x32_bf16 v[22:25], v[180:183], v[220:223], v[22:25]
	v_mfma_f32_16x16x32_bf16 v[54:57], v[180:183], v[204:207], v[54:57]
	v_mfma_f32_16x16x32_bf16 v[54:57], v[176:179], v[200:203], v[54:57]
	v_mfma_f32_16x16x32_bf16 v[38:41], v[176:179], v[208:211], v[38:41]
	v_mfma_f32_16x16x32_bf16 v[38:41], v[180:183], v[212:215], v[38:41]
	v_mfma_f32_16x16x32_bf16 v[6:9], v[180:183], v[228:231], v[6:9]
	v_mfma_f32_16x16x32_bf16 v[6:9], v[176:179], v[224:227], v[6:9]
	v_mfma_f32_16x16x32_bf16 v[2:5], v[184:187], v[224:227], v[2:5]
	v_mfma_f32_16x16x32_bf16 v[2:5], v[188:191], v[228:231], v[2:5]
	v_mfma_f32_16x16x32_bf16 v[50:53], v[188:191], v[204:207], v[50:53]
	v_mfma_f32_16x16x32_bf16 v[50:53], v[184:187], v[200:203], v[50:53]
	v_mfma_f32_16x16x32_bf16 v[34:37], v[184:187], v[208:211], v[34:37]
	v_mfma_f32_16x16x32_bf16 v[34:37], v[188:191], v[212:215], v[34:37]
	v_mfma_f32_16x16x32_bf16 v[18:21], v[188:191], v[220:223], v[18:21]
	v_mfma_f32_16x16x32_bf16 v[18:21], v[184:187], v[216:219], v[18:21]
	s_barrier
; #define PG8_STAGE(bufoff, gbase, voff) do { _Pragma("unroll") for (int _i = 0; _i < 2; ++_i) \
;         __builtin_amdgcn_global_load_lds((const unsigned*)((const char*)(gbase) + (voff)[_i]), (PG8_LAS unsigned*)(lds + (bufoff) + ldsw + _i * 8192), 16, 0, 0); } while (0)
; #define PG8_LDA(dst, b, h) do { _Pragma("unroll") for (int m = 0; m < 4; ++m) _Pragma("unroll") for (int k = 0; k < 2; ++k) dst[m][k] = *(const PG8_LAS bf16x8*)(lds + PG8_SA(b, h) + aoff + m * 2048 + k * 1024); } while (0)
; #define PG8_LDB(dst, b, h) do { _Pragma("unroll") for (int n = 0; n < 2; ++n) _Pragma("unroll") for (int k = 0; k < 2; ++k) dst[n][k] = *(const PG8_LAS bf16x8*)(lds + PG8_SB(b, h) + boff + n * 2048 + k * 1024); } while (0)
; #define PG8_MMA(ai, bj, At, Bt) do { __builtin_amdgcn_s_setprio(1); _Pragma("unroll") for (int m = 0; m < 4; ++m) _Pragma("unroll") for (int n = 0; n < 2; ++n) _Pragma("unroll") for (int k = 0; k < 2; ++k) \
;         acc[ai][bj][m][n] = __builtin_amdgcn_mfma_f32_16x16x32_bf16(Bt[n][k], At[m][k], acc[ai][bj][m][n], 0, 0, 0); __builtin_amdgcn_s_setprio(0); } while (0)
; #define PG8_WAIT_V(n) asm volatile("s_waitcnt vmcnt(" #n ")" ::: "memory")
; #define PG8_WAIT_L(n) asm volatile("s_waitcnt lgkmcnt(" #n ")" ::: "memory")
; #define PG8_BAR __builtin_amdgcn_s_barrier()
; #define PG8_SCHED __builtin_amdgcn_sched_barrier(0)
; template <class Epi, class Sched, bool ALIGN_EPI = false, bool SP2 = false>
; __device__ __forceinline__ void gemm_phase(PG8_LAS unsigned char* lds, const Gemm g, const Sched& S, const Epi& E) {
;     ...
;             PG8_LDB(B0, 1, 0); PG8_LDB(B1, 1, 1); PG8_SCHED; PG8_LDA(At, 1, 0); PG8_STAGE(PG8_SA(0, 1), a2 + hstep, voffA);
;             PG8_WAIT_V(8); PG8_WAIT_L(0); PG8_BAR; PG8_MMA(0, 0, At, B0); PG8_MMA(0, 1, At, B1); PG8_BAR; PG8_SCHED;
;             PG8_LDA(At, 1, 1); PG8_STAGE(PG8_SB(1, 0), b3, voffB); PG8_STAGE(PG8_SB(1, 1), b3 + hstep, voffB); PG8_STAGE(PG8_SA(1, 0), a3, voffA);
;             PG8_WAIT_V(8); PG8_WAIT_L(0); PG8_BAR; PG8_MMA(1, 0, At, B0); PG8_MMA(1, 1, At, B1); PG8_BAR; PG8_SCHED;
	s_setprio 0
	s_add_i32 s74, 0, 0x18000
	v_add_u32_e32 v166, s74, v153
	s_add_i32 s75, 0, 0x1c000
	ds_read_b128 v[146:149], v166
	ds_read_b128 v[158:161], v166 offset:1024
	ds_read_b128 v[168:171], v166 offset:2048
	ds_read_b128 v[172:175], v166 offset:3072
	v_add_u32_e32 v166, s75, v153
	ds_read_b128 v[176:179], v166
	ds_read_b128 v[180:183], v166 offset:1024
	ds_read_b128 v[184:187], v166 offset:2048
	ds_read_b128 v[188:191], v166 offset:3072
	s_add_u32 s70, s70, 0x80000
	s_addc_u32 s71, s71, 0
	s_mov_b32 m0, s27
	ds_read_b128 v[200:203], v157 offset:32768
	ds_read_b128 v[204:207], v157 offset:33792
	ds_read_b128 v[208:211], v157 offset:34816
	ds_read_b128 v[212:215], v157 offset:35840
	ds_read_b128 v[216:219], v157 offset:36864
	ds_read_b128 v[220:223], v157 offset:37888
	ds_read_b128 v[224:227], v157 offset:38912
	ds_read_b128 v[228:231], v157 offset:39936
	global_load_lds_dwordx4 v136, s[70:71]
	s_mov_b32 m0, s28
	s_nop 0
	global_load_lds_dwordx4 v132, s[70:71]
	s_waitcnt vmcnt(8) lgkmcnt(0)
	s_setprio 1
	s_barrier
	v_mfma_f32_16x16x32_bf16 v[126:129], v[146:149], v[200:203], v[126:129]
	v_mfma_f32_16x16x32_bf16 v[126:129], v[158:161], v[204:207], v[126:129]
	v_mfma_f32_16x16x32_bf16 v[110:113], v[158:161], v[212:215], v[110:113]
	v_mfma_f32_16x16x32_bf16 v[110:113], v[146:149], v[208:211], v[110:113]
	v_mfma_f32_16x16x32_bf16 v[94:97], v[146:149], v[216:219], v[94:97]
	v_mfma_f32_16x16x32_bf16 v[94:97], v[158:161], v[220:223], v[94:97]
	v_mfma_f32_16x16x32_bf16 v[78:81], v[158:161], v[228:231], v[78:81]
	v_mfma_f32_16x16x32_bf16 v[78:81], v[146:149], v[224:227], v[78:81]
	v_mfma_f32_16x16x32_bf16 v[74:77], v[168:171], v[224:227], v[74:77]
	v_mfma_f32_16x16x32_bf16 v[74:77], v[172:175], v[228:231], v[74:77]
	v_mfma_f32_16x16x32_bf16 v[122:125], v[172:175], v[204:207], v[122:125]
	v_mfma_f32_16x16x32_bf16 v[122:125], v[168:171], v[200:203], v[122:125]
	v_mfma_f32_16x16x32_bf16 v[106:109], v[168:171], v[208:211], v[106:109]
	v_mfma_f32_16x16x32_bf16 v[106:109], v[172:175], v[212:215], v[106:109]
	v_mfma_f32_16x16x32_bf16 v[90:93], v[172:175], v[220:223], v[90:93]
	v_mfma_f32_16x16x32_bf16 v[90:93], v[168:171], v[216:219], v[90:93]
	s_setprio 0
	s_setprio 1
	v_mfma_f32_16x16x32_bf16 v[86:89], v[176:179], v[216:219], v[86:89]
	v_mfma_f32_16x16x32_bf16 v[86:89], v[180:183], v[220:223], v[86:89]
	v_mfma_f32_16x16x32_bf16 v[118:121], v[180:183], v[204:207], v[118:121]
	v_mfma_f32_16x16x32_bf16 v[118:121], v[176:179], v[200:203], v[118:121]
	v_mfma_f32_16x16x32_bf16 v[102:105], v[176:179], v[208:211], v[102:105]
	v_mfma_f32_16x16x32_bf16 v[102:105], v[180:183], v[212:215], v[102:105]
	v_mfma_f32_16x16x32_bf16 v[70:73], v[180:183], v[228:231], v[70:73]
	v_mfma_f32_16x16x32_bf16 v[70:73], v[176:179], v[224:227], v[70:73]
	v_mfma_f32_16x16x32_bf16 v[66:69], v[184:187], v[224:227], v[66:69]
	v_mfma_f32_16x16x32_bf16 v[66:69], v[188:191], v[228:231], v[66:69]
	v_mfma_f32_16x16x32_bf16 v[114:117], v[188:191], v[204:207], v[114:117]
	v_mfma_f32_16x16x32_bf16 v[114:117], v[184:187], v[200:203], v[114:117]
	v_mfma_f32_16x16x32_bf16 v[98:101], v[184:187], v[208:211], v[98:101]
	v_mfma_f32_16x16x32_bf16 v[98:101], v[188:191], v[212:215], v[98:101]
	v_mfma_f32_16x16x32_bf16 v[82:85], v[188:191], v[220:223], v[82:85]
	v_mfma_f32_16x16x32_bf16 v[82:85], v[184:187], v[216:219], v[82:85]
	s_barrier
	s_setprio 0
	s_add_i32 s70, s74, s2
	s_add_u32 s98, s68, s8
	s_addc_u32 s99, s69, s9
	s_mov_b32 m0, s70
	ds_read_b128 v[200:203], v157 offset:49152
	ds_read_b128 v[204:207], v157 offset:50176
	ds_read_b128 v[208:211], v157 offset:51200
	ds_read_b128 v[212:215], v157 offset:52224
	ds_read_b128 v[216:219], v157 offset:53248
	ds_read_b128 v[220:223], v157 offset:54272
	ds_read_b128 v[224:227], v157 offset:55296
	ds_read_b128 v[228:231], v157 offset:56320
	global_load_lds_dwordx4 v134, s[98:99]
	s_add_i32 m0, s70, 0x2000
	s_add_u32 s68, s68, 0x80080
	s_addc_u32 s69, s69, 0
	s_add_i32 s70, s75, s2
	global_load_lds_dwordx4 v130, s[98:99]
	s_mov_b32 m0, s70
	s_nop 0
	global_load_lds_dwordx4 v134, s[68:69]
	s_add_i32 m0, s70, 0x2000
	s_nop 0
	global_load_lds_dwordx4 v130, s[68:69]
	v_lshl_add_u64 v[150:151], v[192:193], 0, s[8:9]
	s_mov_b32 m0, s30
	s_nop 0
	global_load_lds_dwordx4 v[150:151], off
	v_lshl_add_u64 v[150:151], v[232:233], 0, s[8:9]
	s_mov_b32 m0, s33
	s_nop 0
	global_load_lds_dwordx4 v[150:151], off
	s_waitcnt vmcnt(8) lgkmcnt(0)
	s_setprio 1
	s_barrier
	v_mfma_f32_16x16x32_bf16 v[62:65], v[146:149], v[200:203], v[62:65]
	v_mfma_f32_16x16x32_bf16 v[62:65], v[158:161], v[204:207], v[62:65]
	v_mfma_f32_16x16x32_bf16 v[46:49], v[158:161], v[212:215], v[46:49]
	v_mfma_f32_16x16x32_bf16 v[46:49], v[146:149], v[208:211], v[46:49]
	v_mfma_f32_16x16x32_bf16 v[30:33], v[146:149], v[216:219], v[30:33]
	v_mfma_f32_16x16x32_bf16 v[30:33], v[158:161], v[220:223], v[30:33]
	v_mfma_f32_16x16x32_bf16 v[14:17], v[158:161], v[228:231], v[14:17]
	v_mfma_f32_16x16x32_bf16 v[14:17], v[146:149], v[224:227], v[14:17]
	v_mfma_f32_16x16x32_bf16 v[10:13], v[168:171], v[224:227], v[10:13]
	v_mfma_f32_16x16x32_bf16 v[10:13], v[172:175], v[228:231], v[10:13]
	v_mfma_f32_16x16x32_bf16 v[58:61], v[172:175], v[204:207], v[58:61]
	v_mfma_f32_16x16x32_bf16 v[58:61], v[168:171], v[200:203], v[58:61]
	v_mfma_f32_16x16x32_bf16 v[42:45], v[168:171], v[208:211], v[42:45]
	v_mfma_f32_16x16x32_bf16 v[42:45], v[172:175], v[212:215], v[42:45]
	v_mfma_f32_16x16x32_bf16 v[26:29], v[172:175], v[220:223], v[26:29]
	v_mfma_f32_16x16x32_bf16 v[26:29], v[168:171], v[216:219], v[26:29]
	s_setprio 0
	s_setprio 1
	v_mfma_f32_16x16x32_bf16 v[22:25], v[176:179], v[216:219], v[22:25]
	v_mfma_f32_16x16x32_bf16 v[22:25], v[180:183], v[220:223], v[22:25]
	v_mfma_f32_16x16x32_bf16 v[54:57], v[180:183], v[204:207], v[54:57]
	v_mfma_f32_16x16x32_bf16 v[54:57], v[176:179], v[200:203], v[54:57]
	v_mfma_f32_16x16x32_bf16 v[38:41], v[176:179], v[208:211], v[38:41]
	v_mfma_f32_16x16x32_bf16 v[38:41], v[180:183], v[212:215], v[38:41]
	v_mfma_f32_16x16x32_bf16 v[6:9], v[180:183], v[228:231], v[6:9]
	v_mfma_f32_16x16x32_bf16 v[6:9], v[176:179], v[224:227], v[6:9]
	v_mfma_f32_16x16x32_bf16 v[2:5], v[184:187], v[224:227], v[2:5]
	v_mfma_f32_16x16x32_bf16 v[2:5], v[188:191], v[228:231], v[2:5]
	v_mfma_f32_16x16x32_bf16 v[50:53], v[188:191], v[204:207], v[50:53]
	v_mfma_f32_16x16x32_bf16 v[50:53], v[184:187], v[200:203], v[50:53]
	v_mfma_f32_16x16x32_bf16 v[34:37], v[184:187], v[208:211], v[34:37]
	v_mfma_f32_16x16x32_bf16 v[34:37], v[188:191], v[212:215], v[34:37]
	v_mfma_f32_16x16x32_bf16 v[18:21], v[188:191], v[220:223], v[18:21]
	v_mfma_f32_16x16x32_bf16 v[18:21], v[184:187], v[216:219], v[18:21]
	s_barrier
	s_setprio 0
	s_add_i32 s73, s73, 2
	s_add_u32 s66, s66, 0x100
	s_addc_u32 s67, s67, 0
	s_add_u32 s65, s65, 0x100
	s_addc_u32 s72, s72, 0
	s_cmp_gt_u32 s73, 29
	s_cbranch_scc0 .LBB0_1078
	s_and_b64 vcc, exec, s[10:11]
	s_cbranch_vccz .LBB0_1081
	s_barrier

; #define PG8_STAGE(bufoff, gbase, voff) do { _Pragma("unroll") for (int _i = 0; _i < 2; ++_i) \
;         __builtin_amdgcn_global_load_lds((const unsigned*)((const char*)(gbase) + (voff)[_i]), (PG8_LAS unsigned*)(lds + (bufoff) + ldsw + _i * 8192), 16, 0, 0); } while (0)
; #define PG8_LDA(dst, b, h) do { _Pragma("unroll") for (int m = 0; m < 4; ++m) _Pragma("unroll") for (int k = 0; k < 2; ++k) dst[m][k] = *(const PG8_LAS bf16x8*)(lds + PG8_SA(b, h) + aoff + m * 2048 + k * 1024); } while (0)
; #define PG8_LDB(dst, b, h) do { _Pragma("unroll") for (int n = 0; n < 2; ++n) _Pragma("unroll") for (int k = 0; k < 2; ++k) dst[n][k] = *(const PG8_LAS bf16x8*)(lds + PG8_SB(b, h) + boff + n * 2048 + k * 1024); } while (0)
; #define PG8_MMA(ai, bj, At, Bt) do { __builtin_amdgcn_s_setprio(1); _Pragma("unroll") for (int m = 0; m < 4; ++m) _Pragma("unroll") for (int n = 0; n < 2; ++n) _Pragma("unroll") for (int k = 0; k < 2; ++k) \
;         acc[ai][bj][m][n] = __builtin_amdgcn_mfma_f32_16x16x32_bf16(Bt[n][k], At[m][k], acc[ai][bj][m][n], 0, 0, 0); __builtin_amdgcn_s_setprio(0); } while (0)
; #define PG8_WAIT_V(n) asm volatile("s_waitcnt vmcnt(" #n ")" ::: "memory")
; #define PG8_WAIT_L(n) asm volatile("s_waitcnt lgkmcnt(" #n ")" ::: "memory")
; template <class Epi, class Sched, bool ALIGN_EPI = false, bool SP2 = false>
; __device__ __forceinline__ void gemm_phase(PG8_LAS unsigned char* lds, const Gemm g, const Sched& S, const Epi& E) {
;     ...
;             const bool last = (t == nt - 2);
;             const char* a1 = cA + (size_t)(t + 1) * kstep;
;             const char* a2 = last ? nA : cA + (size_t)(t + 2) * kstep; const char* b2 = last ? nB : cB + (size_t)(t + 2) * kstep;
;             const char* a3 = a2 + kstep; const char* b3 = b2 + kstep;
;             if (last && has_next) S.a_ready(nxt);
;             if constexpr (SP2) {
;             PG8_LDB(B0, 0, 0); PG8_LDB(B1, 0, 1); PG8_SCHED; PG8_LDA(At, 0, 0); PG8_STAGE(PG8_SA(1, 1), a1 + hstep, voffA);
;             PG8_WAIT_V(8); PG8_WAIT_L(0); PG8_BAR; PG8_MMA(0, 0, At, B0); PG8_MMA(0, 1, At, B1); PG8_BAR; PG8_SCHED;
;             PG8_LDA(At, 0, 1); PG8_STAGE(PG8_SB(0, 0), b2, voffB); PG8_STAGE(PG8_SB(0, 1), b2 + hstep, voffB); PG8_STAGE(PG8_SA(0, 0), a2, voffA);
;             PG8_WAIT_V(8); PG8_WAIT_L(0); PG8_BAR; PG8_MMA(1, 0, At, B0); PG8_MMA(1, 1, At, B1); PG8_BAR; PG8_SCHED;
.LBB0_1203:
	ds_read_b128 v[146:149], v171
	ds_read_b128 v[176:179], v171 offset:1024
	ds_read_b128 v[180:183], v171 offset:2048
	ds_read_b128 v[184:187], v171 offset:3072
	ds_read_b128 v[188:191], v172
	ds_read_b128 v[200:203], v172 offset:1024
	ds_read_b128 v[204:207], v172 offset:2048
	ds_read_b128 v[208:211], v172 offset:3072
	s_add_u32 s63, s64, 0xfff00080
	s_addc_u32 s66, s65, -1
	s_cmp_eq_u32 s61, 60
	s_cselect_b32 s69, s34, s66
	s_cselect_b32 s68, s35, s63
	s_cselect_b32 s67, s40, s55
	s_cselect_b32 s66, s41, s53
	s_add_i32 m0, s4, 0xc000
	ds_read_b128 v[212:215], v173
	ds_read_b128 v[216:219], v173 offset:1024
	ds_read_b128 v[220:223], v173 offset:2048
	ds_read_b128 v[224:227], v173 offset:3072
	ds_read_b128 v[228:231], v173 offset:4096
	ds_read_b128 v[240:243], v173 offset:5120
	ds_read_b128 v[244:247], v173 offset:6144
	ds_read_b128 v[248:251], v173 offset:7168
	global_load_lds_dwordx4 v138, s[64:65]
	s_add_i32 m0, s4, 0xe000
	s_nop 0
	global_load_lds_dwordx4 v140, s[64:65]
	s_waitcnt vmcnt(8) lgkmcnt(0)
	s_setprio 1
	s_barrier
	v_mfma_f32_16x16x32_bf16 v[126:129], v[146:149], v[212:215], v[126:129]
	v_mfma_f32_16x16x32_bf16 v[126:129], v[176:179], v[216:219], v[126:129]
	v_mfma_f32_16x16x32_bf16 v[110:113], v[176:179], v[224:227], v[110:113]
	v_mfma_f32_16x16x32_bf16 v[110:113], v[146:149], v[220:223], v[110:113]
	v_mfma_f32_16x16x32_bf16 v[94:97], v[146:149], v[228:231], v[94:97]
	v_mfma_f32_16x16x32_bf16 v[94:97], v[176:179], v[240:243], v[94:97]
	v_mfma_f32_16x16x32_bf16 v[78:81], v[176:179], v[248:251], v[78:81]
	v_mfma_f32_16x16x32_bf16 v[78:81], v[146:149], v[244:247], v[78:81]
	v_mfma_f32_16x16x32_bf16 v[74:77], v[180:183], v[244:247], v[74:77]
	v_mfma_f32_16x16x32_bf16 v[74:77], v[184:187], v[248:251], v[74:77]
	v_mfma_f32_16x16x32_bf16 v[122:125], v[184:187], v[216:219], v[122:125]
	v_mfma_f32_16x16x32_bf16 v[122:125], v[180:183], v[212:215], v[122:125]
	v_mfma_f32_16x16x32_bf16 v[106:109], v[180:183], v[220:223], v[106:109]
	v_mfma_f32_16x16x32_bf16 v[106:109], v[184:187], v[224:227], v[106:109]
	v_mfma_f32_16x16x32_bf16 v[90:93], v[184:187], v[240:243], v[90:93]
	v_mfma_f32_16x16x32_bf16 v[90:93], v[180:183], v[228:231], v[90:93]
	s_setprio 0
	s_setprio 1
	v_mfma_f32_16x16x32_bf16 v[86:89], v[188:191], v[228:231], v[86:89]
	v_mfma_f32_16x16x32_bf16 v[86:89], v[200:203], v[240:243], v[86:89]
	v_mfma_f32_16x16x32_bf16 v[118:121], v[200:203], v[216:219], v[118:121]
	v_mfma_f32_16x16x32_bf16 v[118:121], v[188:191], v[212:215], v[118:121]
	v_mfma_f32_16x16x32_bf16 v[102:105], v[188:191], v[220:223], v[102:105]
	v_mfma_f32_16x16x32_bf16 v[102:105], v[200:203], v[224:227], v[102:105]
	v_mfma_f32_16x16x32_bf16 v[70:73], v[200:203], v[248:251], v[70:73]
	v_mfma_f32_16x16x32_bf16 v[70:73], v[188:191], v[244:247], v[70:73]
	v_mfma_f32_16x16x32_bf16 v[66:69], v[204:207], v[244:247], v[66:69]
	v_mfma_f32_16x16x32_bf16 v[66:69], v[208:211], v[248:251], v[66:69]
	v_mfma_f32_16x16x32_bf16 v[114:117], v[208:211], v[216:219], v[114:117]
	v_mfma_f32_16x16x32_bf16 v[114:117], v[204:207], v[212:215], v[114:117]
	v_mfma_f32_16x16x32_bf16 v[98:101], v[204:207], v[220:223], v[98:101]
	v_mfma_f32_16x16x32_bf16 v[98:101], v[208:211], v[224:227], v[98:101]
	v_mfma_f32_16x16x32_bf16 v[82:85], v[208:211], v[240:243], v[82:85]
	v_mfma_f32_16x16x32_bf16 v[82:85], v[204:207], v[228:231], v[82:85]
	s_barrier
	s_setprio 0
	s_add_i32 s63, s31, s2
	s_mov_b32 m0, s63
	ds_read_b128 v[212:215], v173 offset:16384
	ds_read_b128 v[216:219], v173 offset:17408
	ds_read_b128 v[220:223], v173 offset:18432
	ds_read_b128 v[224:227], v173 offset:19456
	ds_read_b128 v[228:231], v173 offset:20480
	ds_read_b128 v[240:243], v173 offset:21504
	ds_read_b128 v[244:247], v173 offset:22528
	ds_read_b128 v[248:251], v173 offset:23552
	global_load_lds_dwordx4 v132, s[66:67]
	s_add_i32 m0, s63, 0x2000
	s_add_u32 s70, s66, 0x100000
	s_addc_u32 s71, s67, 0
	s_add_i32 s63, s39, s2
	global_load_lds_dwordx4 v136, s[66:67]
	s_mov_b32 m0, s63
	v_lshl_add_u64 v[252:253], s[68:69], 0, v[134:135]
	global_load_lds_dwordx4 v132, s[70:71]
	s_add_i32 m0, s63, 0x2000
	s_nop 0
	global_load_lds_dwordx4 v136, s[70:71]
	v_lshl_add_u64 v[232:233], s[68:69], 0, v[130:131]
	s_mov_b32 m0, s4
	s_nop 0
	global_load_lds_dwordx4 v130, s[68:69]
	s_mov_b32 m0, s5
	s_nop 0
	global_load_lds_dwordx4 v134, s[68:69]
	s_waitcnt vmcnt(8) lgkmcnt(0)
	s_setprio 1
	s_barrier
	v_mfma_f32_16x16x32_bf16 v[62:65], v[146:149], v[212:215], v[62:65]
	v_mfma_f32_16x16x32_bf16 v[62:65], v[176:179], v[216:219], v[62:65]
	v_mfma_f32_16x16x32_bf16 v[46:49], v[176:179], v[224:227], v[46:49]
	v_mfma_f32_16x16x32_bf16 v[46:49], v[146:149], v[220:223], v[46:49]
	v_mfma_f32_16x16x32_bf16 v[30:33], v[146:149], v[228:231], v[30:33]
	v_mfma_f32_16x16x32_bf16 v[30:33], v[176:179], v[240:243], v[30:33]
	v_mfma_f32_16x16x32_bf16 v[14:17], v[176:179], v[248:251], v[14:17]
	v_mfma_f32_16x16x32_bf16 v[14:17], v[146:149], v[244:247], v[14:17]
	v_mfma_f32_16x16x32_bf16 v[10:13], v[180:183], v[244:247], v[10:13]
	v_mfma_f32_16x16x32_bf16 v[10:13], v[184:187], v[248:251], v[10:13]
	v_mfma_f32_16x16x32_bf16 v[58:61], v[184:187], v[216:219], v[58:61]
	v_mfma_f32_16x16x32_bf16 v[58:61], v[180:183], v[212:215], v[58:61]
	v_mfma_f32_16x16x32_bf16 v[42:45], v[180:183], v[220:223], v[42:45]
	v_mfma_f32_16x16x32_bf16 v[42:45], v[184:187], v[224:227], v[42:45]
	v_mfma_f32_16x16x32_bf16 v[26:29], v[184:187], v[240:243], v[26:29]
	v_mfma_f32_16x16x32_bf16 v[26:29], v[180:183], v[228:231], v[26:29]
	s_setprio 0
	s_setprio 1
	v_mfma_f32_16x16x32_bf16 v[22:25], v[188:191], v[228:231], v[22:25]
	v_mfma_f32_16x16x32_bf16 v[22:25], v[200:203], v[240:243], v[22:25]
	v_mfma_f32_16x16x32_bf16 v[54:57], v[200:203], v[216:219], v[54:57]
	v_mfma_f32_16x16x32_bf16 v[54:57], v[188:191], v[212:215], v[54:57]
	v_mfma_f32_16x16x32_bf16 v[38:41], v[188:191], v[220:223], v[38:41]
	v_mfma_f32_16x16x32_bf16 v[38:41], v[200:203], v[224:227], v[38:41]
	v_mfma_f32_16x16x32_bf16 v[6:9], v[200:203], v[248:251], v[6:9]
	v_mfma_f32_16x16x32_bf16 v[6:9], v[188:191], v[244:247], v[6:9]
	v_mfma_f32_16x16x32_bf16 v[2:5], v[204:207], v[244:247], v[2:5]
	v_mfma_f32_16x16x32_bf16 v[2:5], v[208:211], v[248:251], v[2:5]
	v_mfma_f32_16x16x32_bf16 v[50:53], v[208:211], v[216:219], v[50:53]
	v_mfma_f32_16x16x32_bf16 v[50:53], v[204:207], v[212:215], v[50:53]
	v_mfma_f32_16x16x32_bf16 v[34:37], v[204:207], v[220:223], v[34:37]
	v_mfma_f32_16x16x32_bf16 v[34:37], v[208:211], v[224:227], v[34:37]
	v_mfma_f32_16x16x32_bf16 v[18:21], v[208:211], v[240:243], v[18:21]
	v_mfma_f32_16x16x32_bf16 v[18:21], v[204:207], v[228:231], v[18:21]
	s_barrier
; #define PG8_STAGE(bufoff, gbase, voff) do { _Pragma("unroll") for (int _i = 0; _i < 2; ++_i) \
;         __builtin_amdgcn_global_load_lds((const unsigned*)((const char*)(gbase) + (voff)[_i]), (PG8_LAS unsigned*)(lds + (bufoff) + ldsw + _i * 8192), 16, 0, 0); } while (0)
; #define PG8_LDA(dst, b, h) do { _Pragma("unroll") for (int m = 0; m < 4; ++m) _Pragma("unroll") for (int k = 0; k < 2; ++k) dst[m][k] = *(const PG8_LAS bf16x8*)(lds + PG8_SA(b, h) + aoff + m * 2048 + k * 1024); } while (0)
; #define PG8_LDB(dst, b, h) do { _Pragma("unroll") for (int n = 0; n < 2; ++n) _Pragma("unroll") for (int k = 0; k < 2; ++k) dst[n][k] = *(const PG8_LAS bf16x8*)(lds + PG8_SB(b, h) + boff + n * 2048 + k * 1024); } while (0)
; #define PG8_MMA(ai, bj, At, Bt) do { __builtin_amdgcn_s_setprio(1); _Pragma("unroll") for (int m = 0; m < 4; ++m) _Pragma("unroll") for (int n = 0; n < 2; ++n) _Pragma("unroll") for (int k = 0; k < 2; ++k) \
;         acc[ai][bj][m][n] = __builtin_amdgcn_mfma_f32_16x16x32_bf16(Bt[n][k], At[m][k], acc[ai][bj][m][n], 0, 0, 0); __builtin_amdgcn_s_setprio(0); } while (0)
; #define PG8_WAIT_V(n) asm volatile("s_waitcnt vmcnt(" #n ")" ::: "memory")
; #define PG8_WAIT_L(n) asm volatile("s_waitcnt lgkmcnt(" #n ")" ::: "memory")
; #define PG8_BAR __builtin_amdgcn_s_barrier()
; #define PG8_SCHED __builtin_amdgcn_sched_barrier(0)
; template <class Epi, class Sched, bool ALIGN_EPI = false, bool SP2 = false>
; __device__ __forceinline__ void gemm_phase(PG8_LAS unsigned char* lds, const Gemm g, const Sched& S, const Epi& E) {
;     ...
;             PG8_LDB(B0, 1, 0); PG8_LDB(B1, 1, 1); PG8_SCHED; PG8_LDA(At, 1, 0); PG8_STAGE(PG8_SA(0, 1), a2 + hstep, voffA);
;             PG8_WAIT_V(8); PG8_WAIT_L(0); PG8_BAR; PG8_MMA(0, 0, At, B0); PG8_MMA(0, 1, At, B1); PG8_BAR; PG8_SCHED;
;             PG8_LDA(At, 1, 1); PG8_STAGE(PG8_SB(1, 0), b3, voffB); PG8_STAGE(PG8_SB(1, 1), b3 + hstep, voffB); PG8_STAGE(PG8_SA(1, 0), a3, voffA);
;             PG8_WAIT_V(8); PG8_WAIT_L(0); PG8_BAR; PG8_MMA(1, 0, At, B0); PG8_MMA(1, 1, At, B1); PG8_BAR; PG8_SCHED;
	s_setprio 0
	s_add_i32 s63, 0, 0x18000
	v_add_u32_e32 v175, s63, v153
	s_add_i32 s70, 0, 0x1c000
	ds_read_b128 v[146:149], v175
	ds_read_b128 v[176:179], v175 offset:1024
	ds_read_b128 v[180:183], v175 offset:2048
	ds_read_b128 v[184:187], v175 offset:3072
	v_add_u32_e32 v175, s70, v153
	ds_read_b128 v[188:191], v175
	ds_read_b128 v[200:203], v175 offset:1024
	ds_read_b128 v[204:207], v175 offset:2048
	ds_read_b128 v[208:211], v175 offset:3072
	s_add_u32 s68, s68, 0x100000
	s_addc_u32 s69, s69, 0
	s_mov_b32 m0, s16
	ds_read_b128 v[212:215], v173 offset:32768
	ds_read_b128 v[216:219], v173 offset:33792
	ds_read_b128 v[220:223], v173 offset:34816
	ds_read_b128 v[224:227], v173 offset:35840
	ds_read_b128 v[228:231], v173 offset:36864
	ds_read_b128 v[240:243], v173 offset:37888
	ds_read_b128 v[244:247], v173 offset:38912
	ds_read_b128 v[248:251], v173 offset:39936
	global_load_lds_dwordx4 v130, s[68:69]
	s_mov_b32 m0, s17
	s_nop 0
	global_load_lds_dwordx4 v134, s[68:69]
	s_waitcnt vmcnt(8) lgkmcnt(0)
	s_setprio 1
	s_barrier
	v_mfma_f32_16x16x32_bf16 v[126:129], v[146:149], v[212:215], v[126:129]
	v_mfma_f32_16x16x32_bf16 v[126:129], v[176:179], v[216:219], v[126:129]
	v_mfma_f32_16x16x32_bf16 v[110:113], v[176:179], v[224:227], v[110:113]
	v_mfma_f32_16x16x32_bf16 v[110:113], v[146:149], v[220:223], v[110:113]
	v_mfma_f32_16x16x32_bf16 v[94:97], v[146:149], v[228:231], v[94:97]
	v_mfma_f32_16x16x32_bf16 v[94:97], v[176:179], v[240:243], v[94:97]
	v_mfma_f32_16x16x32_bf16 v[78:81], v[176:179], v[248:251], v[78:81]
	v_mfma_f32_16x16x32_bf16 v[78:81], v[146:149], v[244:247], v[78:81]
	v_mfma_f32_16x16x32_bf16 v[74:77], v[180:183], v[244:247], v[74:77]
	v_mfma_f32_16x16x32_bf16 v[74:77], v[184:187], v[248:251], v[74:77]
	v_mfma_f32_16x16x32_bf16 v[122:125], v[184:187], v[216:219], v[122:125]
	v_mfma_f32_16x16x32_bf16 v[122:125], v[180:183], v[212:215], v[122:125]
	v_mfma_f32_16x16x32_bf16 v[106:109], v[180:183], v[220:223], v[106:109]
	v_mfma_f32_16x16x32_bf16 v[106:109], v[184:187], v[224:227], v[106:109]
	v_mfma_f32_16x16x32_bf16 v[90:93], v[184:187], v[240:243], v[90:93]
	v_mfma_f32_16x16x32_bf16 v[90:93], v[180:183], v[228:231], v[90:93]
	s_setprio 0
	s_setprio 1
	v_mfma_f32_16x16x32_bf16 v[86:89], v[188:191], v[228:231], v[86:89]
	v_mfma_f32_16x16x32_bf16 v[86:89], v[200:203], v[240:243], v[86:89]
	v_mfma_f32_16x16x32_bf16 v[118:121], v[200:203], v[216:219], v[118:121]
	v_mfma_f32_16x16x32_bf16 v[118:121], v[188:191], v[212:215], v[118:121]
	v_mfma_f32_16x16x32_bf16 v[102:105], v[188:191], v[220:223], v[102:105]
	v_mfma_f32_16x16x32_bf16 v[102:105], v[200:203], v[224:227], v[102:105]
	v_mfma_f32_16x16x32_bf16 v[70:73], v[200:203], v[248:251], v[70:73]
	v_mfma_f32_16x16x32_bf16 v[70:73], v[188:191], v[244:247], v[70:73]
	v_mfma_f32_16x16x32_bf16 v[66:69], v[204:207], v[244:247], v[66:69]
	v_mfma_f32_16x16x32_bf16 v[66:69], v[208:211], v[248:251], v[66:69]
	v_mfma_f32_16x16x32_bf16 v[114:117], v[208:211], v[216:219], v[114:117]
	v_mfma_f32_16x16x32_bf16 v[114:117], v[204:207], v[212:215], v[114:117]
	v_mfma_f32_16x16x32_bf16 v[98:101], v[204:207], v[220:223], v[98:101]
	v_mfma_f32_16x16x32_bf16 v[98:101], v[208:211], v[224:227], v[98:101]
	v_mfma_f32_16x16x32_bf16 v[82:85], v[208:211], v[240:243], v[82:85]
	v_mfma_f32_16x16x32_bf16 v[82:85], v[204:207], v[228:231], v[82:85]
	s_barrier
	s_setprio 0
	s_add_i32 s63, s63, s2
	s_add_u32 s98, s66, s44
	s_addc_u32 s99, s67, s45
	s_mov_b32 m0, s63
	ds_read_b128 v[212:215], v173 offset:49152
	ds_read_b128 v[216:219], v173 offset:50176
	ds_read_b128 v[220:223], v173 offset:51200
	ds_read_b128 v[224:227], v173 offset:52224
	ds_read_b128 v[228:231], v173 offset:53248
	ds_read_b128 v[240:243], v173 offset:54272
	ds_read_b128 v[244:247], v173 offset:55296
	ds_read_b128 v[248:251], v173 offset:56320
	global_load_lds_dwordx4 v132, s[98:99]
	s_add_i32 m0, s63, 0x2000
	s_add_u32 s66, s66, 0x100080
	s_addc_u32 s67, s67, 0
	s_add_i32 s63, s70, s2
	global_load_lds_dwordx4 v136, s[98:99]
	s_mov_b32 m0, s63
	s_nop 0
	global_load_lds_dwordx4 v132, s[66:67]
	s_add_i32 m0, s63, 0x2000
	s_nop 0
	global_load_lds_dwordx4 v136, s[66:67]
	v_lshl_add_u64 v[150:151], v[232:233], 0, s[44:45]
	s_mov_b32 m0, s26
	s_nop 0
	global_load_lds_dwordx4 v[150:151], off
	v_lshl_add_u64 v[150:151], v[252:253], 0, s[44:45]
	s_mov_b32 m0, s27
	s_nop 0
	global_load_lds_dwordx4 v[150:151], off
	s_waitcnt vmcnt(8) lgkmcnt(0)
	s_setprio 1
	s_barrier
	v_mfma_f32_16x16x32_bf16 v[62:65], v[146:149], v[212:215], v[62:65]
	v_mfma_f32_16x16x32_bf16 v[62:65], v[176:179], v[216:219], v[62:65]
	v_mfma_f32_16x16x32_bf16 v[46:49], v[176:179], v[224:227], v[46:49]
	v_mfma_f32_16x16x32_bf16 v[46:49], v[146:149], v[220:223], v[46:49]
	v_mfma_f32_16x16x32_bf16 v[30:33], v[146:149], v[228:231], v[30:33]
	v_mfma_f32_16x16x32_bf16 v[30:33], v[176:179], v[240:243], v[30:33]
	v_mfma_f32_16x16x32_bf16 v[14:17], v[176:179], v[248:251], v[14:17]
	v_mfma_f32_16x16x32_bf16 v[14:17], v[146:149], v[244:247], v[14:17]
	v_mfma_f32_16x16x32_bf16 v[10:13], v[180:183], v[244:247], v[10:13]
	v_mfma_f32_16x16x32_bf16 v[10:13], v[184:187], v[248:251], v[10:13]
	v_mfma_f32_16x16x32_bf16 v[58:61], v[184:187], v[216:219], v[58:61]
	v_mfma_f32_16x16x32_bf16 v[58:61], v[180:183], v[212:215], v[58:61]
	v_mfma_f32_16x16x32_bf16 v[42:45], v[180:183], v[220:223], v[42:45]
	v_mfma_f32_16x16x32_bf16 v[42:45], v[184:187], v[224:227], v[42:45]
	v_mfma_f32_16x16x32_bf16 v[26:29], v[184:187], v[240:243], v[26:29]
	v_mfma_f32_16x16x32_bf16 v[26:29], v[180:183], v[228:231], v[26:29]
	s_setprio 0
	s_setprio 1
	v_mfma_f32_16x16x32_bf16 v[22:25], v[188:191], v[228:231], v[22:25]
	v_mfma_f32_16x16x32_bf16 v[22:25], v[200:203], v[240:243], v[22:25]
	v_mfma_f32_16x16x32_bf16 v[54:57], v[200:203], v[216:219], v[54:57]
	v_mfma_f32_16x16x32_bf16 v[54:57], v[188:191], v[212:215], v[54:57]
	v_mfma_f32_16x16x32_bf16 v[38:41], v[188:191], v[220:223], v[38:41]
	v_mfma_f32_16x16x32_bf16 v[38:41], v[200:203], v[224:227], v[38:41]
	v_mfma_f32_16x16x32_bf16 v[6:9], v[200:203], v[248:251], v[6:9]
	v_mfma_f32_16x16x32_bf16 v[6:9], v[188:191], v[244:247], v[6:9]
	v_mfma_f32_16x16x32_bf16 v[2:5], v[204:207], v[244:247], v[2:5]
	v_mfma_f32_16x16x32_bf16 v[2:5], v[208:211], v[248:251], v[2:5]
	v_mfma_f32_16x16x32_bf16 v[50:53], v[208:211], v[216:219], v[50:53]
	v_mfma_f32_16x16x32_bf16 v[50:53], v[204:207], v[212:215], v[50:53]
	v_mfma_f32_16x16x32_bf16 v[34:37], v[204:207], v[220:223], v[34:37]
	v_mfma_f32_16x16x32_bf16 v[34:37], v[208:211], v[224:227], v[34:37]
	v_mfma_f32_16x16x32_bf16 v[18:21], v[208:211], v[240:243], v[18:21]
	v_mfma_f32_16x16x32_bf16 v[18:21], v[204:207], v[228:231], v[18:21]
	s_barrier
	s_setprio 0
	s_add_i32 s61, s61, 2
	s_add_u32 s64, s64, 0x100
	s_addc_u32 s65, s65, 0
	s_add_u32 s53, s53, 0x100
	s_addc_u32 s55, s55, 0
	s_cmp_gt_u32 s61, 61
	s_cbranch_scc0 .LBB0_1203
	s_and_b64 vcc, exec, s[46:47]
	s_cbranch_vccz .LBB0_1206
	s_barrier

; #define PG8_STAGE(bufoff, gbase, voff) do { _Pragma("unroll") for (int _i = 0; _i < 2; ++_i) \
;         __builtin_amdgcn_global_load_lds((const unsigned*)((const char*)(gbase) + (voff)[_i]), (PG8_LAS unsigned*)(lds + (bufoff) + ldsw + _i * 8192), 16, 0, 0); } while (0)
; #define PG8_LDA(dst, b, h) do { _Pragma("unroll") for (int m = 0; m < 4; ++m) _Pragma("unroll") for (int k = 0; k < 2; ++k) dst[m][k] = *(const PG8_LAS bf16x8*)(lds + PG8_SA(b, h) + aoff + m * 2048 + k * 1024); } while (0)
; #define PG8_LDB(dst, b, h) do { _Pragma("unroll") for (int n = 0; n < 2; ++n) _Pragma("unroll") for (int k = 0; k < 2; ++k) dst[n][k] = *(const PG8_LAS bf16x8*)(lds + PG8_SB(b, h) + boff + n * 2048 + k * 1024); } while (0)
; #define PG8_MMA(ai, bj, At, Bt) do { __builtin_amdgcn_s_setprio(1); _Pragma("unroll") for (int m = 0; m < 4; ++m) _Pragma("unroll") for (int n = 0; n < 2; ++n) _Pragma("unroll") for (int k = 0; k < 2; ++k) \
;         acc[ai][bj][m][n] = __builtin_amdgcn_mfma_f32_16x16x32_bf16(Bt[n][k], At[m][k], acc[ai][bj][m][n], 0, 0, 0); __builtin_amdgcn_s_setprio(0); } while (0)
; #define PG8_WAIT_V(n) asm volatile("s_waitcnt vmcnt(" #n ")" ::: "memory")
; #define PG8_WAIT_L(n) asm volatile("s_waitcnt lgkmcnt(" #n ")" ::: "memory")
; template <class Epi, class Sched, bool ALIGN_EPI = false, bool SP2 = false>
; __device__ __forceinline__ void gemm_phase(PG8_LAS unsigned char* lds, const Gemm g, const Sched& S, const Epi& E) {
;     ...
;             const bool last = (t == nt - 2);
;             const char* a1 = cA + (size_t)(t + 1) * kstep;
;             const char* a2 = last ? nA : cA + (size_t)(t + 2) * kstep; const char* b2 = last ? nB : cB + (size_t)(t + 2) * kstep;
;             const char* a3 = a2 + kstep; const char* b3 = b2 + kstep;
;             if (last && has_next) S.a_ready(nxt);
;             if constexpr (SP2) {
;             PG8_LDB(B0, 0, 0); PG8_LDB(B1, 0, 1); PG8_SCHED; PG8_LDA(At, 0, 0); PG8_STAGE(PG8_SA(1, 1), a1 + hstep, voffA);
;             PG8_WAIT_V(8); PG8_WAIT_L(0); PG8_BAR; PG8_MMA(0, 0, At, B0); PG8_MMA(0, 1, At, B1); PG8_BAR; PG8_SCHED;
;             PG8_LDA(At, 0, 1); PG8_STAGE(PG8_SB(0, 0), b2, voffB); PG8_STAGE(PG8_SB(0, 1), b2 + hstep, voffB); PG8_STAGE(PG8_SA(0, 0), a2, voffA);
;             PG8_WAIT_V(8); PG8_WAIT_L(0); PG8_BAR; PG8_MMA(1, 0, At, B0); PG8_MMA(1, 1, At, B1); PG8_BAR; PG8_SCHED;
.LBB0_1230:
	ds_read_b128 v[146:149], v140
	ds_read_b128 v[150:153], v140 offset:1024
	ds_read_b128 v[154:157], v140 offset:2048
	ds_read_b128 v[158:161], v140 offset:3072
	ds_read_b128 v[168:171], v141
	ds_read_b128 v[172:175], v141 offset:1024
	ds_read_b128 v[176:179], v141 offset:2048
	ds_read_b128 v[180:183], v141 offset:3072
	s_add_u32 s50, s46, 0x100
	s_addc_u32 s51, s47, 0
	s_cmp_lg_u32 s30, 12
	s_cselect_b32 s52, s50, 0
	s_cselect_b32 s53, s51, 0
	s_add_u32 s54, s10, s52
	s_addc_u32 s55, s11, s53
	s_add_u32 s52, s8, s52
	s_addc_u32 s53, s9, s53
	s_mov_b32 m0, s33
	v_lshl_add_u64 v[162:163], v[134:135], 0, s[46:47]
	ds_read_b128 v[184:187], v142
	ds_read_b128 v[188:191], v142 offset:1024
	ds_read_b128 v[200:203], v142 offset:2048
	ds_read_b128 v[204:207], v142 offset:3072
	ds_read_b128 v[208:211], v142 offset:4096
	ds_read_b128 v[212:215], v142 offset:5120
	ds_read_b128 v[216:219], v142 offset:6144
	ds_read_b128 v[220:223], v142 offset:7168
	global_load_lds_dwordx4 v[162:163], off
	v_lshl_add_u64 v[162:163], v[136:137], 0, s[46:47]
	s_mov_b32 m0, s34
	s_nop 0
	global_load_lds_dwordx4 v[162:163], off
	s_waitcnt vmcnt(8) lgkmcnt(0)
	s_setprio 1
	s_barrier
	v_mfma_f32_16x16x32_bf16 v[126:129], v[146:149], v[184:187], v[126:129]
	v_mfma_f32_16x16x32_bf16 v[126:129], v[150:153], v[188:191], v[126:129]
	v_mfma_f32_16x16x32_bf16 v[118:121], v[150:153], v[204:207], v[118:121]
	v_mfma_f32_16x16x32_bf16 v[118:121], v[146:149], v[200:203], v[118:121]
	v_mfma_f32_16x16x32_bf16 v[106:109], v[146:149], v[208:211], v[106:109]
	v_mfma_f32_16x16x32_bf16 v[106:109], v[150:153], v[212:215], v[106:109]
	v_mfma_f32_16x16x32_bf16 v[90:93], v[150:153], v[220:223], v[90:93]
	v_mfma_f32_16x16x32_bf16 v[90:93], v[146:149], v[216:219], v[90:93]
	v_mfma_f32_16x16x32_bf16 v[82:85], v[154:157], v[216:219], v[82:85]
	v_mfma_f32_16x16x32_bf16 v[82:85], v[158:161], v[220:223], v[82:85]
	v_mfma_f32_16x16x32_bf16 v[122:125], v[158:161], v[188:191], v[122:125]
	v_mfma_f32_16x16x32_bf16 v[122:125], v[154:157], v[184:187], v[122:125]
	v_mfma_f32_16x16x32_bf16 v[114:117], v[154:157], v[200:203], v[114:117]
	v_mfma_f32_16x16x32_bf16 v[114:117], v[158:161], v[204:207], v[114:117]
	v_mfma_f32_16x16x32_bf16 v[98:101], v[158:161], v[212:215], v[98:101]
	v_mfma_f32_16x16x32_bf16 v[98:101], v[154:157], v[208:211], v[98:101]
	s_setprio 0
	s_setprio 1
	v_mfma_f32_16x16x32_bf16 v[78:81], v[168:171], v[208:211], v[78:81]
	v_mfma_f32_16x16x32_bf16 v[78:81], v[172:175], v[212:215], v[78:81]
	v_mfma_f32_16x16x32_bf16 v[110:113], v[172:175], v[188:191], v[110:113]
	v_mfma_f32_16x16x32_bf16 v[110:113], v[168:171], v[184:187], v[110:113]
	v_mfma_f32_16x16x32_bf16 v[94:97], v[168:171], v[200:203], v[94:97]
	v_mfma_f32_16x16x32_bf16 v[94:97], v[172:175], v[204:207], v[94:97]
	v_mfma_f32_16x16x32_bf16 v[70:73], v[172:175], v[220:223], v[70:73]
	v_mfma_f32_16x16x32_bf16 v[70:73], v[168:171], v[216:219], v[70:73]
	v_mfma_f32_16x16x32_bf16 v[66:69], v[176:179], v[216:219], v[66:69]
	v_mfma_f32_16x16x32_bf16 v[66:69], v[180:183], v[220:223], v[66:69]
	v_mfma_f32_16x16x32_bf16 v[102:105], v[180:183], v[188:191], v[102:105]
	v_mfma_f32_16x16x32_bf16 v[102:105], v[176:179], v[184:187], v[102:105]
	v_mfma_f32_16x16x32_bf16 v[86:89], v[176:179], v[200:203], v[86:89]
	v_mfma_f32_16x16x32_bf16 v[86:89], v[180:183], v[204:207], v[86:89]
	v_mfma_f32_16x16x32_bf16 v[74:77], v[180:183], v[212:215], v[74:77]
	v_mfma_f32_16x16x32_bf16 v[74:77], v[176:179], v[208:211], v[74:77]
	s_barrier
	s_setprio 0
	s_mov_b32 m0, s35
	v_lshl_add_u64 v[162:163], s[52:53], 0, v[130:131]
	s_add_u32 s46, s52, 0x100000
	ds_read_b128 v[184:187], v142 offset:16384
	ds_read_b128 v[188:191], v142 offset:17408
	ds_read_b128 v[200:203], v142 offset:18432
	ds_read_b128 v[204:207], v142 offset:19456
	ds_read_b128 v[208:211], v142 offset:20480
	ds_read_b128 v[212:215], v142 offset:21504
	ds_read_b128 v[216:219], v142 offset:22528
	ds_read_b128 v[220:223], v142 offset:23552
	global_load_lds_dwordx4 v[162:163], off
	v_lshl_add_u64 v[192:193], s[52:53], 0, v[132:133]
	s_mov_b32 m0, s39
	s_addc_u32 s47, s53, 0
	global_load_lds_dwordx4 v[192:193], off
	v_lshl_add_u64 v[194:195], s[46:47], 0, v[130:131]
	s_mov_b32 m0, s40
	v_lshl_add_u64 v[224:225], s[54:55], 0, v[132:133]
	global_load_lds_dwordx4 v[194:195], off
	v_lshl_add_u64 v[194:195], s[46:47], 0, v[132:133]
	s_mov_b32 m0, s41
	s_nop 0
	global_load_lds_dwordx4 v[194:195], off
	v_lshl_add_u64 v[194:195], s[54:55], 0, v[130:131]
	s_mov_b32 m0, s7
	s_nop 0
	global_load_lds_dwordx4 v[194:195], off
	s_mov_b32 m0, s16
	s_nop 0
	global_load_lds_dwordx4 v[224:225], off
	s_waitcnt vmcnt(8) lgkmcnt(0)
	s_setprio 1
	s_barrier
; #define PG8_STAGE(bufoff, gbase, voff) do { _Pragma("unroll") for (int _i = 0; _i < 2; ++_i) \
;         __builtin_amdgcn_global_load_lds((const unsigned*)((const char*)(gbase) + (voff)[_i]), (PG8_LAS unsigned*)(lds + (bufoff) + ldsw + _i * 8192), 16, 0, 0); } while (0)
; #define PG8_LDA(dst, b, h) do { _Pragma("unroll") for (int m = 0; m < 4; ++m) _Pragma("unroll") for (int k = 0; k < 2; ++k) dst[m][k] = *(const PG8_LAS bf16x8*)(lds + PG8_SA(b, h) + aoff + m * 2048 + k * 1024); } while (0)
; #define PG8_LDB(dst, b, h) do { _Pragma("unroll") for (int n = 0; n < 2; ++n) _Pragma("unroll") for (int k = 0; k < 2; ++k) dst[n][k] = *(const PG8_LAS bf16x8*)(lds + PG8_SB(b, h) + boff + n * 2048 + k * 1024); } while (0)
; #define PG8_MMA(ai, bj, At, Bt) do { __builtin_amdgcn_s_setprio(1); _Pragma("unroll") for (int m = 0; m < 4; ++m) _Pragma("unroll") for (int n = 0; n < 2; ++n) _Pragma("unroll") for (int k = 0; k < 2; ++k) \
;         acc[ai][bj][m][n] = __builtin_amdgcn_mfma_f32_16x16x32_bf16(Bt[n][k], At[m][k], acc[ai][bj][m][n], 0, 0, 0); __builtin_amdgcn_s_setprio(0); } while (0)
; #define PG8_WAIT_V(n) asm volatile("s_waitcnt vmcnt(" #n ")" ::: "memory")
; #define PG8_WAIT_L(n) asm volatile("s_waitcnt lgkmcnt(" #n ")" ::: "memory")
; #define PG8_BAR __builtin_amdgcn_s_barrier()
; #define PG8_SCHED __builtin_amdgcn_sched_barrier(0)
; template <class Epi, class Sched, bool ALIGN_EPI = false, bool SP2 = false>
; __device__ __forceinline__ void gemm_phase(PG8_LAS unsigned char* lds, const Gemm g, const Sched& S, const Epi& E) {
;     ...
;             PG8_WAIT_V(8); PG8_WAIT_L(0); PG8_BAR; PG8_MMA(1, 0, At, B0); PG8_MMA(1, 1, At, B1); PG8_BAR; PG8_SCHED;
;             PG8_LDB(B0, 1, 0); PG8_LDB(B1, 1, 1); PG8_SCHED; PG8_LDA(At, 1, 0); PG8_STAGE(PG8_SA(0, 1), a2 + hstep, voffA);
;             PG8_WAIT_V(8); PG8_WAIT_L(0); PG8_BAR; PG8_MMA(0, 0, At, B0); PG8_MMA(0, 1, At, B1); PG8_BAR; PG8_SCHED;
	v_mfma_f32_16x16x32_bf16 v[62:65], v[146:149], v[184:187], v[62:65]
	v_mfma_f32_16x16x32_bf16 v[62:65], v[150:153], v[188:191], v[62:65]
	v_mfma_f32_16x16x32_bf16 v[54:57], v[150:153], v[204:207], v[54:57]
	v_mfma_f32_16x16x32_bf16 v[54:57], v[146:149], v[200:203], v[54:57]
	v_mfma_f32_16x16x32_bf16 v[42:45], v[146:149], v[208:211], v[42:45]
	v_mfma_f32_16x16x32_bf16 v[42:45], v[150:153], v[212:215], v[42:45]
	v_mfma_f32_16x16x32_bf16 v[26:29], v[150:153], v[220:223], v[26:29]
	v_mfma_f32_16x16x32_bf16 v[26:29], v[146:149], v[216:219], v[26:29]
	v_mfma_f32_16x16x32_bf16 v[18:21], v[154:157], v[216:219], v[18:21]
	v_mfma_f32_16x16x32_bf16 v[18:21], v[158:161], v[220:223], v[18:21]
	v_mfma_f32_16x16x32_bf16 v[58:61], v[158:161], v[188:191], v[58:61]
	v_mfma_f32_16x16x32_bf16 v[58:61], v[154:157], v[184:187], v[58:61]
	v_mfma_f32_16x16x32_bf16 v[50:53], v[154:157], v[200:203], v[50:53]
	v_mfma_f32_16x16x32_bf16 v[50:53], v[158:161], v[204:207], v[50:53]
	v_mfma_f32_16x16x32_bf16 v[34:37], v[158:161], v[212:215], v[34:37]
	v_mfma_f32_16x16x32_bf16 v[34:37], v[154:157], v[208:211], v[34:37]
	s_setprio 0
	s_setprio 1
	v_mfma_f32_16x16x32_bf16 v[14:17], v[168:171], v[208:211], v[14:17]
	v_mfma_f32_16x16x32_bf16 v[14:17], v[172:175], v[212:215], v[14:17]
	v_mfma_f32_16x16x32_bf16 v[46:49], v[172:175], v[188:191], v[46:49]
	v_mfma_f32_16x16x32_bf16 v[46:49], v[168:171], v[184:187], v[46:49]
	v_mfma_f32_16x16x32_bf16 v[30:33], v[168:171], v[200:203], v[30:33]
	v_mfma_f32_16x16x32_bf16 v[30:33], v[172:175], v[204:207], v[30:33]
	v_mfma_f32_16x16x32_bf16 v[6:9], v[172:175], v[220:223], v[6:9]
	v_mfma_f32_16x16x32_bf16 v[6:9], v[168:171], v[216:219], v[6:9]
	v_mfma_f32_16x16x32_bf16 v[2:5], v[176:179], v[216:219], v[2:5]
	v_mfma_f32_16x16x32_bf16 v[2:5], v[180:183], v[220:223], v[2:5]
	v_mfma_f32_16x16x32_bf16 v[38:41], v[180:183], v[188:191], v[38:41]
	v_mfma_f32_16x16x32_bf16 v[38:41], v[176:179], v[184:187], v[38:41]
	v_mfma_f32_16x16x32_bf16 v[22:25], v[176:179], v[200:203], v[22:25]
	v_mfma_f32_16x16x32_bf16 v[22:25], v[180:183], v[204:207], v[22:25]
	v_mfma_f32_16x16x32_bf16 v[10:13], v[180:183], v[212:215], v[10:13]
	v_mfma_f32_16x16x32_bf16 v[10:13], v[176:179], v[208:211], v[10:13]
	s_barrier
	s_setprio 0
	ds_read_b128 v[146:149], v143
	ds_read_b128 v[150:153], v143 offset:1024
	ds_read_b128 v[154:157], v143 offset:2048
	ds_read_b128 v[158:161], v143 offset:3072
	ds_read_b128 v[168:171], v144
	ds_read_b128 v[172:175], v144 offset:1024
	ds_read_b128 v[176:179], v144 offset:2048
	ds_read_b128 v[180:183], v144 offset:3072
	s_add_u32 s46, s54, 0x100000
	s_addc_u32 s47, s55, 0
	s_mov_b32 m0, s17
	v_lshl_add_u64 v[226:227], s[46:47], 0, v[130:131]
	ds_read_b128 v[184:187], v142 offset:32768
	ds_read_b128 v[188:191], v142 offset:33792
	ds_read_b128 v[200:203], v142 offset:34816
	ds_read_b128 v[204:207], v142 offset:35840
	ds_read_b128 v[208:211], v142 offset:36864
	ds_read_b128 v[212:215], v142 offset:37888
	ds_read_b128 v[216:219], v142 offset:38912
	ds_read_b128 v[220:223], v142 offset:39936
	global_load_lds_dwordx4 v[226:227], off
	v_lshl_add_u64 v[226:227], s[46:47], 0, v[132:133]
	s_mov_b32 m0, s26
	s_nop 0
	global_load_lds_dwordx4 v[226:227], off
	s_waitcnt vmcnt(8) lgkmcnt(0)
	s_setprio 1
	s_barrier
	v_mfma_f32_16x16x32_bf16 v[126:129], v[146:149], v[184:187], v[126:129]
	v_mfma_f32_16x16x32_bf16 v[126:129], v[150:153], v[188:191], v[126:129]
	v_mfma_f32_16x16x32_bf16 v[118:121], v[150:153], v[204:207], v[118:121]
	v_mfma_f32_16x16x32_bf16 v[118:121], v[146:149], v[200:203], v[118:121]
	v_mfma_f32_16x16x32_bf16 v[106:109], v[146:149], v[208:211], v[106:109]
	v_mfma_f32_16x16x32_bf16 v[106:109], v[150:153], v[212:215], v[106:109]
	v_mfma_f32_16x16x32_bf16 v[90:93], v[150:153], v[220:223], v[90:93]
	v_mfma_f32_16x16x32_bf16 v[90:93], v[146:149], v[216:219], v[90:93]
	v_mfma_f32_16x16x32_bf16 v[82:85], v[154:157], v[216:219], v[82:85]
	v_mfma_f32_16x16x32_bf16 v[82:85], v[158:161], v[220:223], v[82:85]
	v_mfma_f32_16x16x32_bf16 v[122:125], v[158:161], v[188:191], v[122:125]
	v_mfma_f32_16x16x32_bf16 v[122:125], v[154:157], v[184:187], v[122:125]
	v_mfma_f32_16x16x32_bf16 v[114:117], v[154:157], v[200:203], v[114:117]
	v_mfma_f32_16x16x32_bf16 v[114:117], v[158:161], v[204:207], v[114:117]
	v_mfma_f32_16x16x32_bf16 v[98:101], v[158:161], v[212:215], v[98:101]
	v_mfma_f32_16x16x32_bf16 v[98:101], v[154:157], v[208:211], v[98:101]
	s_setprio 0
	s_setprio 1
	v_mfma_f32_16x16x32_bf16 v[78:81], v[168:171], v[208:211], v[78:81]
	v_mfma_f32_16x16x32_bf16 v[78:81], v[172:175], v[212:215], v[78:81]
	v_mfma_f32_16x16x32_bf16 v[110:113], v[172:175], v[188:191], v[110:113]
	v_mfma_f32_16x16x32_bf16 v[110:113], v[168:171], v[184:187], v[110:113]
	v_mfma_f32_16x16x32_bf16 v[94:97], v[168:171], v[200:203], v[94:97]
	v_mfma_f32_16x16x32_bf16 v[94:97], v[172:175], v[204:207], v[94:97]
	v_mfma_f32_16x16x32_bf16 v[70:73], v[172:175], v[220:223], v[70:73]
	v_mfma_f32_16x16x32_bf16 v[70:73], v[168:171], v[216:219], v[70:73]
	v_mfma_f32_16x16x32_bf16 v[66:69], v[176:179], v[216:219], v[66:69]
	v_mfma_f32_16x16x32_bf16 v[66:69], v[180:183], v[220:223], v[66:69]
	v_mfma_f32_16x16x32_bf16 v[102:105], v[180:183], v[188:191], v[102:105]
	v_mfma_f32_16x16x32_bf16 v[102:105], v[176:179], v[184:187], v[102:105]
	v_mfma_f32_16x16x32_bf16 v[86:89], v[176:179], v[200:203], v[86:89]
	v_mfma_f32_16x16x32_bf16 v[86:89], v[180:183], v[204:207], v[86:89]
	v_mfma_f32_16x16x32_bf16 v[74:77], v[180:183], v[212:215], v[74:77]
	v_mfma_f32_16x16x32_bf16 v[74:77], v[176:179], v[208:211], v[74:77]
	s_barrier
; #define PG8_STAGE(bufoff, gbase, voff) do { _Pragma("unroll") for (int _i = 0; _i < 2; ++_i) \
;         __builtin_amdgcn_global_load_lds((const unsigned*)((const char*)(gbase) + (voff)[_i]), (PG8_LAS unsigned*)(lds + (bufoff) + ldsw + _i * 8192), 16, 0, 0); } while (0)
; #define PG8_LDA(dst, b, h) do { _Pragma("unroll") for (int m = 0; m < 4; ++m) _Pragma("unroll") for (int k = 0; k < 2; ++k) dst[m][k] = *(const PG8_LAS bf16x8*)(lds + PG8_SA(b, h) + aoff + m * 2048 + k * 1024); } while (0)
; #define PG8_MMA(ai, bj, At, Bt) do { __builtin_amdgcn_s_setprio(1); _Pragma("unroll") for (int m = 0; m < 4; ++m) _Pragma("unroll") for (int n = 0; n < 2; ++n) _Pragma("unroll") for (int k = 0; k < 2; ++k) \
;         acc[ai][bj][m][n] = __builtin_amdgcn_mfma_f32_16x16x32_bf16(Bt[n][k], At[m][k], acc[ai][bj][m][n], 0, 0, 0); __builtin_amdgcn_s_setprio(0); } while (0)
; #define PG8_WAIT_V(n) asm volatile("s_waitcnt vmcnt(" #n ")" ::: "memory")
; #define PG8_WAIT_L(n) asm volatile("s_waitcnt lgkmcnt(" #n ")" ::: "memory")
; #define PG8_BAR __builtin_amdgcn_s_barrier()
; #define PG8_SCHED __builtin_amdgcn_sched_barrier(0)
; template <class Epi, class Sched, bool ALIGN_EPI = false, bool SP2 = false>
; __device__ __forceinline__ void gemm_phase(PG8_LAS unsigned char* lds, const Gemm g, const Sched& S, const Epi& E) {
;     ...
;             PG8_LDA(At, 1, 1); PG8_STAGE(PG8_SB(1, 0), b3, voffB); PG8_STAGE(PG8_SB(1, 1), b3 + hstep, voffB); PG8_STAGE(PG8_SA(1, 0), a3, voffA);
;             PG8_WAIT_V(8); PG8_WAIT_L(0); PG8_BAR; PG8_MMA(1, 0, At, B0); PG8_MMA(1, 1, At, B1); PG8_BAR; PG8_SCHED;
	s_setprio 0
	s_mov_b32 m0, s44
	v_lshl_add_u64 v[162:163], v[162:163], 0, s[12:13]
	s_add_u32 s46, s52, 0x100080
	ds_read_b128 v[184:187], v142 offset:49152
	ds_read_b128 v[188:191], v142 offset:50176
	ds_read_b128 v[200:203], v142 offset:51200
	ds_read_b128 v[204:207], v142 offset:52224
	ds_read_b128 v[208:211], v142 offset:53248
	ds_read_b128 v[212:215], v142 offset:54272
	ds_read_b128 v[216:219], v142 offset:55296
	ds_read_b128 v[220:223], v142 offset:56320
	global_load_lds_dwordx4 v[162:163], off
	v_lshl_add_u64 v[162:163], v[192:193], 0, s[12:13]
	s_mov_b32 m0, s45
	s_addc_u32 s47, s53, 0
	global_load_lds_dwordx4 v[162:163], off
	v_lshl_add_u64 v[162:163], s[46:47], 0, v[130:131]
	s_mov_b32 m0, s56
	s_nop 0
	global_load_lds_dwordx4 v[162:163], off
	v_lshl_add_u64 v[162:163], s[46:47], 0, v[132:133]
	s_mov_b32 m0, s57
	s_nop 0
	global_load_lds_dwordx4 v[162:163], off
	v_lshl_add_u64 v[162:163], v[194:195], 0, s[12:13]
	s_mov_b32 m0, s28
	s_nop 0
	global_load_lds_dwordx4 v[162:163], off
	v_lshl_add_u64 v[162:163], v[224:225], 0, s[12:13]
	s_mov_b32 m0, s29
	s_nop 0
	global_load_lds_dwordx4 v[162:163], off
	s_waitcnt vmcnt(8) lgkmcnt(0)
	s_setprio 1
	s_barrier
	v_mfma_f32_16x16x32_bf16 v[62:65], v[146:149], v[184:187], v[62:65]
	v_mfma_f32_16x16x32_bf16 v[62:65], v[150:153], v[188:191], v[62:65]
	v_mfma_f32_16x16x32_bf16 v[54:57], v[150:153], v[204:207], v[54:57]
	v_mfma_f32_16x16x32_bf16 v[54:57], v[146:149], v[200:203], v[54:57]
	v_mfma_f32_16x16x32_bf16 v[42:45], v[146:149], v[208:211], v[42:45]
	v_mfma_f32_16x16x32_bf16 v[42:45], v[150:153], v[212:215], v[42:45]
	v_mfma_f32_16x16x32_bf16 v[26:29], v[150:153], v[220:223], v[26:29]
	v_mfma_f32_16x16x32_bf16 v[26:29], v[146:149], v[216:219], v[26:29]
	v_mfma_f32_16x16x32_bf16 v[18:21], v[154:157], v[216:219], v[18:21]
	v_mfma_f32_16x16x32_bf16 v[18:21], v[158:161], v[220:223], v[18:21]
	v_mfma_f32_16x16x32_bf16 v[58:61], v[158:161], v[188:191], v[58:61]
	v_mfma_f32_16x16x32_bf16 v[58:61], v[154:157], v[184:187], v[58:61]
	v_mfma_f32_16x16x32_bf16 v[50:53], v[154:157], v[200:203], v[50:53]
	v_mfma_f32_16x16x32_bf16 v[50:53], v[158:161], v[204:207], v[50:53]
	v_mfma_f32_16x16x32_bf16 v[34:37], v[158:161], v[212:215], v[34:37]
	v_mfma_f32_16x16x32_bf16 v[34:37], v[154:157], v[208:211], v[34:37]
	s_setprio 0
	s_setprio 1
	v_mfma_f32_16x16x32_bf16 v[14:17], v[168:171], v[208:211], v[14:17]
	v_mfma_f32_16x16x32_bf16 v[14:17], v[172:175], v[212:215], v[14:17]
	v_mfma_f32_16x16x32_bf16 v[46:49], v[172:175], v[188:191], v[46:49]
	v_mfma_f32_16x16x32_bf16 v[46:49], v[168:171], v[184:187], v[46:49]
	v_mfma_f32_16x16x32_bf16 v[30:33], v[168:171], v[200:203], v[30:33]
	v_mfma_f32_16x16x32_bf16 v[30:33], v[172:175], v[204:207], v[30:33]
	v_mfma_f32_16x16x32_bf16 v[6:9], v[172:175], v[220:223], v[6:9]
	v_mfma_f32_16x16x32_bf16 v[6:9], v[168:171], v[216:219], v[6:9]
	v_mfma_f32_16x16x32_bf16 v[2:5], v[176:179], v[216:219], v[2:5]
	v_mfma_f32_16x16x32_bf16 v[2:5], v[180:183], v[220:223], v[2:5]
	v_mfma_f32_16x16x32_bf16 v[38:41], v[180:183], v[188:191], v[38:41]
	v_mfma_f32_16x16x32_bf16 v[38:41], v[176:179], v[184:187], v[38:41]
	v_mfma_f32_16x16x32_bf16 v[22:25], v[176:179], v[200:203], v[22:25]
	v_mfma_f32_16x16x32_bf16 v[22:25], v[180:183], v[204:207], v[22:25]
	v_mfma_f32_16x16x32_bf16 v[10:13], v[180:183], v[212:215], v[10:13]
	v_mfma_f32_16x16x32_bf16 v[10:13], v[176:179], v[208:211], v[10:13]
	s_barrier
	s_setprio 0
	s_add_i32 s30, s30, 2
	s_cmp_gt_u32 s30, 13
	s_mov_b64 s[46:47], s[50:51]
	s_cbranch_scc0 .LBB0_1230
	s_cmpk_lt_u32 s2, 0x100
	s_cbranch_scc0 .LBB0_1233
	s_barrier

; #define PG8_STAGE(bufoff, gbase, voff) do { _Pragma("unroll") for (int _i = 0; _i < 2; ++_i) \
;         __builtin_amdgcn_global_load_lds((const unsigned*)((const char*)(gbase) + (voff)[_i]), (PG8_LAS unsigned*)(lds + (bufoff) + ldsw + _i * 8192), 16, 0, 0); } while (0)
; #define PG8_LDA(dst, b, h) do { _Pragma("unroll") for (int m = 0; m < 4; ++m) _Pragma("unroll") for (int k = 0; k < 2; ++k) dst[m][k] = *(const PG8_LAS bf16x8*)(lds + PG8_SA(b, h) + aoff + m * 2048 + k * 1024); } while (0)
; #define PG8_LDB(dst, b, h) do { _Pragma("unroll") for (int n = 0; n < 2; ++n) _Pragma("unroll") for (int k = 0; k < 2; ++k) dst[n][k] = *(const PG8_LAS bf16x8*)(lds + PG8_SB(b, h) + boff + n * 2048 + k * 1024); } while (0)
; #define PG8_MMA(ai, bj, At, Bt) do { __builtin_amdgcn_s_setprio(1); _Pragma("unroll") for (int m = 0; m < 4; ++m) _Pragma("unroll") for (int n = 0; n < 2; ++n) _Pragma("unroll") for (int k = 0; k < 2; ++k) \
;         acc[ai][bj][m][n] = __builtin_amdgcn_mfma_f32_16x16x32_bf16(Bt[n][k], At[m][k], acc[ai][bj][m][n], 0, 0, 0); __builtin_amdgcn_s_setprio(0); } while (0)
; #define PG8_WAIT_V(n) asm volatile("s_waitcnt vmcnt(" #n ")" ::: "memory")
; #define PG8_WAIT_L(n) asm volatile("s_waitcnt lgkmcnt(" #n ")" ::: "memory")
; template <class Epi, class Sched, bool ALIGN_EPI = false, bool SP2 = false>
; __device__ __forceinline__ void gemm_phase(PG8_LAS unsigned char* lds, const Gemm g, const Sched& S, const Epi& E) {
;     ...
;             const bool last = (t == nt - 2);
;             const char* a1 = cA + (size_t)(t + 1) * kstep;
;             const char* a2 = last ? nA : cA + (size_t)(t + 2) * kstep; const char* b2 = last ? nB : cB + (size_t)(t + 2) * kstep;
;             const char* a3 = a2 + kstep; const char* b3 = b2 + kstep;
;             if (last && has_next) S.a_ready(nxt);
;             if constexpr (SP2) {
;             PG8_LDB(B0, 0, 0); PG8_LDB(B1, 0, 1); PG8_SCHED; PG8_LDA(At, 0, 0); PG8_STAGE(PG8_SA(1, 1), a1 + hstep, voffA);
;             PG8_WAIT_V(8); PG8_WAIT_L(0); PG8_BAR; PG8_MMA(0, 0, At, B0); PG8_MMA(0, 1, At, B1); PG8_BAR; PG8_SCHED;
;             PG8_LDA(At, 0, 1); PG8_STAGE(PG8_SB(0, 0), b2, voffB); PG8_STAGE(PG8_SB(0, 1), b2 + hstep, voffB); PG8_STAGE(PG8_SA(0, 0), a2, voffA);
;             PG8_WAIT_V(8); PG8_WAIT_L(0); PG8_BAR; PG8_MMA(1, 0, At, B0); PG8_MMA(1, 1, At, B1); PG8_BAR; PG8_SCHED;
.LBB0_1478:
	v_add_u32_e32 v144, s31, v201
	v_add_u32_e32 v160, s52, v201
	ds_read_b128 v[132:135], v144
	ds_read_b128 v[136:139], v144 offset:1024
	ds_read_b128 v[140:143], v144 offset:2048
	ds_read_b128 v[144:147], v144 offset:3072
	ds_read_b128 v[148:151], v160
	ds_read_b128 v[152:155], v160 offset:1024
	ds_read_b128 v[156:159], v160 offset:2048
	ds_read_b128 v[160:163], v160 offset:3072
	s_add_u32 s50, s82, 0xfff00080
	s_addc_u32 s56, s83, -1
	s_and_b64 s[34:35], s[84:85], exec
	s_cselect_b32 s87, s65, s56
	s_cselect_b32 s86, s69, s50
	s_cselect_b32 s85, s67, s88
	s_cselect_b32 s84, s77, s79
	s_add_i32 m0, s28, 0xc000
	ds_read_b128 v[164:167], v242
	ds_read_b128 v[168:171], v242 offset:1024
	ds_read_b128 v[172:175], v242 offset:2048
	ds_read_b128 v[176:179], v242 offset:3072
	ds_read_b128 v[180:183], v242 offset:4096
	ds_read_b128 v[184:187], v242 offset:5120
	ds_read_b128 v[188:191], v242 offset:6144
	ds_read_b128 v[226:229], v242 offset:7168
	global_load_lds_dwordx4 v220, s[82:83]
	s_add_i32 m0, s28, 0xe000
	s_nop 0
	global_load_lds_dwordx4 v222, s[82:83]
	s_waitcnt vmcnt(8) lgkmcnt(0)
	s_setprio 1
	s_barrier
	v_mfma_f32_16x16x32_bf16 v[126:129], v[132:135], v[164:167], v[126:129]
	v_mfma_f32_16x16x32_bf16 v[126:129], v[136:139], v[168:171], v[126:129]
	v_mfma_f32_16x16x32_bf16 v[118:121], v[136:139], v[176:179], v[118:121]
	v_mfma_f32_16x16x32_bf16 v[118:121], v[132:135], v[172:175], v[118:121]
	v_mfma_f32_16x16x32_bf16 v[110:113], v[132:135], v[180:183], v[110:113]
	v_mfma_f32_16x16x32_bf16 v[110:113], v[136:139], v[184:187], v[110:113]
	v_mfma_f32_16x16x32_bf16 v[102:105], v[136:139], v[226:229], v[102:105]
	v_mfma_f32_16x16x32_bf16 v[102:105], v[132:135], v[188:191], v[102:105]
	v_mfma_f32_16x16x32_bf16 v[106:109], v[140:143], v[188:191], v[106:109]
	v_mfma_f32_16x16x32_bf16 v[106:109], v[144:147], v[226:229], v[106:109]
	v_mfma_f32_16x16x32_bf16 v[46:49], v[144:147], v[168:171], v[46:49]
	v_mfma_f32_16x16x32_bf16 v[46:49], v[140:143], v[164:167], v[46:49]
	v_mfma_f32_16x16x32_bf16 v[122:125], v[140:143], v[172:175], v[122:125]
	v_mfma_f32_16x16x32_bf16 v[122:125], v[144:147], v[176:179], v[122:125]
	v_mfma_f32_16x16x32_bf16 v[114:117], v[144:147], v[184:187], v[114:117]
	v_mfma_f32_16x16x32_bf16 v[114:117], v[140:143], v[180:183], v[114:117]
	s_setprio 0
	s_setprio 1
	v_mfma_f32_16x16x32_bf16 v[62:65], v[148:151], v[180:183], v[62:65]
	v_mfma_f32_16x16x32_bf16 v[62:65], v[152:155], v[184:187], v[62:65]
	v_mfma_f32_16x16x32_bf16 v[54:57], v[152:155], v[168:171], v[54:57]
	v_mfma_f32_16x16x32_bf16 v[54:57], v[148:151], v[164:167], v[54:57]
	v_mfma_f32_16x16x32_bf16 v[58:61], v[148:151], v[172:175], v[58:61]
	v_mfma_f32_16x16x32_bf16 v[58:61], v[152:155], v[176:179], v[58:61]
	v_mfma_f32_16x16x32_bf16 v[98:101], v[152:155], v[226:229], v[98:101]
	v_mfma_f32_16x16x32_bf16 v[98:101], v[148:151], v[188:191], v[98:101]
	v_mfma_f32_16x16x32_bf16 v[50:53], v[156:159], v[188:191], v[50:53]
	v_mfma_f32_16x16x32_bf16 v[50:53], v[160:163], v[226:229], v[50:53]
	v_mfma_f32_16x16x32_bf16 v[38:41], v[160:163], v[168:171], v[38:41]
	v_mfma_f32_16x16x32_bf16 v[38:41], v[156:159], v[164:167], v[38:41]
	v_mfma_f32_16x16x32_bf16 v[30:33], v[156:159], v[172:175], v[30:33]
	v_mfma_f32_16x16x32_bf16 v[30:33], v[160:163], v[176:179], v[30:33]
	v_mfma_f32_16x16x32_bf16 v[22:25], v[160:163], v[184:187], v[22:25]
	v_mfma_f32_16x16x32_bf16 v[22:25], v[156:159], v[180:183], v[22:25]
	s_barrier
	s_setprio 0
	s_add_i32 s34, s31, s45
	s_mov_b32 m0, s34
	ds_read_b128 v[164:167], v242 offset:16384
	ds_read_b128 v[168:171], v242 offset:17408
	ds_read_b128 v[172:175], v242 offset:18432
	ds_read_b128 v[176:179], v242 offset:19456
	ds_read_b128 v[180:183], v242 offset:20480
	ds_read_b128 v[184:187], v242 offset:21504
	ds_read_b128 v[188:191], v242 offset:22528
	ds_read_b128 v[226:229], v242 offset:23552
	global_load_lds_dwordx4 v208, s[84:85]
	s_add_i32 m0, s34, 0x2000
	s_add_u32 s34, s84, 0x100000
	s_addc_u32 s35, s85, 0
	s_add_i32 s50, s52, s45
	global_load_lds_dwordx4 v212, s[84:85]
	s_mov_b32 m0, s50
	s_nop 0
	global_load_lds_dwordx4 v208, s[34:35]
	s_add_i32 m0, s50, 0x2000
	s_nop 0
	global_load_lds_dwordx4 v212, s[34:35]
	s_mov_b32 m0, s28
	s_nop 0
	global_load_lds_dwordx4 v206, s[86:87]
	s_mov_b32 m0, s29
	s_nop 0
	global_load_lds_dwordx4 v210, s[86:87]
	s_waitcnt vmcnt(8) lgkmcnt(0)
	s_setprio 1
	s_barrier
	v_mfma_f32_16x16x32_bf16 v[78:81], v[132:135], v[164:167], v[78:81]
	v_mfma_f32_16x16x32_bf16 v[78:81], v[136:139], v[168:171], v[78:81]
	v_mfma_f32_16x16x32_bf16 v[66:69], v[136:139], v[176:179], v[66:69]
	v_mfma_f32_16x16x32_bf16 v[66:69], v[132:135], v[172:175], v[66:69]
	v_mfma_f32_16x16x32_bf16 v[70:73], v[132:135], v[180:183], v[70:73]
	v_mfma_f32_16x16x32_bf16 v[70:73], v[136:139], v[184:187], v[70:73]
	v_mfma_f32_16x16x32_bf16 v[74:77], v[136:139], v[226:229], v[74:77]
	v_mfma_f32_16x16x32_bf16 v[74:77], v[132:135], v[188:191], v[74:77]
	v_mfma_f32_16x16x32_bf16 v[10:13], v[140:143], v[188:191], v[10:13]
	v_mfma_f32_16x16x32_bf16 v[10:13], v[144:147], v[226:229], v[10:13]
	v_mfma_f32_16x16x32_bf16 v[14:17], v[144:147], v[168:171], v[14:17]
	v_mfma_f32_16x16x32_bf16 v[14:17], v[140:143], v[164:167], v[14:17]
	v_mfma_f32_16x16x32_bf16 v[94:97], v[140:143], v[172:175], v[94:97]
	v_mfma_f32_16x16x32_bf16 v[94:97], v[144:147], v[176:179], v[94:97]
	v_mfma_f32_16x16x32_bf16 v[90:93], v[144:147], v[184:187], v[90:93]
	v_mfma_f32_16x16x32_bf16 v[90:93], v[140:143], v[180:183], v[90:93]
	s_setprio 0
	s_setprio 1
	v_mfma_f32_16x16x32_bf16 v[86:89], v[148:151], v[180:183], v[86:89]
	v_mfma_f32_16x16x32_bf16 v[86:89], v[152:155], v[184:187], v[86:89]
	v_mfma_f32_16x16x32_bf16 v[42:45], v[152:155], v[168:171], v[42:45]
	v_mfma_f32_16x16x32_bf16 v[42:45], v[148:151], v[164:167], v[42:45]
	v_mfma_f32_16x16x32_bf16 v[34:37], v[148:151], v[172:175], v[34:37]
	v_mfma_f32_16x16x32_bf16 v[34:37], v[152:155], v[176:179], v[34:37]
	v_mfma_f32_16x16x32_bf16 v[82:85], v[152:155], v[226:229], v[82:85]
	v_mfma_f32_16x16x32_bf16 v[82:85], v[148:151], v[188:191], v[82:85]
	v_mfma_f32_16x16x32_bf16 v[18:21], v[156:159], v[188:191], v[18:21]
	v_mfma_f32_16x16x32_bf16 v[18:21], v[160:163], v[226:229], v[18:21]
	v_mfma_f32_16x16x32_bf16 v[2:5], v[160:163], v[168:171], v[2:5]
	v_mfma_f32_16x16x32_bf16 v[2:5], v[156:159], v[164:167], v[2:5]
	v_mfma_f32_16x16x32_bf16 v[6:9], v[156:159], v[172:175], v[6:9]
	v_mfma_f32_16x16x32_bf16 v[6:9], v[160:163], v[176:179], v[6:9]
	v_mfma_f32_16x16x32_bf16 v[26:29], v[160:163], v[184:187], v[26:29]
	v_mfma_f32_16x16x32_bf16 v[26:29], v[156:159], v[180:183], v[26:29]
	s_barrier
; #define PG8_STAGE(bufoff, gbase, voff) do { _Pragma("unroll") for (int _i = 0; _i < 2; ++_i) \
;         __builtin_amdgcn_global_load_lds((const unsigned*)((const char*)(gbase) + (voff)[_i]), (PG8_LAS unsigned*)(lds + (bufoff) + ldsw + _i * 8192), 16, 0, 0); } while (0)
; #define PG8_LDA(dst, b, h) do { _Pragma("unroll") for (int m = 0; m < 4; ++m) _Pragma("unroll") for (int k = 0; k < 2; ++k) dst[m][k] = *(const PG8_LAS bf16x8*)(lds + PG8_SA(b, h) + aoff + m * 2048 + k * 1024); } while (0)
; #define PG8_LDB(dst, b, h) do { _Pragma("unroll") for (int n = 0; n < 2; ++n) _Pragma("unroll") for (int k = 0; k < 2; ++k) dst[n][k] = *(const PG8_LAS bf16x8*)(lds + PG8_SB(b, h) + boff + n * 2048 + k * 1024); } while (0)
; #define PG8_MMA(ai, bj, At, Bt) do { __builtin_amdgcn_s_setprio(1); _Pragma("unroll") for (int m = 0; m < 4; ++m) _Pragma("unroll") for (int n = 0; n < 2; ++n) _Pragma("unroll") for (int k = 0; k < 2; ++k) \
;         acc[ai][bj][m][n] = __builtin_amdgcn_mfma_f32_16x16x32_bf16(Bt[n][k], At[m][k], acc[ai][bj][m][n], 0, 0, 0); __builtin_amdgcn_s_setprio(0); } while (0)
; #define PG8_WAIT_V(n) asm volatile("s_waitcnt vmcnt(" #n ")" ::: "memory")
; #define PG8_WAIT_L(n) asm volatile("s_waitcnt lgkmcnt(" #n ")" ::: "memory")
; #define PG8_BAR __builtin_amdgcn_s_barrier()
; #define PG8_SCHED __builtin_amdgcn_sched_barrier(0)
; template <class Epi, class Sched, bool ALIGN_EPI = false, bool SP2 = false>
; __device__ __forceinline__ void gemm_phase(PG8_LAS unsigned char* lds, const Gemm g, const Sched& S, const Epi& E) {
;     ...
;             PG8_LDB(B0, 1, 0); PG8_LDB(B1, 1, 1); PG8_SCHED; PG8_LDA(At, 1, 0); PG8_STAGE(PG8_SA(0, 1), a2 + hstep, voffA);
;             PG8_WAIT_V(8); PG8_WAIT_L(0); PG8_BAR; PG8_MMA(0, 0, At, B0); PG8_MMA(0, 1, At, B1); PG8_BAR; PG8_SCHED;
;             PG8_LDA(At, 1, 1); PG8_STAGE(PG8_SB(1, 0), b3, voffB); PG8_STAGE(PG8_SB(1, 1), b3 + hstep, voffB); PG8_STAGE(PG8_SA(1, 0), a3, voffA);
;             PG8_WAIT_V(8); PG8_WAIT_L(0); PG8_BAR; PG8_MMA(1, 0, At, B0); PG8_MMA(1, 1, At, B1); PG8_BAR; PG8_SCHED;
	s_setprio 0
	s_add_i32 s50, 0, 0x18000
	s_add_i32 s56, 0, 0x1c000
	v_add_u32_e32 v144, s50, v201
	v_add_u32_e32 v160, s56, v201
	ds_read_b128 v[132:135], v144
	ds_read_b128 v[136:139], v144 offset:1024
	ds_read_b128 v[140:143], v144 offset:2048
	ds_read_b128 v[144:147], v144 offset:3072
	ds_read_b128 v[148:151], v160
	ds_read_b128 v[152:155], v160 offset:1024
	ds_read_b128 v[156:159], v160 offset:2048
	ds_read_b128 v[160:163], v160 offset:3072
	s_add_u32 s34, s86, 0x100000
	s_addc_u32 s35, s87, 0
	s_mov_b32 m0, s16
	ds_read_b128 v[164:167], v242 offset:32768
	ds_read_b128 v[168:171], v242 offset:33792
	ds_read_b128 v[172:175], v242 offset:34816
	ds_read_b128 v[176:179], v242 offset:35840
	ds_read_b128 v[180:183], v242 offset:36864
	ds_read_b128 v[184:187], v242 offset:37888
	ds_read_b128 v[188:191], v242 offset:38912
	ds_read_b128 v[226:229], v242 offset:39936
	global_load_lds_dwordx4 v206, s[34:35]
	s_mov_b32 m0, s17
	s_nop 0
	global_load_lds_dwordx4 v210, s[34:35]
	s_waitcnt vmcnt(8) lgkmcnt(0)
	s_setprio 1
	s_barrier
	v_mfma_f32_16x16x32_bf16 v[126:129], v[132:135], v[164:167], v[126:129]
	v_mfma_f32_16x16x32_bf16 v[126:129], v[136:139], v[168:171], v[126:129]
	v_mfma_f32_16x16x32_bf16 v[118:121], v[136:139], v[176:179], v[118:121]
	v_mfma_f32_16x16x32_bf16 v[118:121], v[132:135], v[172:175], v[118:121]
	v_mfma_f32_16x16x32_bf16 v[110:113], v[132:135], v[180:183], v[110:113]
	v_mfma_f32_16x16x32_bf16 v[110:113], v[136:139], v[184:187], v[110:113]
	v_mfma_f32_16x16x32_bf16 v[102:105], v[136:139], v[226:229], v[102:105]
	v_mfma_f32_16x16x32_bf16 v[102:105], v[132:135], v[188:191], v[102:105]
	v_mfma_f32_16x16x32_bf16 v[106:109], v[140:143], v[188:191], v[106:109]
	v_mfma_f32_16x16x32_bf16 v[106:109], v[144:147], v[226:229], v[106:109]
	v_mfma_f32_16x16x32_bf16 v[46:49], v[144:147], v[168:171], v[46:49]
	v_mfma_f32_16x16x32_bf16 v[46:49], v[140:143], v[164:167], v[46:49]
	v_mfma_f32_16x16x32_bf16 v[122:125], v[140:143], v[172:175], v[122:125]
	v_mfma_f32_16x16x32_bf16 v[122:125], v[144:147], v[176:179], v[122:125]
	v_mfma_f32_16x16x32_bf16 v[114:117], v[144:147], v[184:187], v[114:117]
	v_mfma_f32_16x16x32_bf16 v[114:117], v[140:143], v[180:183], v[114:117]
	s_setprio 0
	s_setprio 1
	v_mfma_f32_16x16x32_bf16 v[62:65], v[148:151], v[180:183], v[62:65]
	v_mfma_f32_16x16x32_bf16 v[62:65], v[152:155], v[184:187], v[62:65]
	v_mfma_f32_16x16x32_bf16 v[54:57], v[152:155], v[168:171], v[54:57]
	v_mfma_f32_16x16x32_bf16 v[54:57], v[148:151], v[164:167], v[54:57]
	v_mfma_f32_16x16x32_bf16 v[58:61], v[148:151], v[172:175], v[58:61]
	v_mfma_f32_16x16x32_bf16 v[58:61], v[152:155], v[176:179], v[58:61]
	v_mfma_f32_16x16x32_bf16 v[98:101], v[152:155], v[226:229], v[98:101]
	v_mfma_f32_16x16x32_bf16 v[98:101], v[148:151], v[188:191], v[98:101]
	v_mfma_f32_16x16x32_bf16 v[50:53], v[156:159], v[188:191], v[50:53]
	v_mfma_f32_16x16x32_bf16 v[50:53], v[160:163], v[226:229], v[50:53]
	v_mfma_f32_16x16x32_bf16 v[38:41], v[160:163], v[168:171], v[38:41]
	v_mfma_f32_16x16x32_bf16 v[38:41], v[156:159], v[164:167], v[38:41]
	v_mfma_f32_16x16x32_bf16 v[30:33], v[156:159], v[172:175], v[30:33]
	v_mfma_f32_16x16x32_bf16 v[30:33], v[160:163], v[176:179], v[30:33]
	v_mfma_f32_16x16x32_bf16 v[22:25], v[160:163], v[184:187], v[22:25]
	v_mfma_f32_16x16x32_bf16 v[22:25], v[156:159], v[180:183], v[22:25]
	s_barrier
	s_setprio 0
	s_add_i32 s34, s50, s45
	s_add_u32 s98, s84, s54
	s_addc_u32 s99, s85, s55
	s_mov_b32 m0, s34
	ds_read_b128 v[164:167], v242 offset:49152
	ds_read_b128 v[168:171], v242 offset:50176
	ds_read_b128 v[172:175], v242 offset:51200
	ds_read_b128 v[176:179], v242 offset:52224
	ds_read_b128 v[180:183], v242 offset:53248
	ds_read_b128 v[184:187], v242 offset:54272
	ds_read_b128 v[188:191], v242 offset:55296
	ds_read_b128 v[226:229], v242 offset:56320
	global_load_lds_dwordx4 v208, s[98:99]
	s_add_i32 m0, s34, 0x2000
	s_add_u32 s34, s84, 0x100080
	s_addc_u32 s35, s85, 0
	s_add_i32 s50, s56, s45
	global_load_lds_dwordx4 v212, s[98:99]
	s_mov_b32 m0, s50
	s_nop 0
	global_load_lds_dwordx4 v208, s[34:35]
	s_add_i32 m0, s50, 0x2000
	s_nop 0
	global_load_lds_dwordx4 v212, s[34:35]
	s_add_u32 s100, s86, s54
	s_addc_u32 s101, s87, s55
	s_mov_b32 m0, s39
	s_nop 0
	global_load_lds_dwordx4 v206, s[100:101]
	s_mov_b32 m0, s46
	s_nop 0
	global_load_lds_dwordx4 v210, s[100:101]
	s_waitcnt vmcnt(8) lgkmcnt(0)
	s_setprio 1
	s_barrier
	v_mfma_f32_16x16x32_bf16 v[78:81], v[132:135], v[164:167], v[78:81]
	v_mfma_f32_16x16x32_bf16 v[78:81], v[136:139], v[168:171], v[78:81]
	v_mfma_f32_16x16x32_bf16 v[66:69], v[136:139], v[176:179], v[66:69]
	v_mfma_f32_16x16x32_bf16 v[66:69], v[132:135], v[172:175], v[66:69]
	v_mfma_f32_16x16x32_bf16 v[70:73], v[132:135], v[180:183], v[70:73]
	v_mfma_f32_16x16x32_bf16 v[70:73], v[136:139], v[184:187], v[70:73]
	v_mfma_f32_16x16x32_bf16 v[74:77], v[136:139], v[226:229], v[74:77]
	v_mfma_f32_16x16x32_bf16 v[74:77], v[132:135], v[188:191], v[74:77]
	v_mfma_f32_16x16x32_bf16 v[10:13], v[140:143], v[188:191], v[10:13]
	v_mfma_f32_16x16x32_bf16 v[10:13], v[144:147], v[226:229], v[10:13]
	v_mfma_f32_16x16x32_bf16 v[14:17], v[144:147], v[168:171], v[14:17]
	v_mfma_f32_16x16x32_bf16 v[14:17], v[140:143], v[164:167], v[14:17]
	v_mfma_f32_16x16x32_bf16 v[94:97], v[140:143], v[172:175], v[94:97]
	v_mfma_f32_16x16x32_bf16 v[94:97], v[144:147], v[176:179], v[94:97]
	v_mfma_f32_16x16x32_bf16 v[90:93], v[144:147], v[184:187], v[90:93]
	v_mfma_f32_16x16x32_bf16 v[90:93], v[140:143], v[180:183], v[90:93]
	s_setprio 0
	s_setprio 1
	v_mfma_f32_16x16x32_bf16 v[86:89], v[148:151], v[180:183], v[86:89]
	v_mfma_f32_16x16x32_bf16 v[86:89], v[152:155], v[184:187], v[86:89]
	v_mfma_f32_16x16x32_bf16 v[42:45], v[152:155], v[168:171], v[42:45]
	v_mfma_f32_16x16x32_bf16 v[42:45], v[148:151], v[164:167], v[42:45]
	v_mfma_f32_16x16x32_bf16 v[34:37], v[148:151], v[172:175], v[34:37]
	v_mfma_f32_16x16x32_bf16 v[34:37], v[152:155], v[176:179], v[34:37]
	v_mfma_f32_16x16x32_bf16 v[82:85], v[152:155], v[226:229], v[82:85]
	v_mfma_f32_16x16x32_bf16 v[82:85], v[148:151], v[188:191], v[82:85]
	v_mfma_f32_16x16x32_bf16 v[18:21], v[156:159], v[188:191], v[18:21]
	v_mfma_f32_16x16x32_bf16 v[18:21], v[160:163], v[226:229], v[18:21]
	v_mfma_f32_16x16x32_bf16 v[2:5], v[160:163], v[168:171], v[2:5]
	v_mfma_f32_16x16x32_bf16 v[2:5], v[156:159], v[164:167], v[2:5]
	v_mfma_f32_16x16x32_bf16 v[6:9], v[156:159], v[172:175], v[6:9]
	v_mfma_f32_16x16x32_bf16 v[6:9], v[160:163], v[176:179], v[6:9]
	v_mfma_f32_16x16x32_bf16 v[26:29], v[160:163], v[184:187], v[26:29]
	v_mfma_f32_16x16x32_bf16 v[26:29], v[156:159], v[180:183], v[26:29]
	s_barrier
	s_setprio 0
	s_add_i32 s89, s89, 2
	s_add_u32 s82, s82, 0x100
	s_addc_u32 s83, s83, 0
	s_add_u32 s79, s79, 0x100
	s_addc_u32 s88, s88, 0
	s_cmp_gt_u32 s89, 61
	s_cbranch_scc1 .LBB0_1490

; #define PG8_STAGE(bufoff, gbase, voff) do { _Pragma("unroll") for (int _i = 0; _i < 2; ++_i) \
;         __builtin_amdgcn_global_load_lds((const unsigned*)((const char*)(gbase) + (voff)[_i]), (PG8_LAS unsigned*)(lds + (bufoff) + ldsw + _i * 8192), 16, 0, 0); } while (0)
; #define PG8_LDA(dst, b, h) do { _Pragma("unroll") for (int m = 0; m < 4; ++m) _Pragma("unroll") for (int k = 0; k < 2; ++k) dst[m][k] = *(const PG8_LAS bf16x8*)(lds + PG8_SA(b, h) + aoff + m * 2048 + k * 1024); } while (0)
; #define PG8_LDB(dst, b, h) do { _Pragma("unroll") for (int n = 0; n < 2; ++n) _Pragma("unroll") for (int k = 0; k < 2; ++k) dst[n][k] = *(const PG8_LAS bf16x8*)(lds + PG8_SB(b, h) + boff + n * 2048 + k * 1024); } while (0)
; #define PG8_MMA(ai, bj, At, Bt) do { __builtin_amdgcn_s_setprio(1); _Pragma("unroll") for (int m = 0; m < 4; ++m) _Pragma("unroll") for (int n = 0; n < 2; ++n) _Pragma("unroll") for (int k = 0; k < 2; ++k) \
;         acc[ai][bj][m][n] = __builtin_amdgcn_mfma_f32_16x16x32_bf16(Bt[n][k], At[m][k], acc[ai][bj][m][n], 0, 0, 0); __builtin_amdgcn_s_setprio(0); } while (0)
; #define PG8_WAIT_V(n) asm volatile("s_waitcnt vmcnt(" #n ")" ::: "memory")
; #define PG8_WAIT_L(n) asm volatile("s_waitcnt lgkmcnt(" #n ")" ::: "memory")
; template <class Epi, class Sched, bool ALIGN_EPI = false, bool SP2 = false>
; __device__ __forceinline__ void gemm_phase(PG8_LAS unsigned char* lds, const Gemm g, const Sched& S, const Epi& E) {
;     ...
;             const bool last = (t == nt - 2);
;             const char* a1 = cA + (size_t)(t + 1) * kstep;
;             const char* a2 = last ? nA : cA + (size_t)(t + 2) * kstep; const char* b2 = last ? nB : cB + (size_t)(t + 2) * kstep;
;             const char* a3 = a2 + kstep; const char* b3 = b2 + kstep;
;             if (last && has_next) S.a_ready(nxt);
;             if constexpr (SP2) {
;             PG8_LDB(B0, 0, 0); PG8_LDB(B1, 0, 1); PG8_SCHED; PG8_LDA(At, 0, 0); PG8_STAGE(PG8_SA(1, 1), a1 + hstep, voffA);
;             PG8_WAIT_V(8); PG8_WAIT_L(0); PG8_BAR; PG8_MMA(0, 0, At, B0); PG8_MMA(0, 1, At, B1); PG8_BAR; PG8_SCHED;
;             PG8_LDA(At, 0, 1); PG8_STAGE(PG8_SB(0, 0), b2, voffB); PG8_STAGE(PG8_SB(0, 1), b2 + hstep, voffB); PG8_STAGE(PG8_SA(0, 0), a2, voffA);
;             PG8_WAIT_V(8); PG8_WAIT_L(0); PG8_BAR; PG8_MMA(1, 0, At, B0); PG8_MMA(1, 1, At, B1); PG8_BAR; PG8_SCHED;
.LBB0_1731:
	ds_read_b128 v[170:173], v166
	ds_read_b128 v[174:177], v166 offset:1024
	ds_read_b128 v[178:181], v166 offset:2048
	ds_read_b128 v[182:185], v166 offset:3072
	ds_read_b128 v[186:189], v167
	ds_read_b128 v[190:193], v167 offset:1024
	ds_read_b128 v[196:199], v167 offset:2048
	ds_read_b128 v[202:205], v167 offset:3072
	s_add_u32 s48, s40, 0x100
	s_addc_u32 s49, s41, 0
	s_cmpk_eq_i32 s56, 0xa8
	s_cselect_b32 s53, s7, s49
	s_cselect_b32 s52, s6, s48
	s_cselect_b32 s51, s39, s55
	s_cselect_b32 s50, s38, s54
	v_lshl_add_u64 v[146:147], s[40:41], 0, v[138:139]
	s_add_i32 m0, s16, 0xc000
	ds_read_b128 v[206:209], v168
	ds_read_b128 v[210:213], v168 offset:1024
	ds_read_b128 v[214:217], v168 offset:2048
	ds_read_b128 v[218:221], v168 offset:3072
	ds_read_b128 v[222:225], v168 offset:4096
	ds_read_b128 v[226:229], v168 offset:5120
	ds_read_b128 v[230:233], v168 offset:6144
	ds_read_b128 v[234:237], v168 offset:7168
	global_load_lds_dwordx4 v[146:147], off
	v_lshl_add_u64 v[146:147], s[40:41], 0, v[140:141]
	s_add_i32 m0, s16, 0xe000
	s_nop 0
	global_load_lds_dwordx4 v[146:147], off
	s_waitcnt vmcnt(8) lgkmcnt(0)
	s_setprio 1
	s_barrier
	v_mfma_f32_16x16x32_bf16 v[126:129], v[170:173], v[206:209], v[126:129]
	v_mfma_f32_16x16x32_bf16 v[126:129], v[174:177], v[210:213], v[126:129]
	v_mfma_f32_16x16x32_bf16 v[110:113], v[174:177], v[218:221], v[110:113]
	v_mfma_f32_16x16x32_bf16 v[110:113], v[170:173], v[214:217], v[110:113]
	v_mfma_f32_16x16x32_bf16 v[94:97], v[170:173], v[222:225], v[94:97]
	v_mfma_f32_16x16x32_bf16 v[94:97], v[174:177], v[226:229], v[94:97]
	v_mfma_f32_16x16x32_bf16 v[78:81], v[174:177], v[234:237], v[78:81]
	v_mfma_f32_16x16x32_bf16 v[78:81], v[170:173], v[230:233], v[78:81]
	v_mfma_f32_16x16x32_bf16 v[74:77], v[178:181], v[230:233], v[74:77]
	v_mfma_f32_16x16x32_bf16 v[74:77], v[182:185], v[234:237], v[74:77]
	v_mfma_f32_16x16x32_bf16 v[122:125], v[182:185], v[210:213], v[122:125]
	v_mfma_f32_16x16x32_bf16 v[122:125], v[178:181], v[206:209], v[122:125]
	v_mfma_f32_16x16x32_bf16 v[106:109], v[178:181], v[214:217], v[106:109]
	v_mfma_f32_16x16x32_bf16 v[106:109], v[182:185], v[218:221], v[106:109]
	v_mfma_f32_16x16x32_bf16 v[90:93], v[182:185], v[226:229], v[90:93]
	v_mfma_f32_16x16x32_bf16 v[90:93], v[178:181], v[222:225], v[90:93]
	s_setprio 0
	s_setprio 1
	v_mfma_f32_16x16x32_bf16 v[86:89], v[186:189], v[222:225], v[86:89]
	v_mfma_f32_16x16x32_bf16 v[86:89], v[190:193], v[226:229], v[86:89]
	v_mfma_f32_16x16x32_bf16 v[118:121], v[190:193], v[210:213], v[118:121]
	v_mfma_f32_16x16x32_bf16 v[118:121], v[186:189], v[206:209], v[118:121]
	v_mfma_f32_16x16x32_bf16 v[102:105], v[186:189], v[214:217], v[102:105]
	v_mfma_f32_16x16x32_bf16 v[102:105], v[190:193], v[218:221], v[102:105]
	v_mfma_f32_16x16x32_bf16 v[70:73], v[190:193], v[234:237], v[70:73]
	v_mfma_f32_16x16x32_bf16 v[70:73], v[186:189], v[230:233], v[70:73]
	v_mfma_f32_16x16x32_bf16 v[66:69], v[196:199], v[230:233], v[66:69]
	v_mfma_f32_16x16x32_bf16 v[66:69], v[202:205], v[234:237], v[66:69]
	v_mfma_f32_16x16x32_bf16 v[114:117], v[202:205], v[210:213], v[114:117]
	v_mfma_f32_16x16x32_bf16 v[114:117], v[196:199], v[206:209], v[114:117]
	v_mfma_f32_16x16x32_bf16 v[98:101], v[196:199], v[214:217], v[98:101]
	v_mfma_f32_16x16x32_bf16 v[98:101], v[202:205], v[218:221], v[98:101]
	v_mfma_f32_16x16x32_bf16 v[82:85], v[202:205], v[226:229], v[82:85]
	v_mfma_f32_16x16x32_bf16 v[82:85], v[196:199], v[222:225], v[82:85]
	s_barrier
	s_setprio 0
	s_add_i32 s40, s31, s3
	s_mov_b32 m0, s40
	ds_read_b128 v[206:209], v168 offset:16384
	ds_read_b128 v[210:213], v168 offset:17408
	ds_read_b128 v[214:217], v168 offset:18432
	ds_read_b128 v[218:221], v168 offset:19456
	ds_read_b128 v[222:225], v168 offset:20480
	ds_read_b128 v[226:229], v168 offset:21504
	ds_read_b128 v[230:233], v168 offset:22528
	ds_read_b128 v[234:237], v168 offset:23552
	global_load_lds_dwordx4 v132, s[50:51]
	s_add_i32 m0, s40, 0x2000
	s_add_u32 s40, s50, 0x2b0000
	s_addc_u32 s41, s51, 0
	s_add_i32 s57, s35, s3
	global_load_lds_dwordx4 v136, s[50:51]
	s_mov_b32 m0, s57
	s_nop 0
	global_load_lds_dwordx4 v132, s[40:41]
	s_add_i32 m0, s57, 0x2000
	s_nop 0
	global_load_lds_dwordx4 v136, s[40:41]
	s_mov_b32 m0, s16
	s_nop 0
	global_load_lds_dwordx4 v130, s[52:53]
	s_mov_b32 m0, s17
	s_nop 0
	global_load_lds_dwordx4 v134, s[52:53]
	s_waitcnt vmcnt(8) lgkmcnt(0)
	s_setprio 1
	s_barrier
	v_mfma_f32_16x16x32_bf16 v[62:65], v[170:173], v[206:209], v[62:65]
	v_mfma_f32_16x16x32_bf16 v[62:65], v[174:177], v[210:213], v[62:65]
	v_mfma_f32_16x16x32_bf16 v[46:49], v[174:177], v[218:221], v[46:49]
	v_mfma_f32_16x16x32_bf16 v[46:49], v[170:173], v[214:217], v[46:49]
	v_mfma_f32_16x16x32_bf16 v[30:33], v[170:173], v[222:225], v[30:33]
	v_mfma_f32_16x16x32_bf16 v[30:33], v[174:177], v[226:229], v[30:33]
	v_mfma_f32_16x16x32_bf16 v[14:17], v[174:177], v[234:237], v[14:17]
	v_mfma_f32_16x16x32_bf16 v[14:17], v[170:173], v[230:233], v[14:17]
	v_mfma_f32_16x16x32_bf16 v[10:13], v[178:181], v[230:233], v[10:13]
	v_mfma_f32_16x16x32_bf16 v[10:13], v[182:185], v[234:237], v[10:13]
	v_mfma_f32_16x16x32_bf16 v[58:61], v[182:185], v[210:213], v[58:61]
	v_mfma_f32_16x16x32_bf16 v[58:61], v[178:181], v[206:209], v[58:61]
	v_mfma_f32_16x16x32_bf16 v[42:45], v[178:181], v[214:217], v[42:45]
	v_mfma_f32_16x16x32_bf16 v[42:45], v[182:185], v[218:221], v[42:45]
	v_mfma_f32_16x16x32_bf16 v[26:29], v[182:185], v[226:229], v[26:29]
	v_mfma_f32_16x16x32_bf16 v[26:29], v[178:181], v[222:225], v[26:29]
	s_setprio 0
	s_setprio 1
	v_mfma_f32_16x16x32_bf16 v[22:25], v[186:189], v[222:225], v[22:25]
	v_mfma_f32_16x16x32_bf16 v[22:25], v[190:193], v[226:229], v[22:25]
	v_mfma_f32_16x16x32_bf16 v[54:57], v[190:193], v[210:213], v[54:57]
	v_mfma_f32_16x16x32_bf16 v[54:57], v[186:189], v[206:209], v[54:57]
	v_mfma_f32_16x16x32_bf16 v[38:41], v[186:189], v[214:217], v[38:41]
	v_mfma_f32_16x16x32_bf16 v[38:41], v[190:193], v[218:221], v[38:41]
	v_mfma_f32_16x16x32_bf16 v[6:9], v[190:193], v[234:237], v[6:9]
	v_mfma_f32_16x16x32_bf16 v[6:9], v[186:189], v[230:233], v[6:9]
	v_mfma_f32_16x16x32_bf16 v[2:5], v[196:199], v[230:233], v[2:5]
	v_mfma_f32_16x16x32_bf16 v[2:5], v[202:205], v[234:237], v[2:5]
	v_mfma_f32_16x16x32_bf16 v[50:53], v[202:205], v[210:213], v[50:53]
	v_mfma_f32_16x16x32_bf16 v[50:53], v[196:199], v[206:209], v[50:53]
	v_mfma_f32_16x16x32_bf16 v[34:37], v[196:199], v[214:217], v[34:37]
	v_mfma_f32_16x16x32_bf16 v[34:37], v[202:205], v[218:221], v[34:37]
	v_mfma_f32_16x16x32_bf16 v[18:21], v[202:205], v[226:229], v[18:21]
	v_mfma_f32_16x16x32_bf16 v[18:21], v[196:199], v[222:225], v[18:21]
	s_barrier
; #define PG8_STAGE(bufoff, gbase, voff) do { _Pragma("unroll") for (int _i = 0; _i < 2; ++_i) \
;         __builtin_amdgcn_global_load_lds((const unsigned*)((const char*)(gbase) + (voff)[_i]), (PG8_LAS unsigned*)(lds + (bufoff) + ldsw + _i * 8192), 16, 0, 0); } while (0)
; #define PG8_LDA(dst, b, h) do { _Pragma("unroll") for (int m = 0; m < 4; ++m) _Pragma("unroll") for (int k = 0; k < 2; ++k) dst[m][k] = *(const PG8_LAS bf16x8*)(lds + PG8_SA(b, h) + aoff + m * 2048 + k * 1024); } while (0)
; #define PG8_LDB(dst, b, h) do { _Pragma("unroll") for (int n = 0; n < 2; ++n) _Pragma("unroll") for (int k = 0; k < 2; ++k) dst[n][k] = *(const PG8_LAS bf16x8*)(lds + PG8_SB(b, h) + boff + n * 2048 + k * 1024); } while (0)
; #define PG8_MMA(ai, bj, At, Bt) do { __builtin_amdgcn_s_setprio(1); _Pragma("unroll") for (int m = 0; m < 4; ++m) _Pragma("unroll") for (int n = 0; n < 2; ++n) _Pragma("unroll") for (int k = 0; k < 2; ++k) \
;         acc[ai][bj][m][n] = __builtin_amdgcn_mfma_f32_16x16x32_bf16(Bt[n][k], At[m][k], acc[ai][bj][m][n], 0, 0, 0); __builtin_amdgcn_s_setprio(0); } while (0)
; #define PG8_WAIT_V(n) asm volatile("s_waitcnt vmcnt(" #n ")" ::: "memory")
; #define PG8_WAIT_L(n) asm volatile("s_waitcnt lgkmcnt(" #n ")" ::: "memory")
; #define PG8_BAR __builtin_amdgcn_s_barrier()
; #define PG8_SCHED __builtin_amdgcn_sched_barrier(0)
; template <class Epi, class Sched, bool ALIGN_EPI = false, bool SP2 = false>
; __device__ __forceinline__ void gemm_phase(PG8_LAS unsigned char* lds, const Gemm g, const Sched& S, const Epi& E) {
;     ...
;             PG8_LDB(B0, 1, 0); PG8_LDB(B1, 1, 1); PG8_SCHED; PG8_LDA(At, 1, 0); PG8_STAGE(PG8_SA(0, 1), a2 + hstep, voffA);
;             PG8_WAIT_V(8); PG8_WAIT_L(0); PG8_BAR; PG8_MMA(0, 0, At, B0); PG8_MMA(0, 1, At, B1); PG8_BAR; PG8_SCHED;
;             PG8_LDA(At, 1, 1); PG8_STAGE(PG8_SB(1, 0), b3, voffB); PG8_STAGE(PG8_SB(1, 1), b3 + hstep, voffB); PG8_STAGE(PG8_SA(1, 0), a3, voffA);
;             PG8_WAIT_V(8); PG8_WAIT_L(0); PG8_BAR; PG8_MMA(1, 0, At, B0); PG8_MMA(1, 1, At, B1); PG8_BAR; PG8_SCHED;
	s_setprio 0
	s_add_i32 s57, 0, 0x18000
	v_add_u32_e32 v169, s57, v148
	s_add_i32 s58, 0, 0x1c000
	ds_read_b128 v[170:173], v169
	ds_read_b128 v[174:177], v169 offset:1024
	ds_read_b128 v[178:181], v169 offset:2048
	ds_read_b128 v[182:185], v169 offset:3072
	v_add_u32_e32 v169, s58, v148
	ds_read_b128 v[186:189], v169
	ds_read_b128 v[190:193], v169 offset:1024
	ds_read_b128 v[196:199], v169 offset:2048
	ds_read_b128 v[202:205], v169 offset:3072
	s_add_u32 s40, s52, 0x2b0000
	s_addc_u32 s41, s53, 0
	s_mov_b32 m0, s25
	ds_read_b128 v[206:209], v168 offset:32768
	ds_read_b128 v[210:213], v168 offset:33792
	ds_read_b128 v[214:217], v168 offset:34816
	ds_read_b128 v[218:221], v168 offset:35840
	ds_read_b128 v[222:225], v168 offset:36864
	ds_read_b128 v[226:229], v168 offset:37888
	ds_read_b128 v[230:233], v168 offset:38912
	ds_read_b128 v[234:237], v168 offset:39936
	global_load_lds_dwordx4 v130, s[40:41]
	s_mov_b32 m0, s26
	s_nop 0
	global_load_lds_dwordx4 v134, s[40:41]
	s_waitcnt vmcnt(8) lgkmcnt(0)
	s_setprio 1
	s_barrier
	v_mfma_f32_16x16x32_bf16 v[126:129], v[170:173], v[206:209], v[126:129]
	v_mfma_f32_16x16x32_bf16 v[126:129], v[174:177], v[210:213], v[126:129]
	v_mfma_f32_16x16x32_bf16 v[110:113], v[174:177], v[218:221], v[110:113]
	v_mfma_f32_16x16x32_bf16 v[110:113], v[170:173], v[214:217], v[110:113]
	v_mfma_f32_16x16x32_bf16 v[94:97], v[170:173], v[222:225], v[94:97]
	v_mfma_f32_16x16x32_bf16 v[94:97], v[174:177], v[226:229], v[94:97]
	v_mfma_f32_16x16x32_bf16 v[78:81], v[174:177], v[234:237], v[78:81]
	v_mfma_f32_16x16x32_bf16 v[78:81], v[170:173], v[230:233], v[78:81]
	v_mfma_f32_16x16x32_bf16 v[74:77], v[178:181], v[230:233], v[74:77]
	v_mfma_f32_16x16x32_bf16 v[74:77], v[182:185], v[234:237], v[74:77]
	v_mfma_f32_16x16x32_bf16 v[122:125], v[182:185], v[210:213], v[122:125]
	v_mfma_f32_16x16x32_bf16 v[122:125], v[178:181], v[206:209], v[122:125]
	v_mfma_f32_16x16x32_bf16 v[106:109], v[178:181], v[214:217], v[106:109]
	v_mfma_f32_16x16x32_bf16 v[106:109], v[182:185], v[218:221], v[106:109]
	v_mfma_f32_16x16x32_bf16 v[90:93], v[182:185], v[226:229], v[90:93]
	v_mfma_f32_16x16x32_bf16 v[90:93], v[178:181], v[222:225], v[90:93]
	s_setprio 0
	s_setprio 1
	v_mfma_f32_16x16x32_bf16 v[86:89], v[186:189], v[222:225], v[86:89]
	v_mfma_f32_16x16x32_bf16 v[86:89], v[190:193], v[226:229], v[86:89]
	v_mfma_f32_16x16x32_bf16 v[118:121], v[190:193], v[210:213], v[118:121]
	v_mfma_f32_16x16x32_bf16 v[118:121], v[186:189], v[206:209], v[118:121]
	v_mfma_f32_16x16x32_bf16 v[102:105], v[186:189], v[214:217], v[102:105]
	v_mfma_f32_16x16x32_bf16 v[102:105], v[190:193], v[218:221], v[102:105]
	v_mfma_f32_16x16x32_bf16 v[70:73], v[190:193], v[234:237], v[70:73]
	v_mfma_f32_16x16x32_bf16 v[70:73], v[186:189], v[230:233], v[70:73]
	v_mfma_f32_16x16x32_bf16 v[66:69], v[196:199], v[230:233], v[66:69]
	v_mfma_f32_16x16x32_bf16 v[66:69], v[202:205], v[234:237], v[66:69]
	v_mfma_f32_16x16x32_bf16 v[114:117], v[202:205], v[210:213], v[114:117]
	v_mfma_f32_16x16x32_bf16 v[114:117], v[196:199], v[206:209], v[114:117]
	v_mfma_f32_16x16x32_bf16 v[98:101], v[196:199], v[214:217], v[98:101]
	v_mfma_f32_16x16x32_bf16 v[98:101], v[202:205], v[218:221], v[98:101]
	v_mfma_f32_16x16x32_bf16 v[82:85], v[202:205], v[226:229], v[82:85]
	v_mfma_f32_16x16x32_bf16 v[82:85], v[196:199], v[222:225], v[82:85]
	s_barrier
	s_setprio 0
	s_add_i32 s40, s57, s3
	s_add_u32 s98, s50, s10
	s_addc_u32 s99, s51, s11
	s_mov_b32 m0, s40
	ds_read_b128 v[206:209], v168 offset:49152
	ds_read_b128 v[210:213], v168 offset:50176
	ds_read_b128 v[214:217], v168 offset:51200
	ds_read_b128 v[218:221], v168 offset:52224
	ds_read_b128 v[222:225], v168 offset:53248
	ds_read_b128 v[226:229], v168 offset:54272
	ds_read_b128 v[230:233], v168 offset:55296
	ds_read_b128 v[234:237], v168 offset:56320
	global_load_lds_dwordx4 v132, s[98:99]
	s_add_i32 m0, s40, 0x2000
	s_add_u32 s40, s50, 0x2b0080
	s_addc_u32 s41, s51, 0
	s_add_i32 s50, s58, s3
	global_load_lds_dwordx4 v136, s[98:99]
	s_mov_b32 m0, s50
	s_nop 0
	global_load_lds_dwordx4 v132, s[40:41]
	s_add_i32 m0, s50, 0x2000
	s_nop 0
	global_load_lds_dwordx4 v136, s[40:41]
	s_add_u32 s100, s52, s10
	s_addc_u32 s101, s53, s11
	s_mov_b32 m0, s28
	s_nop 0
	global_load_lds_dwordx4 v130, s[100:101]
	s_mov_b32 m0, s29
	s_nop 0
	global_load_lds_dwordx4 v134, s[100:101]
	s_waitcnt vmcnt(8) lgkmcnt(0)
	s_setprio 1
	s_barrier
	v_mfma_f32_16x16x32_bf16 v[62:65], v[170:173], v[206:209], v[62:65]
	v_mfma_f32_16x16x32_bf16 v[62:65], v[174:177], v[210:213], v[62:65]
	v_mfma_f32_16x16x32_bf16 v[46:49], v[174:177], v[218:221], v[46:49]
	v_mfma_f32_16x16x32_bf16 v[46:49], v[170:173], v[214:217], v[46:49]
	v_mfma_f32_16x16x32_bf16 v[30:33], v[170:173], v[222:225], v[30:33]
	v_mfma_f32_16x16x32_bf16 v[30:33], v[174:177], v[226:229], v[30:33]
	v_mfma_f32_16x16x32_bf16 v[14:17], v[174:177], v[234:237], v[14:17]
	v_mfma_f32_16x16x32_bf16 v[14:17], v[170:173], v[230:233], v[14:17]
	v_mfma_f32_16x16x32_bf16 v[10:13], v[178:181], v[230:233], v[10:13]
	v_mfma_f32_16x16x32_bf16 v[10:13], v[182:185], v[234:237], v[10:13]
	v_mfma_f32_16x16x32_bf16 v[58:61], v[182:185], v[210:213], v[58:61]
	v_mfma_f32_16x16x32_bf16 v[58:61], v[178:181], v[206:209], v[58:61]
	v_mfma_f32_16x16x32_bf16 v[42:45], v[178:181], v[214:217], v[42:45]
	v_mfma_f32_16x16x32_bf16 v[42:45], v[182:185], v[218:221], v[42:45]
	v_mfma_f32_16x16x32_bf16 v[26:29], v[182:185], v[226:229], v[26:29]
	v_mfma_f32_16x16x32_bf16 v[26:29], v[178:181], v[222:225], v[26:29]
	s_setprio 0
	s_setprio 1
	v_mfma_f32_16x16x32_bf16 v[22:25], v[186:189], v[222:225], v[22:25]
	v_mfma_f32_16x16x32_bf16 v[22:25], v[190:193], v[226:229], v[22:25]
	v_mfma_f32_16x16x32_bf16 v[54:57], v[190:193], v[210:213], v[54:57]
	v_mfma_f32_16x16x32_bf16 v[54:57], v[186:189], v[206:209], v[54:57]
	v_mfma_f32_16x16x32_bf16 v[38:41], v[186:189], v[214:217], v[38:41]
	v_mfma_f32_16x16x32_bf16 v[38:41], v[190:193], v[218:221], v[38:41]
	v_mfma_f32_16x16x32_bf16 v[6:9], v[190:193], v[234:237], v[6:9]
	v_mfma_f32_16x16x32_bf16 v[6:9], v[186:189], v[230:233], v[6:9]
	v_mfma_f32_16x16x32_bf16 v[2:5], v[196:199], v[230:233], v[2:5]
	v_mfma_f32_16x16x32_bf16 v[2:5], v[202:205], v[234:237], v[2:5]
	v_mfma_f32_16x16x32_bf16 v[50:53], v[202:205], v[210:213], v[50:53]
	v_mfma_f32_16x16x32_bf16 v[50:53], v[196:199], v[206:209], v[50:53]
	v_mfma_f32_16x16x32_bf16 v[34:37], v[196:199], v[214:217], v[34:37]
	v_mfma_f32_16x16x32_bf16 v[34:37], v[202:205], v[218:221], v[34:37]
	v_mfma_f32_16x16x32_bf16 v[18:21], v[202:205], v[226:229], v[18:21]
	v_mfma_f32_16x16x32_bf16 v[18:21], v[196:199], v[222:225], v[18:21]
	s_barrier
	s_setprio 0
	s_add_i32 s56, s56, 2
	s_add_u32 s54, s54, 0x100
	s_addc_u32 s55, s55, 0
	s_cmpk_gt_u32 s56, 0xa9
	s_mov_b64 s[40:41], s[48:49]
	s_cbranch_scc0 .LBB0_1731
	s_and_b64 vcc, exec, s[12:13]
	s_cbranch_vccz .LBB0_1734
	s_barrier

; #define PG8_STAGE(bufoff, gbase, voff) do { _Pragma("unroll") for (int _i = 0; _i < 2; ++_i) \
;         __builtin_amdgcn_global_load_lds((const unsigned*)((const char*)(gbase) + (voff)[_i]), (PG8_LAS unsigned*)(lds + (bufoff) + ldsw + _i * 8192), 16, 0, 0); } while (0)
; #define PG8_LDA(dst, b, h) do { _Pragma("unroll") for (int m = 0; m < 4; ++m) _Pragma("unroll") for (int k = 0; k < 2; ++k) dst[m][k] = *(const PG8_LAS bf16x8*)(lds + PG8_SA(b, h) + aoff + m * 2048 + k * 1024); } while (0)
; #define PG8_LDB(dst, b, h) do { _Pragma("unroll") for (int n = 0; n < 2; ++n) _Pragma("unroll") for (int k = 0; k < 2; ++k) dst[n][k] = *(const PG8_LAS bf16x8*)(lds + PG8_SB(b, h) + boff + n * 2048 + k * 1024); } while (0)
; #define PG8_MMA(ai, bj, At, Bt) do { __builtin_amdgcn_s_setprio(1); _Pragma("unroll") for (int m = 0; m < 4; ++m) _Pragma("unroll") for (int n = 0; n < 2; ++n) _Pragma("unroll") for (int k = 0; k < 2; ++k) \
;         acc[ai][bj][m][n] = __builtin_amdgcn_mfma_f32_16x16x32_bf16(Bt[n][k], At[m][k], acc[ai][bj][m][n], 0, 0, 0); __builtin_amdgcn_s_setprio(0); } while (0)
; #define PG8_WAIT_V(n) asm volatile("s_waitcnt vmcnt(" #n ")" ::: "memory")
; #define PG8_WAIT_L(n) asm volatile("s_waitcnt lgkmcnt(" #n ")" ::: "memory")
; template <class Epi, class Sched, bool ALIGN_EPI = false, bool SP2 = false>
; __device__ __forceinline__ void gemm_phase(PG8_LAS unsigned char* lds, const Gemm g, const Sched& S, const Epi& E) {
;     ...
;             const bool last = (t == nt - 2);
;             const char* a1 = cA + (size_t)(t + 1) * kstep;
;             const char* a2 = last ? nA : cA + (size_t)(t + 2) * kstep; const char* b2 = last ? nB : cB + (size_t)(t + 2) * kstep;
;             const char* a3 = a2 + kstep; const char* b3 = b2 + kstep;
;             if (last && has_next) S.a_ready(nxt);
;             if constexpr (SP2) {
;             PG8_LDB(B0, 0, 0); PG8_LDB(B1, 0, 1); PG8_SCHED; PG8_LDA(At, 0, 0); PG8_STAGE(PG8_SA(1, 1), a1 + hstep, voffA);
;             PG8_WAIT_V(8); PG8_WAIT_L(0); PG8_BAR; PG8_MMA(0, 0, At, B0); PG8_MMA(0, 1, At, B1); PG8_BAR; PG8_SCHED;
;             PG8_LDA(At, 0, 1); PG8_STAGE(PG8_SB(0, 0), b2, voffB); PG8_STAGE(PG8_SB(0, 1), b2 + hstep, voffB); PG8_STAGE(PG8_SA(0, 0), a2, voffA);
;             PG8_WAIT_V(8); PG8_WAIT_L(0); PG8_BAR; PG8_MMA(1, 0, At, B0); PG8_MMA(1, 1, At, B1); PG8_BAR; PG8_SCHED;
.LBB0_1746:
	ds_read_b128 v[140:143], v134
	ds_read_b128 v[144:147], v134 offset:1024
	ds_read_b128 v[148:151], v134 offset:2048
	ds_read_b128 v[152:155], v134 offset:3072
	ds_read_b128 v[156:159], v135
	ds_read_b128 v[160:163], v135 offset:1024
	ds_read_b128 v[164:167], v135 offset:2048
	ds_read_b128 v[168:171], v135 offset:3072
	s_add_i32 s36, s38, 2
	s_mov_b32 s37, s11
	s_or_b32 s10, s38, 1
	s_lshl_b64 s[40:41], s[36:37], 7
	s_cmp_lg_u32 s38, s42
	s_cselect_b32 s38, s40, 0
	s_cselect_b32 s37, s41, 0
	s_add_u32 s40, s6, s38
	s_addc_u32 s41, s7, s37
	s_add_u32 s38, s2, s38
	s_addc_u32 s39, s3, s37
	s_lshl_b64 s[52:53], s[10:11], 7
	s_add_u32 s52, s8, s52
	s_addc_u32 s53, s9, s53
	s_mov_b32 m0, s43
	ds_read_b128 v[172:175], v136
	ds_read_b128 v[176:179], v136 offset:1024
	ds_read_b128 v[180:183], v136 offset:2048
	ds_read_b128 v[184:187], v136 offset:3072
	ds_read_b128 v[188:191], v136 offset:4096
	ds_read_b128 v[196:199], v136 offset:5120
	ds_read_b128 v[202:205], v136 offset:6144
	ds_read_b128 v[206:209], v136 offset:7168
	global_load_lds_dwordx4 v128, s[52:53]
	s_mov_b32 m0, s44
	s_nop 0
	global_load_lds_dwordx4 v130, s[52:53]
	s_waitcnt vmcnt(8) lgkmcnt(0)
	s_setprio 1
	s_barrier
	v_mfma_f32_16x16x32_bf16 v[124:127], v[140:143], v[172:175], v[124:127]
	v_mfma_f32_16x16x32_bf16 v[124:127], v[144:147], v[176:179], v[124:127]
	v_mfma_f32_16x16x32_bf16 v[116:119], v[144:147], v[184:187], v[116:119]
	v_mfma_f32_16x16x32_bf16 v[116:119], v[140:143], v[180:183], v[116:119]
	v_mfma_f32_16x16x32_bf16 v[104:107], v[140:143], v[188:191], v[104:107]
	v_mfma_f32_16x16x32_bf16 v[104:107], v[144:147], v[196:199], v[104:107]
	v_mfma_f32_16x16x32_bf16 v[88:91], v[144:147], v[206:209], v[88:91]
	v_mfma_f32_16x16x32_bf16 v[88:91], v[140:143], v[202:205], v[88:91]
	v_mfma_f32_16x16x32_bf16 v[80:83], v[148:151], v[202:205], v[80:83]
	v_mfma_f32_16x16x32_bf16 v[80:83], v[152:155], v[206:209], v[80:83]
	v_mfma_f32_16x16x32_bf16 v[120:123], v[152:155], v[176:179], v[120:123]
	v_mfma_f32_16x16x32_bf16 v[120:123], v[148:151], v[172:175], v[120:123]
	v_mfma_f32_16x16x32_bf16 v[112:115], v[148:151], v[180:183], v[112:115]
	v_mfma_f32_16x16x32_bf16 v[112:115], v[152:155], v[184:187], v[112:115]
	v_mfma_f32_16x16x32_bf16 v[96:99], v[152:155], v[196:199], v[96:99]
	v_mfma_f32_16x16x32_bf16 v[96:99], v[148:151], v[188:191], v[96:99]
	s_setprio 0
	s_setprio 1
	v_mfma_f32_16x16x32_bf16 v[76:79], v[156:159], v[188:191], v[76:79]
	v_mfma_f32_16x16x32_bf16 v[76:79], v[160:163], v[196:199], v[76:79]
	v_mfma_f32_16x16x32_bf16 v[108:111], v[160:163], v[176:179], v[108:111]
	v_mfma_f32_16x16x32_bf16 v[108:111], v[156:159], v[172:175], v[108:111]
	v_mfma_f32_16x16x32_bf16 v[92:95], v[156:159], v[180:183], v[92:95]
	v_mfma_f32_16x16x32_bf16 v[92:95], v[160:163], v[184:187], v[92:95]
	v_mfma_f32_16x16x32_bf16 v[68:71], v[160:163], v[206:209], v[68:71]
	v_mfma_f32_16x16x32_bf16 v[68:71], v[156:159], v[202:205], v[68:71]
	v_mfma_f32_16x16x32_bf16 v[64:67], v[164:167], v[202:205], v[64:67]
	v_mfma_f32_16x16x32_bf16 v[64:67], v[168:171], v[206:209], v[64:67]
	v_mfma_f32_16x16x32_bf16 v[100:103], v[168:171], v[176:179], v[100:103]
	v_mfma_f32_16x16x32_bf16 v[100:103], v[164:167], v[172:175], v[100:103]
	v_mfma_f32_16x16x32_bf16 v[84:87], v[164:167], v[180:183], v[84:87]
	v_mfma_f32_16x16x32_bf16 v[84:87], v[168:171], v[184:187], v[84:87]
	v_mfma_f32_16x16x32_bf16 v[72:75], v[168:171], v[196:199], v[72:75]
	v_mfma_f32_16x16x32_bf16 v[72:75], v[164:167], v[188:191], v[72:75]
	s_barrier
	s_setprio 0
	s_mov_b32 m0, s31
	s_add_u32 s52, s38, 0x2b0000
	ds_read_b128 v[172:175], v136 offset:16384
	ds_read_b128 v[176:179], v136 offset:17408
	ds_read_b128 v[180:183], v136 offset:18432
	ds_read_b128 v[184:187], v136 offset:19456
	ds_read_b128 v[188:191], v136 offset:20480
	ds_read_b128 v[196:199], v136 offset:21504
	ds_read_b128 v[202:205], v136 offset:22528
	ds_read_b128 v[206:209], v136 offset:23552
	global_load_lds_dwordx4 v128, s[38:39]
	s_mov_b32 m0, s45
	s_addc_u32 s53, s39, 0
	global_load_lds_dwordx4 v130, s[38:39]
	s_mov_b32 m0, s46
	v_lshl_add_u64 v[212:213], s[40:41], 0, v[130:131]
	global_load_lds_dwordx4 v128, s[52:53]
	s_mov_b32 m0, s47
	s_nop 0
	global_load_lds_dwordx4 v130, s[52:53]
	v_lshl_add_u64 v[210:211], s[40:41], 0, v[128:129]
	s_mov_b32 m0, s26
	s_nop 0
	global_load_lds_dwordx4 v128, s[40:41]
	s_mov_b32 m0, s27
	s_nop 0
	global_load_lds_dwordx4 v130, s[40:41]
	s_waitcnt vmcnt(8) lgkmcnt(0)
	s_setprio 1
	s_barrier
	v_mfma_f32_16x16x32_bf16 v[60:63], v[140:143], v[172:175], v[60:63]
	v_mfma_f32_16x16x32_bf16 v[60:63], v[144:147], v[176:179], v[60:63]
	v_mfma_f32_16x16x32_bf16 v[52:55], v[144:147], v[184:187], v[52:55]
	v_mfma_f32_16x16x32_bf16 v[52:55], v[140:143], v[180:183], v[52:55]
	v_mfma_f32_16x16x32_bf16 v[40:43], v[140:143], v[188:191], v[40:43]
	v_mfma_f32_16x16x32_bf16 v[40:43], v[144:147], v[196:199], v[40:43]
	v_mfma_f32_16x16x32_bf16 v[24:27], v[144:147], v[206:209], v[24:27]
	v_mfma_f32_16x16x32_bf16 v[24:27], v[140:143], v[202:205], v[24:27]
	v_mfma_f32_16x16x32_bf16 v[16:19], v[148:151], v[202:205], v[16:19]
	v_mfma_f32_16x16x32_bf16 v[16:19], v[152:155], v[206:209], v[16:19]
	v_mfma_f32_16x16x32_bf16 v[56:59], v[152:155], v[176:179], v[56:59]
	v_mfma_f32_16x16x32_bf16 v[56:59], v[148:151], v[172:175], v[56:59]
	v_mfma_f32_16x16x32_bf16 v[48:51], v[148:151], v[180:183], v[48:51]
	v_mfma_f32_16x16x32_bf16 v[48:51], v[152:155], v[184:187], v[48:51]
	v_mfma_f32_16x16x32_bf16 v[32:35], v[152:155], v[196:199], v[32:35]
	v_mfma_f32_16x16x32_bf16 v[32:35], v[148:151], v[188:191], v[32:35]
	s_setprio 0
	s_setprio 1
	v_mfma_f32_16x16x32_bf16 v[12:15], v[156:159], v[188:191], v[12:15]
	v_mfma_f32_16x16x32_bf16 v[12:15], v[160:163], v[196:199], v[12:15]
	v_mfma_f32_16x16x32_bf16 v[44:47], v[160:163], v[176:179], v[44:47]
	v_mfma_f32_16x16x32_bf16 v[44:47], v[156:159], v[172:175], v[44:47]
	v_mfma_f32_16x16x32_bf16 v[28:31], v[156:159], v[180:183], v[28:31]
	v_mfma_f32_16x16x32_bf16 v[28:31], v[160:163], v[184:187], v[28:31]
	v_mfma_f32_16x16x32_bf16 v[4:7], v[160:163], v[206:209], v[4:7]
	v_mfma_f32_16x16x32_bf16 v[4:7], v[156:159], v[202:205], v[4:7]
	v_mfma_f32_16x16x32_bf16 v[0:3], v[164:167], v[202:205], v[0:3]
	v_mfma_f32_16x16x32_bf16 v[0:3], v[168:171], v[206:209], v[0:3]
	v_mfma_f32_16x16x32_bf16 v[36:39], v[168:171], v[176:179], v[36:39]
	v_mfma_f32_16x16x32_bf16 v[36:39], v[164:167], v[172:175], v[36:39]
	v_mfma_f32_16x16x32_bf16 v[20:23], v[164:167], v[180:183], v[20:23]
	v_mfma_f32_16x16x32_bf16 v[20:23], v[168:171], v[184:187], v[20:23]
	v_mfma_f32_16x16x32_bf16 v[8:11], v[168:171], v[196:199], v[8:11]
	v_mfma_f32_16x16x32_bf16 v[8:11], v[164:167], v[188:191], v[8:11]
	s_barrier
; #define PG8_STAGE(bufoff, gbase, voff) do { _Pragma("unroll") for (int _i = 0; _i < 2; ++_i) \
;         __builtin_amdgcn_global_load_lds((const unsigned*)((const char*)(gbase) + (voff)[_i]), (PG8_LAS unsigned*)(lds + (bufoff) + ldsw + _i * 8192), 16, 0, 0); } while (0)
; #define PG8_LDA(dst, b, h) do { _Pragma("unroll") for (int m = 0; m < 4; ++m) _Pragma("unroll") for (int k = 0; k < 2; ++k) dst[m][k] = *(const PG8_LAS bf16x8*)(lds + PG8_SA(b, h) + aoff + m * 2048 + k * 1024); } while (0)
; #define PG8_LDB(dst, b, h) do { _Pragma("unroll") for (int n = 0; n < 2; ++n) _Pragma("unroll") for (int k = 0; k < 2; ++k) dst[n][k] = *(const PG8_LAS bf16x8*)(lds + PG8_SB(b, h) + boff + n * 2048 + k * 1024); } while (0)
; #define PG8_MMA(ai, bj, At, Bt) do { __builtin_amdgcn_s_setprio(1); _Pragma("unroll") for (int m = 0; m < 4; ++m) _Pragma("unroll") for (int n = 0; n < 2; ++n) _Pragma("unroll") for (int k = 0; k < 2; ++k) \
;         acc[ai][bj][m][n] = __builtin_amdgcn_mfma_f32_16x16x32_bf16(Bt[n][k], At[m][k], acc[ai][bj][m][n], 0, 0, 0); __builtin_amdgcn_s_setprio(0); } while (0)
; #define PG8_WAIT_V(n) asm volatile("s_waitcnt vmcnt(" #n ")" ::: "memory")
; #define PG8_WAIT_L(n) asm volatile("s_waitcnt lgkmcnt(" #n ")" ::: "memory")
; #define PG8_BAR __builtin_amdgcn_s_barrier()
; #define PG8_SCHED __builtin_amdgcn_sched_barrier(0)
; template <class Epi, class Sched, bool ALIGN_EPI = false, bool SP2 = false>
; __device__ __forceinline__ void gemm_phase(PG8_LAS unsigned char* lds, const Gemm g, const Sched& S, const Epi& E) {
;     ...
;             PG8_LDB(B0, 1, 0); PG8_LDB(B1, 1, 1); PG8_SCHED; PG8_LDA(At, 1, 0); PG8_STAGE(PG8_SA(0, 1), a2 + hstep, voffA);
;             PG8_WAIT_V(8); PG8_WAIT_L(0); PG8_BAR; PG8_MMA(0, 0, At, B0); PG8_MMA(0, 1, At, B1); PG8_BAR; PG8_SCHED;
;             PG8_LDA(At, 1, 1); PG8_STAGE(PG8_SB(1, 0), b3, voffB); PG8_STAGE(PG8_SB(1, 1), b3 + hstep, voffB); PG8_STAGE(PG8_SA(1, 0), a3, voffA);
;             PG8_WAIT_V(8); PG8_WAIT_L(0); PG8_BAR; PG8_MMA(1, 0, At, B0); PG8_MMA(1, 1, At, B1); PG8_BAR; PG8_SCHED;
	s_setprio 0
	ds_read_b128 v[140:143], v137
	ds_read_b128 v[144:147], v137 offset:1024
	ds_read_b128 v[148:151], v137 offset:2048
	ds_read_b128 v[152:155], v137 offset:3072
	ds_read_b128 v[156:159], v138
	ds_read_b128 v[160:163], v138 offset:1024
	ds_read_b128 v[164:167], v138 offset:2048
	ds_read_b128 v[168:171], v138 offset:3072
	s_add_u32 s40, s40, 0x2b0000
	s_addc_u32 s41, s41, 0
	s_mov_b32 m0, s28
	ds_read_b128 v[172:175], v136 offset:32768
	ds_read_b128 v[176:179], v136 offset:33792
	ds_read_b128 v[180:183], v136 offset:34816
	ds_read_b128 v[184:187], v136 offset:35840
	ds_read_b128 v[188:191], v136 offset:36864
	ds_read_b128 v[196:199], v136 offset:37888
	ds_read_b128 v[202:205], v136 offset:38912
	ds_read_b128 v[206:209], v136 offset:39936
	global_load_lds_dwordx4 v128, s[40:41]
	s_mov_b32 m0, s30
	s_nop 0
	global_load_lds_dwordx4 v130, s[40:41]
	s_waitcnt vmcnt(8) lgkmcnt(0)
	s_setprio 1
	s_barrier
	v_mfma_f32_16x16x32_bf16 v[124:127], v[140:143], v[172:175], v[124:127]
	v_mfma_f32_16x16x32_bf16 v[124:127], v[144:147], v[176:179], v[124:127]
	v_mfma_f32_16x16x32_bf16 v[116:119], v[144:147], v[184:187], v[116:119]
	v_mfma_f32_16x16x32_bf16 v[116:119], v[140:143], v[180:183], v[116:119]
	v_mfma_f32_16x16x32_bf16 v[104:107], v[140:143], v[188:191], v[104:107]
	v_mfma_f32_16x16x32_bf16 v[104:107], v[144:147], v[196:199], v[104:107]
	v_mfma_f32_16x16x32_bf16 v[88:91], v[144:147], v[206:209], v[88:91]
	v_mfma_f32_16x16x32_bf16 v[88:91], v[140:143], v[202:205], v[88:91]
	v_mfma_f32_16x16x32_bf16 v[80:83], v[148:151], v[202:205], v[80:83]
	v_mfma_f32_16x16x32_bf16 v[80:83], v[152:155], v[206:209], v[80:83]
	v_mfma_f32_16x16x32_bf16 v[120:123], v[152:155], v[176:179], v[120:123]
	v_mfma_f32_16x16x32_bf16 v[120:123], v[148:151], v[172:175], v[120:123]
	v_mfma_f32_16x16x32_bf16 v[112:115], v[148:151], v[180:183], v[112:115]
	v_mfma_f32_16x16x32_bf16 v[112:115], v[152:155], v[184:187], v[112:115]
	v_mfma_f32_16x16x32_bf16 v[96:99], v[152:155], v[196:199], v[96:99]
	v_mfma_f32_16x16x32_bf16 v[96:99], v[148:151], v[188:191], v[96:99]
	s_setprio 0
	s_setprio 1
	v_mfma_f32_16x16x32_bf16 v[76:79], v[156:159], v[188:191], v[76:79]
	v_mfma_f32_16x16x32_bf16 v[76:79], v[160:163], v[196:199], v[76:79]
	v_mfma_f32_16x16x32_bf16 v[108:111], v[160:163], v[176:179], v[108:111]
	v_mfma_f32_16x16x32_bf16 v[108:111], v[156:159], v[172:175], v[108:111]
	v_mfma_f32_16x16x32_bf16 v[92:95], v[156:159], v[180:183], v[92:95]
	v_mfma_f32_16x16x32_bf16 v[92:95], v[160:163], v[184:187], v[92:95]
	v_mfma_f32_16x16x32_bf16 v[68:71], v[160:163], v[206:209], v[68:71]
	v_mfma_f32_16x16x32_bf16 v[68:71], v[156:159], v[202:205], v[68:71]
	v_mfma_f32_16x16x32_bf16 v[64:67], v[164:167], v[202:205], v[64:67]
	v_mfma_f32_16x16x32_bf16 v[64:67], v[168:171], v[206:209], v[64:67]
	v_mfma_f32_16x16x32_bf16 v[100:103], v[168:171], v[176:179], v[100:103]
	v_mfma_f32_16x16x32_bf16 v[100:103], v[164:167], v[172:175], v[100:103]
	v_mfma_f32_16x16x32_bf16 v[84:87], v[164:167], v[180:183], v[84:87]
	v_mfma_f32_16x16x32_bf16 v[84:87], v[168:171], v[184:187], v[84:87]
	v_mfma_f32_16x16x32_bf16 v[72:75], v[168:171], v[196:199], v[72:75]
	v_mfma_f32_16x16x32_bf16 v[72:75], v[164:167], v[188:191], v[72:75]
	s_barrier
	s_setprio 0
	s_mov_b32 m0, s48
	s_add_u32 s98, s38, s12
	s_addc_u32 s99, s39, s13
	s_add_u32 s38, s38, 0x2b0080
	ds_read_b128 v[172:175], v136 offset:49152
	ds_read_b128 v[176:179], v136 offset:50176
	ds_read_b128 v[180:183], v136 offset:51200
	ds_read_b128 v[184:187], v136 offset:52224
	ds_read_b128 v[188:191], v136 offset:53248
	ds_read_b128 v[196:199], v136 offset:54272
	ds_read_b128 v[202:205], v136 offset:55296
	ds_read_b128 v[206:209], v136 offset:56320
	global_load_lds_dwordx4 v128, s[98:99]
	s_mov_b32 m0, s49
	s_addc_u32 s39, s39, 0
	global_load_lds_dwordx4 v130, s[98:99]
	s_mov_b32 m0, s50
	s_nop 0
	global_load_lds_dwordx4 v128, s[38:39]
	s_mov_b32 m0, s51
	s_nop 0
	global_load_lds_dwordx4 v130, s[38:39]
	v_lshl_add_u64 v[192:193], v[210:211], 0, s[12:13]
	s_mov_b32 m0, s34
	s_nop 0
	global_load_lds_dwordx4 v[192:193], off
	v_lshl_add_u64 v[192:193], v[212:213], 0, s[12:13]
	s_mov_b32 m0, s35
	s_nop 0
	global_load_lds_dwordx4 v[192:193], off
	s_waitcnt vmcnt(8) lgkmcnt(0)
	s_setprio 1
	s_barrier
	v_mfma_f32_16x16x32_bf16 v[60:63], v[140:143], v[172:175], v[60:63]
	v_mfma_f32_16x16x32_bf16 v[60:63], v[144:147], v[176:179], v[60:63]
	v_mfma_f32_16x16x32_bf16 v[52:55], v[144:147], v[184:187], v[52:55]
	v_mfma_f32_16x16x32_bf16 v[52:55], v[140:143], v[180:183], v[52:55]
	v_mfma_f32_16x16x32_bf16 v[40:43], v[140:143], v[188:191], v[40:43]
	v_mfma_f32_16x16x32_bf16 v[40:43], v[144:147], v[196:199], v[40:43]
	v_mfma_f32_16x16x32_bf16 v[24:27], v[144:147], v[206:209], v[24:27]
	v_mfma_f32_16x16x32_bf16 v[24:27], v[140:143], v[202:205], v[24:27]
	v_mfma_f32_16x16x32_bf16 v[16:19], v[148:151], v[202:205], v[16:19]
	v_mfma_f32_16x16x32_bf16 v[16:19], v[152:155], v[206:209], v[16:19]
	v_mfma_f32_16x16x32_bf16 v[56:59], v[152:155], v[176:179], v[56:59]
	v_mfma_f32_16x16x32_bf16 v[56:59], v[148:151], v[172:175], v[56:59]
	v_mfma_f32_16x16x32_bf16 v[48:51], v[148:151], v[180:183], v[48:51]
	v_mfma_f32_16x16x32_bf16 v[48:51], v[152:155], v[184:187], v[48:51]
	v_mfma_f32_16x16x32_bf16 v[32:35], v[152:155], v[196:199], v[32:35]
	v_mfma_f32_16x16x32_bf16 v[32:35], v[148:151], v[188:191], v[32:35]
	s_setprio 0
	s_setprio 1
	v_mfma_f32_16x16x32_bf16 v[12:15], v[156:159], v[188:191], v[12:15]
	v_mfma_f32_16x16x32_bf16 v[12:15], v[160:163], v[196:199], v[12:15]
	v_mfma_f32_16x16x32_bf16 v[44:47], v[160:163], v[176:179], v[44:47]
	v_mfma_f32_16x16x32_bf16 v[44:47], v[156:159], v[172:175], v[44:47]
	v_mfma_f32_16x16x32_bf16 v[28:31], v[156:159], v[180:183], v[28:31]
	v_mfma_f32_16x16x32_bf16 v[28:31], v[160:163], v[184:187], v[28:31]
	v_mfma_f32_16x16x32_bf16 v[4:7], v[160:163], v[206:209], v[4:7]
	v_mfma_f32_16x16x32_bf16 v[4:7], v[156:159], v[202:205], v[4:7]
	v_mfma_f32_16x16x32_bf16 v[0:3], v[164:167], v[202:205], v[0:3]
	v_mfma_f32_16x16x32_bf16 v[0:3], v[168:171], v[206:209], v[0:3]
	v_mfma_f32_16x16x32_bf16 v[36:39], v[168:171], v[176:179], v[36:39]
	v_mfma_f32_16x16x32_bf16 v[36:39], v[164:167], v[172:175], v[36:39]
	v_mfma_f32_16x16x32_bf16 v[20:23], v[164:167], v[180:183], v[20:23]
	v_mfma_f32_16x16x32_bf16 v[20:23], v[168:171], v[184:187], v[20:23]
	v_mfma_f32_16x16x32_bf16 v[8:11], v[168:171], v[196:199], v[8:11]
	v_mfma_f32_16x16x32_bf16 v[8:11], v[164:167], v[188:191], v[8:11]
	s_barrier
	s_setprio 0
	s_cmp_ge_u32 s36, s5
	s_mov_b32 s38, s36
	s_cbranch_scc0 .LBB0_1746
	s_cmpk_lt_u32 s16, 0x100
	s_cbranch_scc0 .LBB0_1749
	s_barrier
